# all packed f32 VALU ops (v_pk_mul/add/fma_f32) split into scalar pairs, bit-identical
# baseline (speedup 1.0000x reference)
.LBB0_44:
	v_lshlrev_b64 v[20:21], 12, v[20:21]
	v_lshl_add_u64 v[24:25], v[18:19], 0, v[20:21]
	v_lshlrev_b64 v[16:17], 11, v[16:17]
	v_lshl_add_u64 v[20:21], v[66:67], 0, v[16:17]
	v_lshl_add_u64 v[32:33], v[24:25], 0, v[74:75]
	global_load_dwordx4 v[16:19], v[20:21], off
	s_nop 0
	global_load_dwordx4 v[20:23], v[20:21], off offset:1024
	s_nop 0
	global_load_dwordx4 v[28:31], v[32:33], off offset:16
	global_load_dwordx4 v[36:39], v[32:33], off
	global_load_dwordx4 v[24:27], v[32:33], off offset:2064
	s_nop 0
	global_load_dwordx4 v[32:35], v[32:33], off offset:2048
	s_waitcnt vmcnt(10)
	v_lshlrev_b32_e32 v86, 16, v60
	v_and_b32_e32 v87, 0xffff0000, v60
	v_lshlrev_b32_e32 v82, 16, v61
	v_and_b32_e32 v83, 0xffff0000, v61
	v_mul_f32_e32 v60, v86, v86
	v_mul_f32_e32 v61, v87, v87
	v_mul_f32_e32 v84, v82, v82
	v_mul_f32_e32 v85, v83, v83
	v_add_f32_e32 v60, v60, v61
	v_lshlrev_b32_e32 v80, 16, v62
	v_and_b32_e32 v81, 0xffff0000, v62
	v_add_f32_e32 v60, v84, v60
	v_lshlrev_b32_e32 v76, 16, v63
	v_and_b32_e32 v77, 0xffff0000, v63
	v_mul_f32_e32 v62, v80, v80
	v_mul_f32_e32 v63, v81, v81
	v_add_f32_e32 v60, v85, v60
	v_add_f32_e32 v60, v62, v60
	v_mul_f32_e32 v78, v76, v76
	v_mul_f32_e32 v79, v77, v77
	v_add_f32_e32 v60, v63, v60
	v_lshlrev_b32_e32 v98, 16, v56
	v_and_b32_e32 v99, 0xffff0000, v56
	v_add_f32_e32 v60, v78, v60
	v_lshlrev_b32_e32 v94, 16, v57
	v_and_b32_e32 v95, 0xffff0000, v57
	v_mul_f32_e32 v56, v98, v98
	v_mul_f32_e32 v57, v99, v99
	v_add_f32_e32 v60, v79, v60
	v_add_f32_e32 v56, v56, v60
	v_mul_f32_e32 v96, v94, v94
	v_mul_f32_e32 v97, v95, v95
	v_add_f32_e32 v56, v57, v56
	v_lshlrev_b32_e32 v92, 16, v58
	v_and_b32_e32 v93, 0xffff0000, v58
	v_add_f32_e32 v56, v96, v56
	v_lshlrev_b32_e32 v88, 16, v59
	v_and_b32_e32 v89, 0xffff0000, v59
	v_mul_f32_e32 v58, v92, v92
	v_mul_f32_e32 v59, v93, v93
	v_add_f32_e32 v56, v97, v56
	v_add_f32_e32 v56, v58, v56
	v_mul_f32_e32 v90, v88, v88
	v_mul_f32_e32 v91, v89, v89
	v_add_f32_e32 v56, v59, v56
	v_add_f32_e32 v56, v90, v56
	v_add_f32_e32 v56, v91, v56
	s_nop 1
	v_add_f32_dpp v56, v56, v56 quad_perm:[1,0,3,2] row_mask:0xf bank_mask:0xf bound_ctrl:1
	s_nop 1
	v_add_f32_dpp v56, v56, v56 quad_perm:[2,3,0,1] row_mask:0xf bank_mask:0xf bound_ctrl:1
	s_nop 1
	v_add_f32_dpp v56, v56, v56 row_half_mirror row_mask:0xf bank_mask:0xf bound_ctrl:1
	s_nop 1
	v_add_f32_dpp v56, v56, v56 row_mirror row_mask:0xf bank_mask:0xf bound_ctrl:1
	v_mov_b32_e32 v57, v56
	s_nop 1
	v_permlane16_swap_b32_e32 v56, v57
	v_add_f32_e32 v56, v56, v57
	v_mov_b32_e32 v57, v56
	s_nop 1
	v_permlane32_swap_b32_e32 v56, v57
	v_add_f32_e32 v56, v56, v57
	v_fmamk_f32 v56, v56, 0x3a800000, v230
	v_mul_f32_e32 v57, 0x4b800000, v56
	v_cmp_gt_f32_e32 vcc, s91, v56
	s_nop 1
	v_cndmask_b32_e32 v56, v56, v57, vcc
	v_rsq_f32_e32 v56, v56
	s_nop 0
	v_mul_f32_e32 v57, 0x45800000, v56
	v_cndmask_b32_e32 v56, v56, v57, vcc
	v_mul_f32_e32 v58, v56, v86
	v_mul_f32_e32 v59, v56, v87
	s_waitcnt vmcnt(9)
	v_fma_f32 v52, v0, v58, v52
	v_fma_f32 v53, v1, v59, v53
	v_mul_f32_e32 v58, v56, v80
	v_mul_f32_e32 v59, v56, v81
	s_waitcnt vmcnt(8)
	v_fma_f32 v48, v4, v58, v48
	v_fma_f32 v49, v5, v59, v49
	v_mul_f32_e32 v58, v56, v82
	v_mul_f32_e32 v59, v56, v83
	v_fma_f32 v54, v2, v58, v54
	v_fma_f32 v55, v3, v59, v55
	v_mul_f32_e32 v58, v56, v76
	v_mul_f32_e32 v59, v56, v77
	v_fma_f32 v50, v6, v58, v50
	v_fma_f32 v51, v7, v59, v51
	v_mul_f32_e32 v58, v56, v98
	v_mul_f32_e32 v59, v56, v99
	s_waitcnt vmcnt(7)
	v_fma_f32 v44, v8, v58, v44
	v_fma_f32 v45, v9, v59, v45
	v_mul_f32_e32 v58, v56, v92
	v_mul_f32_e32 v59, v56, v93
	s_waitcnt vmcnt(6)
	v_fma_f32 v40, v12, v58, v40
	v_fma_f32 v41, v13, v59, v41
	v_mul_f32_e32 v58, v56, v94
	v_mul_f32_e32 v59, v56, v95
	v_mul_f32_e32 v57, v56, v89
	v_mul_f32_e32 v56, v56, v88
	v_fma_f32 v46, v10, v58, v46
	v_fma_f32 v47, v11, v59, v47
	v_fma_f32 v42, v14, v56, v42
	v_fma_f32 v43, v15, v57, v43
	v_lshl_add_u64 v[56:57], s[68:69], 0, v[70:71]
	s_andn2_b64 vcc, exec, s[8:9]
	global_store_dwordx4 v[56:57], v[52:55], off
	global_store_dwordx4 v[56:57], v[48:51], off offset:16
	global_store_dwordx4 v[56:57], v[44:47], off offset:2048
	global_store_dwordx4 v[56:57], v[40:43], off offset:2064
	s_cbranch_vccnz .LBB0_35
	v_mul_f32_e32 v56, v52, v52
	v_mul_f32_e32 v57, v53, v53
	v_mul_f32_e32 v58, v54, v54
	v_mul_f32_e32 v59, v55, v55
	v_add_f32_e32 v56, v56, v57
	v_add_f32_e32 v56, v58, v56
	v_mul_f32_e32 v60, v48, v48
	v_mul_f32_e32 v61, v49, v49
	v_add_f32_e32 v56, v59, v56
	v_add_f32_e32 v56, v60, v56
	v_mul_f32_e32 v62, v50, v50
	v_mul_f32_e32 v63, v51, v51
	v_add_f32_e32 v56, v61, v56
	v_add_f32_e32 v56, v62, v56
	v_mul_f32_e32 v76, v44, v44
	v_mul_f32_e32 v77, v45, v45
	v_add_f32_e32 v56, v63, v56
	v_add_f32_e32 v56, v76, v56
	v_mul_f32_e32 v78, v46, v46
	v_mul_f32_e32 v79, v47, v47
	v_add_f32_e32 v56, v77, v56
	v_add_f32_e32 v56, v78, v56
	v_mul_f32_e32 v80, v40, v40
	v_mul_f32_e32 v81, v41, v41
	v_add_f32_e32 v56, v79, v56
	v_add_f32_e32 v56, v80, v56
	v_mul_f32_e32 v82, v42, v42
	v_mul_f32_e32 v83, v43, v43
	v_add_f32_e32 v56, v81, v56
	v_add_f32_e32 v56, v82, v56
	v_add_f32_e32 v56, v83, v56
	s_nop 1
	v_add_f32_dpp v56, v56, v56 quad_perm:[1,0,3,2] row_mask:0xf bank_mask:0xf bound_ctrl:1
	s_nop 1
	v_add_f32_dpp v56, v56, v56 quad_perm:[2,3,0,1] row_mask:0xf bank_mask:0xf bound_ctrl:1
	s_nop 1
	v_add_f32_dpp v56, v56, v56 row_half_mirror row_mask:0xf bank_mask:0xf bound_ctrl:1
	s_nop 1
	v_add_f32_dpp v56, v56, v56 row_mirror row_mask:0xf bank_mask:0xf bound_ctrl:1
	v_mov_b32_e32 v57, v56
	s_nop 1
	v_permlane16_swap_b32_e32 v56, v57
	v_add_f32_e32 v56, v56, v57
	v_mov_b32_e32 v57, v56
	s_nop 1
	v_permlane32_swap_b32_e32 v56, v57
	v_add_f32_e32 v56, v56, v57
	v_fmamk_f32 v56, v56, 0x3a800000, v230
	v_cmp_gt_f32_e32 vcc, s91, v56
	v_mul_f32_e32 v57, 0x4b800000, v56
	s_nop 0
	v_cndmask_b32_e32 v56, v56, v57, vcc
	v_rsq_f32_e32 v56, v56
	s_nop 0
	v_mul_f32_e32 v57, 0x45800000, v56
	v_cndmask_b32_e32 v60, v56, v57, vcc
	global_load_dwordx4 v[56:59], v[68:69], off offset:16
	global_load_dwordx4 v[76:79], v[68:69], off
	v_mul_f32_e32 v52, v52, v60
	v_mul_f32_e32 v53, v53, v60
	v_mul_f32_e32 v54, v54, v60
	v_mul_f32_e32 v55, v55, v60
	v_mul_f32_e32 v48, v48, v60
	v_mul_f32_e32 v49, v49, v60
	v_mul_f32_e32 v44, v44, v60
	v_mul_f32_e32 v45, v45, v60
	v_mul_f32_e32 v46, v46, v60
	v_mul_f32_e32 v47, v47, v60
	v_mul_f32_e32 v40, v40, v60
	v_mul_f32_e32 v41, v41, v60
	s_waitcnt vmcnt(1)
	v_mul_f32_e32 v48, v56, v48
	v_mul_f32_e32 v49, v57, v49
	s_waitcnt vmcnt(0)
	v_mul_f32_e32 v52, v76, v52
	v_mul_f32_e32 v53, v77, v53
	v_mul_f32_e32 v54, v78, v54
	v_mul_f32_e32 v55, v79, v55
	v_cvt_pk_bf16_f32 v52, v52, v53
	v_cvt_pk_bf16_f32 v53, v54, v55
	v_cvt_pk_bf16_f32 v54, v48, v49
	v_mul_f32_e32 v48, v50, v60
	v_mul_f32_e32 v49, v51, v60
	s_nop 0
	v_mul_f32_e32 v48, v58, v48
	v_mul_f32_e32 v49, v59, v49
	s_nop 0
	v_cvt_pk_bf16_f32 v55, v48, v49
	global_store_dwordx4 v[72:73], v[52:55], off offset:-1024
	global_load_dwordx4 v[48:51], v[68:69], off offset:2064
	s_nop 0
	global_load_dwordx4 v[52:55], v[68:69], off offset:2048
	s_waitcnt vmcnt(1)
	v_mul_f32_e32 v40, v48, v40
	v_mul_f32_e32 v41, v49, v41
	s_waitcnt vmcnt(0)
	v_mul_f32_e32 v44, v52, v44
	v_mul_f32_e32 v45, v53, v45
	v_mul_f32_e32 v46, v54, v46
	v_mul_f32_e32 v47, v55, v47
	v_cvt_pk_bf16_f32 v44, v44, v45
	v_cvt_pk_bf16_f32 v45, v46, v47
	v_cvt_pk_bf16_f32 v46, v40, v41
	v_mul_f32_e32 v40, v42, v60
	v_mul_f32_e32 v41, v43, v60
	s_nop 0
	v_mul_f32_e32 v40, v50, v40
	v_mul_f32_e32 v41, v51, v41
	s_nop 0
	v_cvt_pk_bf16_f32 v47, v40, v41
	global_store_dwordx4 v[72:73], v[44:47], off
	s_branch .LBB0_35

.Lk0_scale:
	s_mov_b32 s0, 0x3e38aa3b
	v_mul_f32_e32 v128, s0, v120
	v_mul_f32_e32 v129, s0, v121
	v_mul_f32_e32 v130, s0, v122
	v_mul_f32_e32 v131, s0, v123
	v_mul_f32_e32 v132, s0, v124
	v_mul_f32_e32 v133, s0, v125
	v_mul_f32_e32 v134, s0, v126
	v_mul_f32_e32 v135, s0, v127
	v_cvt_pk_bf16_f32 v32, v128, v129
	v_cvt_pk_bf16_f32 v33, v130, v131
	v_cvt_pk_bf16_f32 v34, v132, v133
	v_cvt_pk_bf16_f32 v35, v134, v135
	global_store_dwordx4 v[136:137], v[32:35], off
	v_mul_f32_e32 v128, s0, v112
	v_mul_f32_e32 v129, s0, v113
	v_mul_f32_e32 v130, s0, v114
	v_mul_f32_e32 v131, s0, v115
	v_mul_f32_e32 v132, s0, v116
	v_mul_f32_e32 v133, s0, v117
	v_mul_f32_e32 v134, s0, v118
	v_mul_f32_e32 v135, s0, v119
	v_lshl_add_u64 v[138:139], vcc, 0, v[136:137]
	v_cvt_pk_bf16_f32 v32, v128, v129
	v_cvt_pk_bf16_f32 v33, v130, v131
	v_cvt_pk_bf16_f32 v34, v132, v133
	v_cvt_pk_bf16_f32 v35, v134, v135
	global_store_dwordx4 v[138:139], v[32:35], off
	v_mul_f32_e32 v128, s0, v104
	v_mul_f32_e32 v129, s0, v105
	v_mul_f32_e32 v130, s0, v106
	v_mul_f32_e32 v131, s0, v107
	v_mul_f32_e32 v132, s0, v108
	v_mul_f32_e32 v133, s0, v109
	v_mul_f32_e32 v134, s0, v110
	v_mul_f32_e32 v135, s0, v111
	v_lshl_add_u64 v[136:137], vcc, 0, v[138:139]
	v_cvt_pk_bf16_f32 v32, v128, v129
	v_cvt_pk_bf16_f32 v33, v130, v131
	v_cvt_pk_bf16_f32 v34, v132, v133
	v_cvt_pk_bf16_f32 v35, v134, v135
	global_store_dwordx4 v[136:137], v[32:35], off
	v_mul_f32_e32 v128, s0, v96
	v_mul_f32_e32 v129, s0, v97
	v_mul_f32_e32 v130, s0, v98
	v_mul_f32_e32 v131, s0, v99
	v_mul_f32_e32 v132, s0, v100
	v_mul_f32_e32 v133, s0, v101
	v_mul_f32_e32 v134, s0, v102
	v_mul_f32_e32 v135, s0, v103
	v_lshl_add_u64 v[138:139], vcc, 0, v[136:137]
	v_cvt_pk_bf16_f32 v32, v128, v129
	v_cvt_pk_bf16_f32 v33, v130, v131
	v_cvt_pk_bf16_f32 v34, v132, v133
	v_cvt_pk_bf16_f32 v35, v134, v135
	global_store_dwordx4 v[138:139], v[32:35], off
	v_mul_f32_e32 v128, s0, v88
	v_mul_f32_e32 v129, s0, v89
	v_mul_f32_e32 v130, s0, v90
	v_mul_f32_e32 v131, s0, v91
	v_mul_f32_e32 v132, s0, v210
	v_mul_f32_e32 v133, s0, v211
	v_mul_f32_e32 v134, s0, v212
	v_mul_f32_e32 v135, s0, v213
	s_mov_b32 vcc_lo, 0x5a000
	v_lshl_add_u64 v[136:137], vcc, 0, v[138:139]
	s_mov_b32 vcc_lo, 0x12000
	v_cvt_pk_bf16_f32 v32, v128, v129
	v_cvt_pk_bf16_f32 v33, v130, v131
	v_cvt_pk_bf16_f32 v34, v132, v133
	v_cvt_pk_bf16_f32 v35, v134, v135
	global_store_dwordx4 v[136:137], v[32:35], off
	v_mul_f32_e32 v128, s0, v80
	v_mul_f32_e32 v129, s0, v81
	v_mul_f32_e32 v130, s0, v82
	v_mul_f32_e32 v131, s0, v83
	v_mul_f32_e32 v132, s0, v84
	v_mul_f32_e32 v133, s0, v85
	v_mul_f32_e32 v134, s0, v86
	v_mul_f32_e32 v135, s0, v87
	v_lshl_add_u64 v[138:139], vcc, 0, v[136:137]
	v_cvt_pk_bf16_f32 v32, v128, v129
	v_cvt_pk_bf16_f32 v33, v130, v131
	v_cvt_pk_bf16_f32 v34, v132, v133
	v_cvt_pk_bf16_f32 v35, v134, v135
	global_store_dwordx4 v[138:139], v[32:35], off
	v_mul_f32_e32 v128, s0, v72
	v_mul_f32_e32 v129, s0, v73
	v_mul_f32_e32 v130, s0, v74
	v_mul_f32_e32 v131, s0, v75
	v_mul_f32_e32 v132, s0, v76
	v_mul_f32_e32 v133, s0, v77
	v_mul_f32_e32 v134, s0, v78
	v_mul_f32_e32 v135, s0, v79
	v_lshl_add_u64 v[136:137], vcc, 0, v[138:139]
	v_cvt_pk_bf16_f32 v32, v128, v129
	v_cvt_pk_bf16_f32 v33, v130, v131
	v_cvt_pk_bf16_f32 v34, v132, v133
	v_cvt_pk_bf16_f32 v35, v134, v135
	global_store_dwordx4 v[136:137], v[32:35], off
	v_mul_f32_e32 v128, s0, v64
	v_mul_f32_e32 v129, s0, v65
	v_mul_f32_e32 v130, s0, v66
	v_mul_f32_e32 v131, s0, v67
	v_mul_f32_e32 v132, s0, v68
	v_mul_f32_e32 v133, s0, v69
	v_mul_f32_e32 v134, s0, v70
	v_mul_f32_e32 v135, s0, v71
	v_lshl_add_u64 v[138:139], vcc, 0, v[136:137]
	v_cvt_pk_bf16_f32 v32, v128, v129
	v_cvt_pk_bf16_f32 v33, v130, v131
	v_cvt_pk_bf16_f32 v34, v132, v133
	v_cvt_pk_bf16_f32 v35, v134, v135
	global_store_dwordx4 v[138:139], v[32:35], off
	s_branch .Lk0_done
.Lk0_silu:
	s_mov_b32 s0, 0xbfb8aa3b
	v_mul_f32_e32 v128, s0, v120
	v_mul_f32_e32 v129, s0, v121
	v_mul_f32_e32 v130, s0, v122
	v_mul_f32_e32 v131, s0, v123
	v_mul_f32_e32 v132, s0, v124
	v_mul_f32_e32 v133, s0, v125
	v_mul_f32_e32 v134, s0, v126
	v_mul_f32_e32 v135, s0, v127
	v_exp_f32_e32 v128, v128
	v_exp_f32_e32 v129, v129
	v_exp_f32_e32 v130, v130
	v_exp_f32_e32 v131, v131
	v_exp_f32_e32 v132, v132
	v_exp_f32_e32 v133, v133
	v_exp_f32_e32 v134, v134
	v_exp_f32_e32 v135, v135
	v_add_f32_e32 v128, 1.0, v128
	v_add_f32_e32 v129, 1.0, v129
	v_add_f32_e32 v130, 1.0, v130
	v_add_f32_e32 v131, 1.0, v131
	v_add_f32_e32 v132, 1.0, v132
	v_add_f32_e32 v133, 1.0, v133
	v_add_f32_e32 v134, 1.0, v134
	v_add_f32_e32 v135, 1.0, v135
	v_rcp_f32_e32 v128, v128
	v_rcp_f32_e32 v129, v129
	v_rcp_f32_e32 v130, v130
	v_rcp_f32_e32 v131, v131
	v_rcp_f32_e32 v132, v132
	v_rcp_f32_e32 v133, v133
	v_rcp_f32_e32 v134, v134
	v_rcp_f32_e32 v135, v135
	s_nop 0
	v_mul_f32_e32 v128, v120, v128
	v_mul_f32_e32 v129, v121, v129
	v_mul_f32_e32 v130, v122, v130
	v_mul_f32_e32 v131, v123, v131
	v_mul_f32_e32 v132, v124, v132
	v_mul_f32_e32 v133, v125, v133
	v_mul_f32_e32 v134, v126, v134
	v_mul_f32_e32 v135, v127, v135
	v_cvt_pk_bf16_f32 v32, v128, v129
	v_cvt_pk_bf16_f32 v33, v130, v131
	v_cvt_pk_bf16_f32 v34, v132, v133
	v_cvt_pk_bf16_f32 v35, v134, v135
	global_store_dwordx4 v[136:137], v[32:35], off
	v_mul_f32_e32 v128, s0, v112
	v_mul_f32_e32 v129, s0, v113
	v_mul_f32_e32 v130, s0, v114
	v_mul_f32_e32 v131, s0, v115
	v_mul_f32_e32 v132, s0, v116
	v_mul_f32_e32 v133, s0, v117
	v_mul_f32_e32 v134, s0, v118
	v_mul_f32_e32 v135, s0, v119
	v_exp_f32_e32 v128, v128
	v_exp_f32_e32 v129, v129
	v_exp_f32_e32 v130, v130
	v_exp_f32_e32 v131, v131
	v_exp_f32_e32 v132, v132
	v_exp_f32_e32 v133, v133
	v_exp_f32_e32 v134, v134
	v_exp_f32_e32 v135, v135
	v_lshl_add_u64 v[138:139], vcc, 0, v[136:137]
	v_add_f32_e32 v128, 1.0, v128
	v_add_f32_e32 v129, 1.0, v129
	v_add_f32_e32 v130, 1.0, v130
	v_add_f32_e32 v131, 1.0, v131
	v_add_f32_e32 v132, 1.0, v132
	v_add_f32_e32 v133, 1.0, v133
	v_add_f32_e32 v134, 1.0, v134
	v_add_f32_e32 v135, 1.0, v135
	v_rcp_f32_e32 v128, v128
	v_rcp_f32_e32 v129, v129
	v_rcp_f32_e32 v130, v130
	v_rcp_f32_e32 v131, v131
	v_rcp_f32_e32 v132, v132
	v_rcp_f32_e32 v133, v133
	v_rcp_f32_e32 v134, v134
	v_rcp_f32_e32 v135, v135
	s_nop 0
	v_mul_f32_e32 v128, v112, v128
	v_mul_f32_e32 v129, v113, v129
	v_mul_f32_e32 v130, v114, v130
	v_mul_f32_e32 v131, v115, v131
	v_mul_f32_e32 v132, v116, v132
	v_mul_f32_e32 v133, v117, v133
	v_mul_f32_e32 v134, v118, v134
	v_mul_f32_e32 v135, v119, v135
	v_cvt_pk_bf16_f32 v32, v128, v129
	v_cvt_pk_bf16_f32 v33, v130, v131
	v_cvt_pk_bf16_f32 v34, v132, v133
	v_cvt_pk_bf16_f32 v35, v134, v135
	global_store_dwordx4 v[138:139], v[32:35], off
	v_mul_f32_e32 v128, s0, v104
	v_mul_f32_e32 v129, s0, v105
	v_mul_f32_e32 v130, s0, v106
	v_mul_f32_e32 v131, s0, v107
	v_mul_f32_e32 v132, s0, v108
	v_mul_f32_e32 v133, s0, v109
	v_mul_f32_e32 v134, s0, v110
	v_mul_f32_e32 v135, s0, v111
	v_exp_f32_e32 v128, v128
	v_exp_f32_e32 v129, v129
	v_exp_f32_e32 v130, v130
	v_exp_f32_e32 v131, v131
	v_exp_f32_e32 v132, v132
	v_exp_f32_e32 v133, v133
	v_exp_f32_e32 v134, v134
	v_exp_f32_e32 v135, v135
	v_lshl_add_u64 v[136:137], vcc, 0, v[138:139]
	v_add_f32_e32 v128, 1.0, v128
	v_add_f32_e32 v129, 1.0, v129
	v_add_f32_e32 v130, 1.0, v130
	v_add_f32_e32 v131, 1.0, v131
	v_add_f32_e32 v132, 1.0, v132
	v_add_f32_e32 v133, 1.0, v133
	v_add_f32_e32 v134, 1.0, v134
	v_add_f32_e32 v135, 1.0, v135
	v_rcp_f32_e32 v128, v128
	v_rcp_f32_e32 v129, v129
	v_rcp_f32_e32 v130, v130
	v_rcp_f32_e32 v131, v131
	v_rcp_f32_e32 v132, v132
	v_rcp_f32_e32 v133, v133
	v_rcp_f32_e32 v134, v134
	v_rcp_f32_e32 v135, v135
	s_nop 0
	v_mul_f32_e32 v128, v104, v128
	v_mul_f32_e32 v129, v105, v129
	v_mul_f32_e32 v130, v106, v130
	v_mul_f32_e32 v131, v107, v131
	v_mul_f32_e32 v132, v108, v132
	v_mul_f32_e32 v133, v109, v133
	v_mul_f32_e32 v134, v110, v134
	v_mul_f32_e32 v135, v111, v135
	v_cvt_pk_bf16_f32 v32, v128, v129
	v_cvt_pk_bf16_f32 v33, v130, v131
	v_cvt_pk_bf16_f32 v34, v132, v133
	v_cvt_pk_bf16_f32 v35, v134, v135
	global_store_dwordx4 v[136:137], v[32:35], off
	v_mul_f32_e32 v128, s0, v96
	v_mul_f32_e32 v129, s0, v97
	v_mul_f32_e32 v130, s0, v98
	v_mul_f32_e32 v131, s0, v99
	v_mul_f32_e32 v132, s0, v100
	v_mul_f32_e32 v133, s0, v101
	v_mul_f32_e32 v134, s0, v102
	v_mul_f32_e32 v135, s0, v103
	v_exp_f32_e32 v128, v128
	v_exp_f32_e32 v129, v129
	v_exp_f32_e32 v130, v130
	v_exp_f32_e32 v131, v131
	v_exp_f32_e32 v132, v132
	v_exp_f32_e32 v133, v133
	v_exp_f32_e32 v134, v134
	v_exp_f32_e32 v135, v135
	v_lshl_add_u64 v[138:139], vcc, 0, v[136:137]
	v_add_f32_e32 v128, 1.0, v128
	v_add_f32_e32 v129, 1.0, v129
	v_add_f32_e32 v130, 1.0, v130
	v_add_f32_e32 v131, 1.0, v131
	v_add_f32_e32 v132, 1.0, v132
	v_add_f32_e32 v133, 1.0, v133
	v_add_f32_e32 v134, 1.0, v134
	v_add_f32_e32 v135, 1.0, v135
	v_rcp_f32_e32 v128, v128
	v_rcp_f32_e32 v129, v129
	v_rcp_f32_e32 v130, v130
	v_rcp_f32_e32 v131, v131
	v_rcp_f32_e32 v132, v132
	v_rcp_f32_e32 v133, v133
	v_rcp_f32_e32 v134, v134
	v_rcp_f32_e32 v135, v135
	s_nop 0
	v_mul_f32_e32 v128, v96, v128
	v_mul_f32_e32 v129, v97, v129
	v_mul_f32_e32 v130, v98, v130
	v_mul_f32_e32 v131, v99, v131
	v_mul_f32_e32 v132, v100, v132
	v_mul_f32_e32 v133, v101, v133
	v_mul_f32_e32 v134, v102, v134
	v_mul_f32_e32 v135, v103, v135
	v_cvt_pk_bf16_f32 v32, v128, v129
	v_cvt_pk_bf16_f32 v33, v130, v131
	v_cvt_pk_bf16_f32 v34, v132, v133
	v_cvt_pk_bf16_f32 v35, v134, v135
	global_store_dwordx4 v[138:139], v[32:35], off
	v_mul_f32_e32 v128, s0, v88
	v_mul_f32_e32 v129, s0, v89
	v_mul_f32_e32 v130, s0, v90
	v_mul_f32_e32 v131, s0, v91
	v_mul_f32_e32 v132, s0, v210
	v_mul_f32_e32 v133, s0, v211
	v_mul_f32_e32 v134, s0, v212
	v_mul_f32_e32 v135, s0, v213
	v_exp_f32_e32 v128, v128
	v_exp_f32_e32 v129, v129
	v_exp_f32_e32 v130, v130
	v_exp_f32_e32 v131, v131
	v_exp_f32_e32 v132, v132
	v_exp_f32_e32 v133, v133
	v_exp_f32_e32 v134, v134
	v_exp_f32_e32 v135, v135
	s_mov_b32 vcc_lo, 0x5a000
	v_lshl_add_u64 v[136:137], vcc, 0, v[138:139]
	s_mov_b32 vcc_lo, 0x12000
	v_add_f32_e32 v128, 1.0, v128
	v_add_f32_e32 v129, 1.0, v129
	v_add_f32_e32 v130, 1.0, v130
	v_add_f32_e32 v131, 1.0, v131
	v_add_f32_e32 v132, 1.0, v132
	v_add_f32_e32 v133, 1.0, v133
	v_add_f32_e32 v134, 1.0, v134
	v_add_f32_e32 v135, 1.0, v135
	v_rcp_f32_e32 v128, v128
	v_rcp_f32_e32 v129, v129
	v_rcp_f32_e32 v130, v130
	v_rcp_f32_e32 v131, v131
	v_rcp_f32_e32 v132, v132
	v_rcp_f32_e32 v133, v133
	v_rcp_f32_e32 v134, v134
	v_rcp_f32_e32 v135, v135
	s_nop 0
	v_mul_f32_e32 v128, v88, v128
	v_mul_f32_e32 v129, v89, v129
	v_mul_f32_e32 v130, v90, v130
	v_mul_f32_e32 v131, v91, v131
	v_mul_f32_e32 v132, v210, v132
	v_mul_f32_e32 v133, v211, v133
	v_mul_f32_e32 v134, v212, v134
	v_mul_f32_e32 v135, v213, v135
	v_cvt_pk_bf16_f32 v32, v128, v129
	v_cvt_pk_bf16_f32 v33, v130, v131
	v_cvt_pk_bf16_f32 v34, v132, v133
	v_cvt_pk_bf16_f32 v35, v134, v135
	global_store_dwordx4 v[136:137], v[32:35], off
	v_mul_f32_e32 v128, s0, v80
	v_mul_f32_e32 v129, s0, v81
	v_mul_f32_e32 v130, s0, v82
	v_mul_f32_e32 v131, s0, v83
	v_mul_f32_e32 v132, s0, v84
	v_mul_f32_e32 v133, s0, v85
	v_mul_f32_e32 v134, s0, v86
	v_mul_f32_e32 v135, s0, v87
	v_exp_f32_e32 v128, v128
	v_exp_f32_e32 v129, v129
	v_exp_f32_e32 v130, v130
	v_exp_f32_e32 v131, v131
	v_exp_f32_e32 v132, v132
	v_exp_f32_e32 v133, v133
	v_exp_f32_e32 v134, v134
	v_exp_f32_e32 v135, v135
	v_lshl_add_u64 v[138:139], vcc, 0, v[136:137]
	v_add_f32_e32 v128, 1.0, v128
	v_add_f32_e32 v129, 1.0, v129
	v_add_f32_e32 v130, 1.0, v130
	v_add_f32_e32 v131, 1.0, v131
	v_add_f32_e32 v132, 1.0, v132
	v_add_f32_e32 v133, 1.0, v133
	v_add_f32_e32 v134, 1.0, v134
	v_add_f32_e32 v135, 1.0, v135
	v_rcp_f32_e32 v128, v128
	v_rcp_f32_e32 v129, v129
	v_rcp_f32_e32 v130, v130
	v_rcp_f32_e32 v131, v131
	v_rcp_f32_e32 v132, v132
	v_rcp_f32_e32 v133, v133
	v_rcp_f32_e32 v134, v134
	v_rcp_f32_e32 v135, v135
	s_nop 0
	v_mul_f32_e32 v128, v80, v128
	v_mul_f32_e32 v129, v81, v129
	v_mul_f32_e32 v130, v82, v130
	v_mul_f32_e32 v131, v83, v131
	v_mul_f32_e32 v132, v84, v132
	v_mul_f32_e32 v133, v85, v133
	v_mul_f32_e32 v134, v86, v134
	v_mul_f32_e32 v135, v87, v135
	v_cvt_pk_bf16_f32 v32, v128, v129
	v_cvt_pk_bf16_f32 v33, v130, v131
	v_cvt_pk_bf16_f32 v34, v132, v133
	v_cvt_pk_bf16_f32 v35, v134, v135
	global_store_dwordx4 v[138:139], v[32:35], off
	v_mul_f32_e32 v128, s0, v72
	v_mul_f32_e32 v129, s0, v73
	v_mul_f32_e32 v130, s0, v74
	v_mul_f32_e32 v131, s0, v75
	v_mul_f32_e32 v132, s0, v76
	v_mul_f32_e32 v133, s0, v77
	v_mul_f32_e32 v134, s0, v78
	v_mul_f32_e32 v135, s0, v79
	v_exp_f32_e32 v128, v128
	v_exp_f32_e32 v129, v129
	v_exp_f32_e32 v130, v130
	v_exp_f32_e32 v131, v131
	v_exp_f32_e32 v132, v132
	v_exp_f32_e32 v133, v133
	v_exp_f32_e32 v134, v134
	v_exp_f32_e32 v135, v135
	v_lshl_add_u64 v[136:137], vcc, 0, v[138:139]
	v_add_f32_e32 v128, 1.0, v128
	v_add_f32_e32 v129, 1.0, v129
	v_add_f32_e32 v130, 1.0, v130
	v_add_f32_e32 v131, 1.0, v131
	v_add_f32_e32 v132, 1.0, v132
	v_add_f32_e32 v133, 1.0, v133
	v_add_f32_e32 v134, 1.0, v134
	v_add_f32_e32 v135, 1.0, v135
	v_rcp_f32_e32 v128, v128
	v_rcp_f32_e32 v129, v129
	v_rcp_f32_e32 v130, v130
	v_rcp_f32_e32 v131, v131
	v_rcp_f32_e32 v132, v132
	v_rcp_f32_e32 v133, v133
	v_rcp_f32_e32 v134, v134
	v_rcp_f32_e32 v135, v135
	s_nop 0
	v_mul_f32_e32 v128, v72, v128
	v_mul_f32_e32 v129, v73, v129
	v_mul_f32_e32 v130, v74, v130
	v_mul_f32_e32 v131, v75, v131
	v_mul_f32_e32 v132, v76, v132
	v_mul_f32_e32 v133, v77, v133
	v_mul_f32_e32 v134, v78, v134
	v_mul_f32_e32 v135, v79, v135
	v_cvt_pk_bf16_f32 v32, v128, v129
	v_cvt_pk_bf16_f32 v33, v130, v131
	v_cvt_pk_bf16_f32 v34, v132, v133
	v_cvt_pk_bf16_f32 v35, v134, v135
	global_store_dwordx4 v[136:137], v[32:35], off
	v_mul_f32_e32 v128, s0, v64
	v_mul_f32_e32 v129, s0, v65
	v_mul_f32_e32 v130, s0, v66
	v_mul_f32_e32 v131, s0, v67
	v_mul_f32_e32 v132, s0, v68
	v_mul_f32_e32 v133, s0, v69
	v_mul_f32_e32 v134, s0, v70
	v_mul_f32_e32 v135, s0, v71
	v_exp_f32_e32 v128, v128
	v_exp_f32_e32 v129, v129
	v_exp_f32_e32 v130, v130
	v_exp_f32_e32 v131, v131
	v_exp_f32_e32 v132, v132
	v_exp_f32_e32 v133, v133
	v_exp_f32_e32 v134, v134
	v_exp_f32_e32 v135, v135
	v_lshl_add_u64 v[138:139], vcc, 0, v[136:137]
	v_add_f32_e32 v128, 1.0, v128
	v_add_f32_e32 v129, 1.0, v129
	v_add_f32_e32 v130, 1.0, v130
	v_add_f32_e32 v131, 1.0, v131
	v_add_f32_e32 v132, 1.0, v132
	v_add_f32_e32 v133, 1.0, v133
	v_add_f32_e32 v134, 1.0, v134
	v_add_f32_e32 v135, 1.0, v135
	v_rcp_f32_e32 v128, v128
	v_rcp_f32_e32 v129, v129
	v_rcp_f32_e32 v130, v130
	v_rcp_f32_e32 v131, v131
	v_rcp_f32_e32 v132, v132
	v_rcp_f32_e32 v133, v133
	v_rcp_f32_e32 v134, v134
	v_rcp_f32_e32 v135, v135
	s_nop 0
	v_mul_f32_e32 v128, v64, v128
	v_mul_f32_e32 v129, v65, v129
	v_mul_f32_e32 v130, v66, v130
	v_mul_f32_e32 v131, v67, v131
	v_mul_f32_e32 v132, v68, v132
	v_mul_f32_e32 v133, v69, v133
	v_mul_f32_e32 v134, v70, v134
	v_mul_f32_e32 v135, v71, v135
	v_cvt_pk_bf16_f32 v32, v128, v129
	v_cvt_pk_bf16_f32 v33, v130, v131
	v_cvt_pk_bf16_f32 v34, v132, v133
	v_cvt_pk_bf16_f32 v35, v134, v135
	global_store_dwordx4 v[138:139], v[32:35], off

.Lk1_scale:
	s_mov_b32 s0, 0x3e38aa3b
	v_mul_f32_e32 v64, s0, v56
	v_mul_f32_e32 v65, s0, v57
	v_mul_f32_e32 v66, s0, v58
	v_mul_f32_e32 v67, s0, v59
	v_mul_f32_e32 v68, s0, v60
	v_mul_f32_e32 v69, s0, v61
	v_mul_f32_e32 v70, s0, v62
	v_mul_f32_e32 v71, s0, v63
	v_cvt_pk_bf16_f32 v32, v64, v65
	v_cvt_pk_bf16_f32 v33, v66, v67
	v_cvt_pk_bf16_f32 v34, v68, v69
	v_cvt_pk_bf16_f32 v35, v70, v71
	global_store_dwordx4 v[72:73], v[32:35], off offset:256
	v_mul_f32_e32 v64, s0, v48
	v_mul_f32_e32 v65, s0, v49
	v_mul_f32_e32 v66, s0, v50
	v_mul_f32_e32 v67, s0, v51
	v_mul_f32_e32 v68, s0, v52
	v_mul_f32_e32 v69, s0, v53
	v_mul_f32_e32 v70, s0, v54
	v_mul_f32_e32 v71, s0, v55
	v_lshl_add_u64 v[74:75], vcc, 0, v[72:73]
	v_cvt_pk_bf16_f32 v32, v64, v65
	v_cvt_pk_bf16_f32 v33, v66, v67
	v_cvt_pk_bf16_f32 v34, v68, v69
	v_cvt_pk_bf16_f32 v35, v70, v71
	global_store_dwordx4 v[74:75], v[32:35], off offset:256
	v_mul_f32_e32 v64, s0, v40
	v_mul_f32_e32 v65, s0, v41
	v_mul_f32_e32 v66, s0, v42
	v_mul_f32_e32 v67, s0, v43
	v_mul_f32_e32 v68, s0, v44
	v_mul_f32_e32 v69, s0, v45
	v_mul_f32_e32 v70, s0, v46
	v_mul_f32_e32 v71, s0, v47
	v_lshl_add_u64 v[72:73], vcc, 0, v[74:75]
	v_cvt_pk_bf16_f32 v32, v64, v65
	v_cvt_pk_bf16_f32 v33, v66, v67
	v_cvt_pk_bf16_f32 v34, v68, v69
	v_cvt_pk_bf16_f32 v35, v70, v71
	global_store_dwordx4 v[72:73], v[32:35], off offset:256
	v_mul_f32_e32 v64, s0, v180
	v_mul_f32_e32 v65, s0, v181
	v_mul_f32_e32 v66, s0, v182
	v_mul_f32_e32 v67, s0, v183
	v_mul_f32_e32 v68, s0, v36
	v_mul_f32_e32 v69, s0, v37
	v_mul_f32_e32 v70, s0, v38
	v_mul_f32_e32 v71, s0, v39
	v_lshl_add_u64 v[74:75], vcc, 0, v[72:73]
	v_cvt_pk_bf16_f32 v32, v64, v65
	v_cvt_pk_bf16_f32 v33, v66, v67
	v_cvt_pk_bf16_f32 v34, v68, v69
	v_cvt_pk_bf16_f32 v35, v70, v71
	global_store_dwordx4 v[74:75], v[32:35], off offset:256
	v_mul_f32_e32 v64, s0, v24
	v_mul_f32_e32 v65, s0, v25
	v_mul_f32_e32 v66, s0, v26
	v_mul_f32_e32 v67, s0, v27
	v_mul_f32_e32 v68, s0, v28
	v_mul_f32_e32 v69, s0, v29
	v_mul_f32_e32 v70, s0, v30
	v_mul_f32_e32 v71, s0, v31
	s_mov_b32 vcc_lo, 0x5a000
	v_lshl_add_u64 v[72:73], vcc, 0, v[74:75]
	s_mov_b32 vcc_lo, 0x12000
	v_cvt_pk_bf16_f32 v32, v64, v65
	v_cvt_pk_bf16_f32 v33, v66, v67
	v_cvt_pk_bf16_f32 v34, v68, v69
	v_cvt_pk_bf16_f32 v35, v70, v71
	global_store_dwordx4 v[72:73], v[32:35], off offset:256
	v_mul_f32_e32 v64, s0, v16
	v_mul_f32_e32 v65, s0, v17
	v_mul_f32_e32 v66, s0, v18
	v_mul_f32_e32 v67, s0, v19
	v_mul_f32_e32 v68, s0, v20
	v_mul_f32_e32 v69, s0, v21
	v_mul_f32_e32 v70, s0, v22
	v_mul_f32_e32 v71, s0, v23
	v_lshl_add_u64 v[74:75], vcc, 0, v[72:73]
	v_cvt_pk_bf16_f32 v32, v64, v65
	v_cvt_pk_bf16_f32 v33, v66, v67
	v_cvt_pk_bf16_f32 v34, v68, v69
	v_cvt_pk_bf16_f32 v35, v70, v71
	global_store_dwordx4 v[74:75], v[32:35], off offset:256
	v_mul_f32_e32 v64, s0, v8
	v_mul_f32_e32 v65, s0, v9
	v_mul_f32_e32 v66, s0, v10
	v_mul_f32_e32 v67, s0, v11
	v_mul_f32_e32 v68, s0, v12
	v_mul_f32_e32 v69, s0, v13
	v_mul_f32_e32 v70, s0, v14
	v_mul_f32_e32 v71, s0, v15
	v_lshl_add_u64 v[72:73], vcc, 0, v[74:75]
	v_cvt_pk_bf16_f32 v32, v64, v65
	v_cvt_pk_bf16_f32 v33, v66, v67
	v_cvt_pk_bf16_f32 v34, v68, v69
	v_cvt_pk_bf16_f32 v35, v70, v71
	global_store_dwordx4 v[72:73], v[32:35], off offset:256
	v_mul_f32_e32 v64, s0, v0
	v_mul_f32_e32 v65, s0, v1
	v_mul_f32_e32 v66, s0, v2
	v_mul_f32_e32 v67, s0, v3
	v_mul_f32_e32 v68, s0, v4
	v_mul_f32_e32 v69, s0, v5
	v_mul_f32_e32 v70, s0, v6
	v_mul_f32_e32 v71, s0, v7
	v_lshl_add_u64 v[74:75], vcc, 0, v[72:73]
	v_cvt_pk_bf16_f32 v32, v64, v65
	v_cvt_pk_bf16_f32 v33, v66, v67
	v_cvt_pk_bf16_f32 v34, v68, v69
	v_cvt_pk_bf16_f32 v35, v70, v71
	global_store_dwordx4 v[74:75], v[32:35], off offset:256
	s_branch .Lk1_done
.Lk1_silu:
	s_mov_b32 s0, 0xbfb8aa3b
	v_mul_f32_e32 v64, s0, v56
	v_mul_f32_e32 v65, s0, v57
	v_mul_f32_e32 v66, s0, v58
	v_mul_f32_e32 v67, s0, v59
	v_mul_f32_e32 v68, s0, v60
	v_mul_f32_e32 v69, s0, v61
	v_mul_f32_e32 v70, s0, v62
	v_mul_f32_e32 v71, s0, v63
	v_exp_f32_e32 v64, v64
	v_exp_f32_e32 v65, v65
	v_exp_f32_e32 v66, v66
	v_exp_f32_e32 v67, v67
	v_exp_f32_e32 v68, v68
	v_exp_f32_e32 v69, v69
	v_exp_f32_e32 v70, v70
	v_exp_f32_e32 v71, v71
	v_add_f32_e32 v64, 1.0, v64
	v_add_f32_e32 v65, 1.0, v65
	v_add_f32_e32 v66, 1.0, v66
	v_add_f32_e32 v67, 1.0, v67
	v_add_f32_e32 v68, 1.0, v68
	v_add_f32_e32 v69, 1.0, v69
	v_add_f32_e32 v70, 1.0, v70
	v_add_f32_e32 v71, 1.0, v71
	v_rcp_f32_e32 v64, v64
	v_rcp_f32_e32 v65, v65
	v_rcp_f32_e32 v66, v66
	v_rcp_f32_e32 v67, v67
	v_rcp_f32_e32 v68, v68
	v_rcp_f32_e32 v69, v69
	v_rcp_f32_e32 v70, v70
	v_rcp_f32_e32 v71, v71
	s_nop 0
	v_mul_f32_e32 v64, v56, v64
	v_mul_f32_e32 v65, v57, v65
	v_mul_f32_e32 v66, v58, v66
	v_mul_f32_e32 v67, v59, v67
	v_mul_f32_e32 v68, v60, v68
	v_mul_f32_e32 v69, v61, v69
	v_mul_f32_e32 v70, v62, v70
	v_mul_f32_e32 v71, v63, v71
	v_cvt_pk_bf16_f32 v32, v64, v65
	v_cvt_pk_bf16_f32 v33, v66, v67
	v_cvt_pk_bf16_f32 v34, v68, v69
	v_cvt_pk_bf16_f32 v35, v70, v71
	global_store_dwordx4 v[72:73], v[32:35], off offset:256
	v_mul_f32_e32 v64, s0, v48
	v_mul_f32_e32 v65, s0, v49
	v_mul_f32_e32 v66, s0, v50
	v_mul_f32_e32 v67, s0, v51
	v_mul_f32_e32 v68, s0, v52
	v_mul_f32_e32 v69, s0, v53
	v_mul_f32_e32 v70, s0, v54
	v_mul_f32_e32 v71, s0, v55
	v_exp_f32_e32 v64, v64
	v_exp_f32_e32 v65, v65
	v_exp_f32_e32 v66, v66
	v_exp_f32_e32 v67, v67
	v_exp_f32_e32 v68, v68
	v_exp_f32_e32 v69, v69
	v_exp_f32_e32 v70, v70
	v_exp_f32_e32 v71, v71
	v_lshl_add_u64 v[74:75], vcc, 0, v[72:73]
	v_add_f32_e32 v64, 1.0, v64
	v_add_f32_e32 v65, 1.0, v65
	v_add_f32_e32 v66, 1.0, v66
	v_add_f32_e32 v67, 1.0, v67
	v_add_f32_e32 v68, 1.0, v68
	v_add_f32_e32 v69, 1.0, v69
	v_add_f32_e32 v70, 1.0, v70
	v_add_f32_e32 v71, 1.0, v71
	v_rcp_f32_e32 v64, v64
	v_rcp_f32_e32 v65, v65
	v_rcp_f32_e32 v66, v66
	v_rcp_f32_e32 v67, v67
	v_rcp_f32_e32 v68, v68
	v_rcp_f32_e32 v69, v69
	v_rcp_f32_e32 v70, v70
	v_rcp_f32_e32 v71, v71
	s_nop 0
	v_mul_f32_e32 v64, v48, v64
	v_mul_f32_e32 v65, v49, v65
	v_mul_f32_e32 v66, v50, v66
	v_mul_f32_e32 v67, v51, v67
	v_mul_f32_e32 v68, v52, v68
	v_mul_f32_e32 v69, v53, v69
	v_mul_f32_e32 v70, v54, v70
	v_mul_f32_e32 v71, v55, v71
	v_cvt_pk_bf16_f32 v32, v64, v65
	v_cvt_pk_bf16_f32 v33, v66, v67
	v_cvt_pk_bf16_f32 v34, v68, v69
	v_cvt_pk_bf16_f32 v35, v70, v71
	global_store_dwordx4 v[74:75], v[32:35], off offset:256
	v_mul_f32_e32 v64, s0, v40
	v_mul_f32_e32 v65, s0, v41
	v_mul_f32_e32 v66, s0, v42
	v_mul_f32_e32 v67, s0, v43
	v_mul_f32_e32 v68, s0, v44
	v_mul_f32_e32 v69, s0, v45
	v_mul_f32_e32 v70, s0, v46
	v_mul_f32_e32 v71, s0, v47
	v_exp_f32_e32 v64, v64
	v_exp_f32_e32 v65, v65
	v_exp_f32_e32 v66, v66
	v_exp_f32_e32 v67, v67
	v_exp_f32_e32 v68, v68
	v_exp_f32_e32 v69, v69
	v_exp_f32_e32 v70, v70
	v_exp_f32_e32 v71, v71
	v_lshl_add_u64 v[72:73], vcc, 0, v[74:75]
	v_add_f32_e32 v64, 1.0, v64
	v_add_f32_e32 v65, 1.0, v65
	v_add_f32_e32 v66, 1.0, v66
	v_add_f32_e32 v67, 1.0, v67
	v_add_f32_e32 v68, 1.0, v68
	v_add_f32_e32 v69, 1.0, v69
	v_add_f32_e32 v70, 1.0, v70
	v_add_f32_e32 v71, 1.0, v71
	v_rcp_f32_e32 v64, v64
	v_rcp_f32_e32 v65, v65
	v_rcp_f32_e32 v66, v66
	v_rcp_f32_e32 v67, v67
	v_rcp_f32_e32 v68, v68
	v_rcp_f32_e32 v69, v69
	v_rcp_f32_e32 v70, v70
	v_rcp_f32_e32 v71, v71
	s_nop 0
	v_mul_f32_e32 v64, v40, v64
	v_mul_f32_e32 v65, v41, v65
	v_mul_f32_e32 v66, v42, v66
	v_mul_f32_e32 v67, v43, v67
	v_mul_f32_e32 v68, v44, v68
	v_mul_f32_e32 v69, v45, v69
	v_mul_f32_e32 v70, v46, v70
	v_mul_f32_e32 v71, v47, v71
	v_cvt_pk_bf16_f32 v32, v64, v65
	v_cvt_pk_bf16_f32 v33, v66, v67
	v_cvt_pk_bf16_f32 v34, v68, v69
	v_cvt_pk_bf16_f32 v35, v70, v71
	global_store_dwordx4 v[72:73], v[32:35], off offset:256
	v_mul_f32_e32 v64, s0, v180
	v_mul_f32_e32 v65, s0, v181
	v_mul_f32_e32 v66, s0, v182
	v_mul_f32_e32 v67, s0, v183
	v_mul_f32_e32 v68, s0, v36
	v_mul_f32_e32 v69, s0, v37
	v_mul_f32_e32 v70, s0, v38
	v_mul_f32_e32 v71, s0, v39
	v_exp_f32_e32 v64, v64
	v_exp_f32_e32 v65, v65
	v_exp_f32_e32 v66, v66
	v_exp_f32_e32 v67, v67
	v_exp_f32_e32 v68, v68
	v_exp_f32_e32 v69, v69
	v_exp_f32_e32 v70, v70
	v_exp_f32_e32 v71, v71
	v_lshl_add_u64 v[74:75], vcc, 0, v[72:73]
	v_add_f32_e32 v64, 1.0, v64
	v_add_f32_e32 v65, 1.0, v65
	v_add_f32_e32 v66, 1.0, v66
	v_add_f32_e32 v67, 1.0, v67
	v_add_f32_e32 v68, 1.0, v68
	v_add_f32_e32 v69, 1.0, v69
	v_add_f32_e32 v70, 1.0, v70
	v_add_f32_e32 v71, 1.0, v71
	v_rcp_f32_e32 v64, v64
	v_rcp_f32_e32 v65, v65
	v_rcp_f32_e32 v66, v66
	v_rcp_f32_e32 v67, v67
	v_rcp_f32_e32 v68, v68
	v_rcp_f32_e32 v69, v69
	v_rcp_f32_e32 v70, v70
	v_rcp_f32_e32 v71, v71
	s_nop 0
	v_mul_f32_e32 v64, v180, v64
	v_mul_f32_e32 v65, v181, v65
	v_mul_f32_e32 v66, v182, v66
	v_mul_f32_e32 v67, v183, v67
	v_mul_f32_e32 v68, v36, v68
	v_mul_f32_e32 v69, v37, v69
	v_mul_f32_e32 v70, v38, v70
	v_mul_f32_e32 v71, v39, v71
	v_cvt_pk_bf16_f32 v32, v64, v65
	v_cvt_pk_bf16_f32 v33, v66, v67
	v_cvt_pk_bf16_f32 v34, v68, v69
	v_cvt_pk_bf16_f32 v35, v70, v71
	global_store_dwordx4 v[74:75], v[32:35], off offset:256
	v_mul_f32_e32 v64, s0, v24
	v_mul_f32_e32 v65, s0, v25
	v_mul_f32_e32 v66, s0, v26
	v_mul_f32_e32 v67, s0, v27
	v_mul_f32_e32 v68, s0, v28
	v_mul_f32_e32 v69, s0, v29
	v_mul_f32_e32 v70, s0, v30
	v_mul_f32_e32 v71, s0, v31
	v_exp_f32_e32 v64, v64
	v_exp_f32_e32 v65, v65
	v_exp_f32_e32 v66, v66
	v_exp_f32_e32 v67, v67
	v_exp_f32_e32 v68, v68
	v_exp_f32_e32 v69, v69
	v_exp_f32_e32 v70, v70
	v_exp_f32_e32 v71, v71
	s_mov_b32 vcc_lo, 0x5a000
	v_lshl_add_u64 v[72:73], vcc, 0, v[74:75]
	s_mov_b32 vcc_lo, 0x12000
	v_add_f32_e32 v64, 1.0, v64
	v_add_f32_e32 v65, 1.0, v65
	v_add_f32_e32 v66, 1.0, v66
	v_add_f32_e32 v67, 1.0, v67
	v_add_f32_e32 v68, 1.0, v68
	v_add_f32_e32 v69, 1.0, v69
	v_add_f32_e32 v70, 1.0, v70
	v_add_f32_e32 v71, 1.0, v71
	v_rcp_f32_e32 v64, v64
	v_rcp_f32_e32 v65, v65
	v_rcp_f32_e32 v66, v66
	v_rcp_f32_e32 v67, v67
	v_rcp_f32_e32 v68, v68
	v_rcp_f32_e32 v69, v69
	v_rcp_f32_e32 v70, v70
	v_rcp_f32_e32 v71, v71
	s_nop 0
	v_mul_f32_e32 v64, v24, v64
	v_mul_f32_e32 v65, v25, v65
	v_mul_f32_e32 v66, v26, v66
	v_mul_f32_e32 v67, v27, v67
	v_mul_f32_e32 v68, v28, v68
	v_mul_f32_e32 v69, v29, v69
	v_mul_f32_e32 v70, v30, v70
	v_mul_f32_e32 v71, v31, v71
	v_cvt_pk_bf16_f32 v32, v64, v65
	v_cvt_pk_bf16_f32 v33, v66, v67
	v_cvt_pk_bf16_f32 v34, v68, v69
	v_cvt_pk_bf16_f32 v35, v70, v71
	global_store_dwordx4 v[72:73], v[32:35], off offset:256
	v_mul_f32_e32 v64, s0, v16
	v_mul_f32_e32 v65, s0, v17
	v_mul_f32_e32 v66, s0, v18
	v_mul_f32_e32 v67, s0, v19
	v_mul_f32_e32 v68, s0, v20
	v_mul_f32_e32 v69, s0, v21
	v_mul_f32_e32 v70, s0, v22
	v_mul_f32_e32 v71, s0, v23
	v_exp_f32_e32 v64, v64
	v_exp_f32_e32 v65, v65
	v_exp_f32_e32 v66, v66
	v_exp_f32_e32 v67, v67
	v_exp_f32_e32 v68, v68
	v_exp_f32_e32 v69, v69
	v_exp_f32_e32 v70, v70
	v_exp_f32_e32 v71, v71
	v_lshl_add_u64 v[74:75], vcc, 0, v[72:73]
	v_add_f32_e32 v64, 1.0, v64
	v_add_f32_e32 v65, 1.0, v65
	v_add_f32_e32 v66, 1.0, v66
	v_add_f32_e32 v67, 1.0, v67
	v_add_f32_e32 v68, 1.0, v68
	v_add_f32_e32 v69, 1.0, v69
	v_add_f32_e32 v70, 1.0, v70
	v_add_f32_e32 v71, 1.0, v71
	v_rcp_f32_e32 v64, v64
	v_rcp_f32_e32 v65, v65
	v_rcp_f32_e32 v66, v66
	v_rcp_f32_e32 v67, v67
	v_rcp_f32_e32 v68, v68
	v_rcp_f32_e32 v69, v69
	v_rcp_f32_e32 v70, v70
	v_rcp_f32_e32 v71, v71
	s_nop 0
	v_mul_f32_e32 v64, v16, v64
	v_mul_f32_e32 v65, v17, v65
	v_mul_f32_e32 v66, v18, v66
	v_mul_f32_e32 v67, v19, v67
	v_mul_f32_e32 v68, v20, v68
	v_mul_f32_e32 v69, v21, v69
	v_mul_f32_e32 v70, v22, v70
	v_mul_f32_e32 v71, v23, v71
	v_cvt_pk_bf16_f32 v32, v64, v65
	v_cvt_pk_bf16_f32 v33, v66, v67
	v_cvt_pk_bf16_f32 v34, v68, v69
	v_cvt_pk_bf16_f32 v35, v70, v71
	global_store_dwordx4 v[74:75], v[32:35], off offset:256
	v_mul_f32_e32 v64, s0, v8
	v_mul_f32_e32 v65, s0, v9
	v_mul_f32_e32 v66, s0, v10
	v_mul_f32_e32 v67, s0, v11
	v_mul_f32_e32 v68, s0, v12
	v_mul_f32_e32 v69, s0, v13
	v_mul_f32_e32 v70, s0, v14
	v_mul_f32_e32 v71, s0, v15
	v_exp_f32_e32 v64, v64
	v_exp_f32_e32 v65, v65
	v_exp_f32_e32 v66, v66
	v_exp_f32_e32 v67, v67
	v_exp_f32_e32 v68, v68
	v_exp_f32_e32 v69, v69
	v_exp_f32_e32 v70, v70
	v_exp_f32_e32 v71, v71
	v_lshl_add_u64 v[72:73], vcc, 0, v[74:75]
	v_add_f32_e32 v64, 1.0, v64
	v_add_f32_e32 v65, 1.0, v65
	v_add_f32_e32 v66, 1.0, v66
	v_add_f32_e32 v67, 1.0, v67
	v_add_f32_e32 v68, 1.0, v68
	v_add_f32_e32 v69, 1.0, v69
	v_add_f32_e32 v70, 1.0, v70
	v_add_f32_e32 v71, 1.0, v71
	v_rcp_f32_e32 v64, v64
	v_rcp_f32_e32 v65, v65
	v_rcp_f32_e32 v66, v66
	v_rcp_f32_e32 v67, v67
	v_rcp_f32_e32 v68, v68
	v_rcp_f32_e32 v69, v69
	v_rcp_f32_e32 v70, v70
	v_rcp_f32_e32 v71, v71
	s_nop 0
	v_mul_f32_e32 v64, v8, v64
	v_mul_f32_e32 v65, v9, v65
	v_mul_f32_e32 v66, v10, v66
	v_mul_f32_e32 v67, v11, v67
	v_mul_f32_e32 v68, v12, v68
	v_mul_f32_e32 v69, v13, v69
	v_mul_f32_e32 v70, v14, v70
	v_mul_f32_e32 v71, v15, v71
	v_cvt_pk_bf16_f32 v32, v64, v65
	v_cvt_pk_bf16_f32 v33, v66, v67
	v_cvt_pk_bf16_f32 v34, v68, v69
	v_cvt_pk_bf16_f32 v35, v70, v71
	global_store_dwordx4 v[72:73], v[32:35], off offset:256
	v_mul_f32_e32 v64, s0, v0
	v_mul_f32_e32 v65, s0, v1
	v_mul_f32_e32 v66, s0, v2
	v_mul_f32_e32 v67, s0, v3
	v_mul_f32_e32 v68, s0, v4
	v_mul_f32_e32 v69, s0, v5
	v_mul_f32_e32 v70, s0, v6
	v_mul_f32_e32 v71, s0, v7
	v_exp_f32_e32 v64, v64
	v_exp_f32_e32 v65, v65
	v_exp_f32_e32 v66, v66
	v_exp_f32_e32 v67, v67
	v_exp_f32_e32 v68, v68
	v_exp_f32_e32 v69, v69
	v_exp_f32_e32 v70, v70
	v_exp_f32_e32 v71, v71
	v_lshl_add_u64 v[74:75], vcc, 0, v[72:73]
	v_add_f32_e32 v64, 1.0, v64
	v_add_f32_e32 v65, 1.0, v65
	v_add_f32_e32 v66, 1.0, v66
	v_add_f32_e32 v67, 1.0, v67
	v_add_f32_e32 v68, 1.0, v68
	v_add_f32_e32 v69, 1.0, v69
	v_add_f32_e32 v70, 1.0, v70
	v_add_f32_e32 v71, 1.0, v71
	v_rcp_f32_e32 v64, v64
	v_rcp_f32_e32 v65, v65
	v_rcp_f32_e32 v66, v66
	v_rcp_f32_e32 v67, v67
	v_rcp_f32_e32 v68, v68
	v_rcp_f32_e32 v69, v69
	v_rcp_f32_e32 v70, v70
	v_rcp_f32_e32 v71, v71
	s_nop 0
	v_mul_f32_e32 v64, v0, v64
	v_mul_f32_e32 v65, v1, v65
	v_mul_f32_e32 v66, v2, v66
	v_mul_f32_e32 v67, v3, v67
	v_mul_f32_e32 v68, v4, v68
	v_mul_f32_e32 v69, v5, v69
	v_mul_f32_e32 v70, v6, v70
	v_mul_f32_e32 v71, v7, v71
	v_cvt_pk_bf16_f32 v32, v64, v65
	v_cvt_pk_bf16_f32 v33, v66, v67
	v_cvt_pk_bf16_f32 v34, v68, v69
	v_cvt_pk_bf16_f32 v35, v70, v71
	global_store_dwordx4 v[74:75], v[32:35], off offset:256

.LBB0_887:
	s_add_i32 s9, s2, -1
	s_min_i32 s9, s9, s3
	s_lshl_b32 s9, s9, 6
	s_waitcnt vmcnt(1)
	ds_write_b128 v153, v[112:115] offset:16384
	s_waitcnt vmcnt(0)
	ds_write_b128 v153, v[116:119] offset:24576
	v_mad_i64_i32 v[64:65], s[18:19], s9, v237, v[140:141]
	global_load_dwordx4 v[112:115], v[64:65], off offset:2048
	global_load_dwordx4 v[116:119], v[144:145], off offset:-128
	ds_read_b128 v[64:67], v150 offset:8192
	ds_read_b128 v[68:71], v150 offset:12288
	ds_read_b128 v[72:75], v149 offset:8192
	ds_read_b128 v[76:79], v149 offset:12288
	s_waitcnt lgkmcnt(3)
	v_mfma_f32_32x32x16_bf16 v[16:31], v[64:67], v[132:135], v[16:31]
	v_max_f32_e32 v64, v33, v33
	v_max_f32_e32 v65, v32, v32
	v_max_f32_e32 v64, v65, v64
	v_max3_f32 v64, v64, v34, v35
	v_max3_f32 v64, v64, v36, v37
	v_max3_f32 v80, v64, v38, v39
	s_waitcnt lgkmcnt(2)
	v_mfma_f32_32x32x16_bf16 v[0:15], v[68:71], v[132:135], v[0:15]
	ds_read_b128 v[64:67], v148 offset:8192
	ds_read_b128 v[68:71], v148 offset:12288
	v_max3_f32 v80, v80, v40, v41
	v_max3_f32 v80, v80, v42, v43
	v_max3_f32 v80, v80, v44, v45
	v_max3_f32 v84, v80, v46, v47
	s_waitcnt lgkmcnt(3)
	v_mfma_f32_32x32x16_bf16 v[16:31], v[72:75], v[128:131], v[16:31]
	ds_read_b128 v[72:75], v139 offset:8192
	ds_read_b128 v[80:83], v139 offset:12288
	v_max3_f32 v84, v84, v48, v49
	v_max3_f32 v84, v84, v50, v51
	v_max3_f32 v84, v84, v52, v53
	v_max3_f32 v84, v84, v54, v55
	s_waitcnt lgkmcnt(4)
	v_mfma_f32_32x32x16_bf16 v[0:15], v[76:79], v[128:131], v[0:15]
	v_max3_f32 v76, v84, v56, v57
	v_max3_f32 v76, v76, v58, v59
	v_max3_f32 v76, v76, v60, v61
	v_max3_f32 v76, v76, v62, v63
	v_mov_b32_e32 v77, v76
	s_nop 1
	v_permlane32_swap_b32_e32 v76, v77
	v_max_f32_e32 v77, v77, v77
	v_max_f32_e32 v76, v76, v76
	v_max_f32_e32 v76, v76, v77
	v_add_f32_e32 v77, 0x41000000, v160
	v_cmp_gt_f32_e32 vcc, v76, v77
	s_nop 1
	v_cndmask_b32_e32 v128, v160, v76, vcc
	v_sub_f32_e32 v134, v160, v128
	s_waitcnt lgkmcnt(3)
	v_mfma_f32_32x32x16_bf16 v[16:31], v[64:67], v[124:127], v[16:31]
	v_add_u32_e32 v129, v154, v155
	ds_read_b128 v[64:67], v129
	ds_read_b128 v[76:79], v129 offset:4096
	s_waitcnt lgkmcnt(4)
	v_mfma_f32_32x32x16_bf16 v[0:15], v[68:71], v[124:127], v[0:15]
	v_add_u32_e32 v124, v154, v156
	ds_read_b128 v[130:133], v124
	ds_read_b128 v[160:163], v124 offset:4096
	s_waitcnt lgkmcnt(5)
	v_mfma_f32_32x32x16_bf16 v[16:31], v[72:75], v[120:123], v[16:31]
	s_waitcnt lgkmcnt(4)
	v_mfma_f32_32x32x16_bf16 v[0:15], v[80:83], v[120:123], v[0:15]
	s_waitcnt lgkmcnt(3)
	v_mfma_f32_32x32x16_bf16 v[80:95], v[64:67], v[96:99], 0
	v_add_u32_e32 v121, v154, v158
	ds_read_b128 v[164:167], v121
	ds_read_b128 v[168:171], v121 offset:4096
	s_waitcnt lgkmcnt(4)
	v_mfma_f32_32x32x16_bf16 v[64:79], v[76:79], v[96:99], 0
	v_add_u32_e32 v122, v154, v159
	ds_read_b128 v[172:175], v122
	ds_read_b128 v[178:181], v122 offset:4096
	s_waitcnt lgkmcnt(5)
	v_mfma_f32_32x32x16_bf16 v[80:95], v[130:133], v[100:103], v[80:95]
	s_waitcnt lgkmcnt(4)
	v_mfma_f32_32x32x16_bf16 v[64:79], v[160:163], v[100:103], v[64:79]
	v_exp_f32_e32 v120, v134
	s_waitcnt lgkmcnt(3)
	v_mfma_f32_32x32x16_bf16 v[80:95], v[164:167], v[104:107], v[80:95]
	s_waitcnt lgkmcnt(2)
	v_mfma_f32_32x32x16_bf16 v[64:79], v[168:171], v[104:107], v[64:79]
	s_waitcnt lgkmcnt(1)
	v_mfma_f32_32x32x16_bf16 v[80:95], v[172:175], v[108:111], v[80:95]
	s_waitcnt lgkmcnt(0)
	v_mfma_f32_32x32x16_bf16 v[64:79], v[178:181], v[108:111], v[64:79]
	s_cbranch_vccz .LBB0_889
	v_mul_f32_e32 v30, v120, v30
	v_mul_f32_e32 v31, v120, v31
	v_mul_f32_e32 v28, v120, v28
	v_mul_f32_e32 v29, v120, v29
	v_mul_f32_e32 v26, v120, v26
	v_mul_f32_e32 v27, v120, v27
	v_mul_f32_e32 v24, v120, v24
	v_mul_f32_e32 v25, v120, v25
	v_mul_f32_e32 v22, v120, v22
	v_mul_f32_e32 v23, v120, v23
	v_mul_f32_e32 v20, v120, v20
	v_mul_f32_e32 v21, v120, v21
	v_mul_f32_e32 v18, v120, v18
	v_mul_f32_e32 v19, v120, v19
	v_mul_f32_e32 v16, v120, v16
	v_mul_f32_e32 v17, v120, v17
	v_mul_f32_e32 v14, v120, v14
	v_mul_f32_e32 v15, v120, v15
	v_mul_f32_e32 v12, v120, v12
	v_mul_f32_e32 v13, v120, v13
	v_mul_f32_e32 v10, v120, v10
	v_mul_f32_e32 v11, v120, v11
	v_mul_f32_e32 v8, v120, v8
	v_mul_f32_e32 v9, v120, v9
	v_mul_f32_e32 v6, v120, v6
	v_mul_f32_e32 v7, v120, v7
	v_mul_f32_e32 v4, v120, v4
	v_mul_f32_e32 v5, v120, v5
	v_mul_f32_e32 v2, v120, v2
	v_mul_f32_e32 v3, v120, v3
	v_mul_f32_e32 v0, v120, v0
	v_mul_f32_e32 v1, v120, v1
.LBB0_889:
	v_sub_f32_e32 v32, v32, v128
	v_exp_f32_e32 v123, v32
	v_sub_f32_e32 v32, v33, v128
	v_exp_f32_e32 v125, v32
	v_sub_f32_e32 v32, v34, v128
	v_exp_f32_e32 v126, v32
	v_sub_f32_e32 v32, v35, v128
	v_exp_f32_e32 v127, v32
	v_sub_f32_e32 v32, v36, v128
	v_exp_f32_e32 v130, v32
	v_sub_f32_e32 v32, v37, v128
	v_exp_f32_e32 v131, v32
	v_sub_f32_e32 v32, v38, v128
	v_exp_f32_e32 v132, v32
	v_sub_f32_e32 v32, v39, v128
	v_exp_f32_e32 v133, v32
	v_sub_f32_e32 v32, v40, v128
	v_exp_f32_e32 v134, v32
	v_sub_f32_e32 v32, v41, v128
	v_exp_f32_e32 v135, v32
	v_sub_f32_e32 v32, v42, v128
	v_exp_f32_e32 v161, v32
	v_sub_f32_e32 v32, v43, v128
	v_exp_f32_e32 v162, v32
	v_sub_f32_e32 v32, v44, v128
	v_exp_f32_e32 v163, v32
	v_sub_f32_e32 v32, v45, v128
	v_exp_f32_e32 v164, v32
	v_sub_f32_e32 v32, v46, v128
	v_exp_f32_e32 v165, v32
	v_sub_f32_e32 v32, v47, v128
	s_min_i32 s9, s2, s3
	v_exp_f32_e32 v166, v32
	v_sub_f32_e32 v32, v48, v128
	s_lshl_b32 s9, s9, 6
	v_exp_f32_e32 v167, v32
	v_sub_f32_e32 v32, v49, v128
	s_waitcnt lgkmcnt(0)
	s_barrier
	s_waitcnt vmcnt(1)
	ds_write_b128 v153, v[112:115]
	s_waitcnt vmcnt(0)
	ds_write_b128 v153, v[116:119] offset:8192
	v_mad_i64_i32 v[48:49], s[18:19], s9, v237, v[140:141]
	global_load_dwordx4 v[112:115], v[48:49], off offset:2048
	global_load_dwordx4 v[116:119], v[144:145], off
	v_exp_f32_e32 v168, v32
	v_sub_f32_e32 v32, v50, v128
	v_exp_f32_e32 v169, v32
	v_sub_f32_e32 v32, v51, v128
	v_exp_f32_e32 v170, v32
	v_sub_f32_e32 v32, v52, v128
	v_exp_f32_e32 v171, v32
	v_sub_f32_e32 v32, v53, v128
	v_exp_f32_e32 v172, v32
	v_sub_f32_e32 v32, v54, v128
	v_exp_f32_e32 v173, v32
	v_sub_f32_e32 v32, v55, v128
	v_exp_f32_e32 v174, v32
	v_sub_f32_e32 v32, v56, v128
	v_exp_f32_e32 v175, v32
	v_sub_f32_e32 v32, v57, v128
	v_exp_f32_e32 v176, v32
	v_sub_f32_e32 v32, v58, v128
	v_exp_f32_e32 v178, v32
	v_sub_f32_e32 v32, v59, v128
	v_exp_f32_e32 v179, v32
	v_sub_f32_e32 v32, v60, v128
	v_exp_f32_e32 v180, v32
	v_sub_f32_e32 v32, v61, v128
	v_exp_f32_e32 v181, v32
	v_sub_f32_e32 v32, v62, v128
	v_exp_f32_e32 v182, v32
	v_sub_f32_e32 v32, v63, v128
	v_exp_f32_e32 v183, v32
	v_cvt_pk_bf16_f32 v44, v123, v125
	v_cvt_pk_bf16_f32 v45, v126, v127
	v_cvt_pk_bf16_f32 v46, v130, v131
	v_cvt_pk_bf16_f32 v47, v132, v133
	v_cvt_pk_bf16_f32 v40, v134, v135
	v_cvt_pk_bf16_f32 v41, v161, v162
	v_cvt_pk_bf16_f32 v42, v163, v164
	v_cvt_pk_bf16_f32 v43, v165, v166
	v_cvt_pk_bf16_f32 v36, v167, v168
	v_cvt_pk_bf16_f32 v37, v169, v170
	v_cvt_pk_bf16_f32 v38, v171, v172
	v_cvt_pk_bf16_f32 v39, v173, v174
	v_cvt_pk_bf16_f32 v32, v175, v176
	v_cvt_pk_bf16_f32 v33, v178, v179
	v_cvt_pk_bf16_f32 v34, v180, v181
	v_cvt_pk_bf16_f32 v35, v182, v183
	ds_read_b128 v[48:51], v150 offset:24576
	ds_read_b128 v[52:55], v150 offset:28672
	ds_read_b128 v[56:59], v149 offset:24576
	ds_read_b128 v[60:63], v149 offset:28672
	s_waitcnt lgkmcnt(3)
	v_mfma_f32_32x32x16_bf16 v[16:31], v[48:51], v[44:47], v[16:31]
	v_max_f32_e32 v48, v81, v81
	v_max_f32_e32 v49, v80, v80
	v_max_f32_e32 v48, v49, v48
	v_max3_f32 v48, v48, v82, v83
	v_max3_f32 v48, v48, v84, v85
	v_max3_f32 v146, v48, v86, v87
	s_waitcnt lgkmcnt(2)
	v_mfma_f32_32x32x16_bf16 v[0:15], v[52:55], v[44:47], v[0:15]
	ds_read_b128 v[44:47], v148 offset:24576
	ds_read_b128 v[48:51], v148 offset:28672
	v_max3_f32 v52, v146, v88, v89
	v_max3_f32 v52, v52, v90, v91
	v_max3_f32 v52, v52, v92, v93
	v_max3_f32 v146, v52, v94, v95
	s_waitcnt lgkmcnt(3)
	v_mfma_f32_32x32x16_bf16 v[16:31], v[56:59], v[40:43], v[16:31]
	ds_read_b128 v[52:55], v139 offset:24576
	ds_read_b128 v[56:59], v139 offset:28672
	v_max3_f32 v146, v146, v64, v65
	v_max3_f32 v146, v146, v66, v67
	v_max3_f32 v146, v146, v68, v69
	v_max3_f32 v146, v146, v70, v71
	s_waitcnt lgkmcnt(4)
	v_mfma_f32_32x32x16_bf16 v[0:15], v[60:63], v[40:43], v[0:15]
	v_max3_f32 v40, v146, v72, v73
	v_max3_f32 v40, v40, v74, v75
	v_max3_f32 v40, v40, v76, v77
	v_max3_f32 v40, v40, v78, v79
	v_mov_b32_e32 v41, v40
	s_nop 1
	v_permlane32_swap_b32_e32 v40, v41
	v_max_f32_e32 v41, v41, v41
	v_max_f32_e32 v40, v40, v40
	v_max_f32_e32 v40, v40, v41
	v_add_f32_e32 v41, 0x41000000, v128
	v_cmp_gt_f32_e32 vcc, v40, v41
	s_nop 1
	v_cndmask_b32_e32 v160, v128, v40, vcc
	v_sub_f32_e32 v128, v128, v160
	s_waitcnt lgkmcnt(3)
	v_mfma_f32_32x32x16_bf16 v[16:31], v[44:47], v[36:39], v[16:31]
	ds_read_b128 v[40:43], v129 offset:16384
	ds_read_b128 v[60:63], v129 offset:20480
	s_waitcnt lgkmcnt(4)
	v_mfma_f32_32x32x16_bf16 v[0:15], v[48:51], v[36:39], v[0:15]
	ds_read_b128 v[184:187], v124 offset:16384
	ds_read_b128 v[188:191], v124 offset:20480
	s_waitcnt lgkmcnt(5)
	v_mfma_f32_32x32x16_bf16 v[16:31], v[52:55], v[32:35], v[16:31]
	s_waitcnt lgkmcnt(4)
	v_mfma_f32_32x32x16_bf16 v[0:15], v[56:59], v[32:35], v[0:15]
	s_waitcnt lgkmcnt(3)
	v_mfma_f32_32x32x16_bf16 v[32:47], v[40:43], v[96:99], 0
	ds_read_b128 v[192:195], v121 offset:16384
	ds_read_b128 v[196:199], v121 offset:20480
	s_waitcnt lgkmcnt(4)
	v_mfma_f32_32x32x16_bf16 v[48:63], v[60:63], v[96:99], 0
	ds_read_b128 v[200:203], v122 offset:16384
	ds_read_b128 v[204:207], v122 offset:20480
	s_waitcnt lgkmcnt(5)
	v_mfma_f32_32x32x16_bf16 v[32:47], v[184:187], v[100:103], v[32:47]
	s_waitcnt lgkmcnt(4)
	v_mfma_f32_32x32x16_bf16 v[48:63], v[188:191], v[100:103], v[48:63]
	v_exp_f32_e32 v146, v128
	s_waitcnt lgkmcnt(3)
	v_mfma_f32_32x32x16_bf16 v[32:47], v[192:195], v[104:107], v[32:47]
	s_waitcnt lgkmcnt(2)
	v_mfma_f32_32x32x16_bf16 v[48:63], v[196:199], v[104:107], v[48:63]
	s_waitcnt lgkmcnt(1)
	v_mfma_f32_32x32x16_bf16 v[32:47], v[200:203], v[108:111], v[32:47]
	s_waitcnt lgkmcnt(0)
	v_mfma_f32_32x32x16_bf16 v[48:63], v[204:207], v[108:111], v[48:63]
	s_cbranch_vccz .LBB0_891
	v_mul_f32_e32 v30, v146, v30
	v_mul_f32_e32 v31, v146, v31
	v_mul_f32_e32 v28, v146, v28
	v_mul_f32_e32 v29, v146, v29
	v_mul_f32_e32 v26, v146, v26
	v_mul_f32_e32 v27, v146, v27
	v_mul_f32_e32 v24, v146, v24
	v_mul_f32_e32 v25, v146, v25
	v_mul_f32_e32 v22, v146, v22
	v_mul_f32_e32 v23, v146, v23
	v_mul_f32_e32 v20, v146, v20
	v_mul_f32_e32 v21, v146, v21
	v_mul_f32_e32 v18, v146, v18
	v_mul_f32_e32 v19, v146, v19
	v_mul_f32_e32 v16, v146, v16
	v_mul_f32_e32 v17, v146, v17
	v_mul_f32_e32 v14, v146, v14
	v_mul_f32_e32 v15, v146, v15
	v_mul_f32_e32 v12, v146, v12
	v_mul_f32_e32 v13, v146, v13
	v_mul_f32_e32 v10, v146, v10
	v_mul_f32_e32 v11, v146, v11
	v_mul_f32_e32 v8, v146, v8
	v_mul_f32_e32 v9, v146, v9
	v_mul_f32_e32 v6, v146, v6
	v_mul_f32_e32 v7, v146, v7
	v_mul_f32_e32 v4, v146, v4
	v_mul_f32_e32 v5, v146, v5
	v_mul_f32_e32 v2, v146, v2
	v_mul_f32_e32 v3, v146, v3
	v_mul_f32_e32 v0, v146, v0
	v_mul_f32_e32 v1, v146, v1

.LBB0_893:
	v_ashrrev_i32_e32 v64, 1, v151
	s_waitcnt vmcnt(1)
	ds_write_b128 v153, v[112:115] offset:16384
	s_waitcnt vmcnt(0)
	ds_write_b128 v153, v[116:119] offset:24576
	v_and_or_b32 v112, v64, s88, v157
	v_mov_b64_e32 v[64:65], s[12:13]
	v_mad_i64_i32 v[64:65], s[2:3], v112, s33, v[64:65]
	v_lshlrev_b32_e32 v176, 4, v147
	v_lshl_add_u64 v[64:65], v[64:65], 0, v[176:177]
	global_load_dwordx4 v[92:95], v[64:65], off offset:2560
	global_load_dwordx4 v[88:91], v[64:65], off offset:2592
	global_load_dwordx4 v[84:87], v[64:65], off offset:2624
	global_load_dwordx4 v[80:83], v[64:65], off offset:2656
	v_mov_b64_e32 v[64:65], s[14:15]
	v_mad_i64_i32 v[64:65], s[2:3], v112, s33, v[64:65]
	v_and_b32_e32 v176, 16, v152
	v_lshl_add_u64 v[64:65], v[64:65], 0, v[176:177]
	global_load_dwordx4 v[96:99], v[64:65], off offset:1024
	global_load_dwordx4 v[100:103], v[64:65], off offset:1056
	global_load_dwordx4 v[104:107], v[64:65], off offset:1088
	global_load_dwordx4 v[108:111], v[64:65], off offset:1120
	v_lshl_add_u64 v[64:65], s[34:35], 0, v[142:143]
	v_lshlrev_b32_e32 v176, 1, v138
	v_lshl_add_u64 v[72:73], v[64:65], 0, v[176:177]
	s_mov_b32 s2, 0x48000
	v_add_co_u32_e32 v68, vcc, s2, v72
	s_mov_b32 s2, 0x90000
	s_nop 0
	v_addc_co_u32_e32 v69, vcc, 0, v73, vcc
	global_load_dwordx4 v[64:67], v[72:73], off offset:2048
	s_nop 0
	global_load_dwordx4 v[68:71], v[68:69], off offset:2048
	v_add_co_u32_e32 v72, vcc, s2, v72
	v_mad_i64_i32 v[76:77], s[2:3], s8, v136, 0
	v_lshl_add_u64 v[76:77], v[76:77], 1, s[10:11]
	v_addc_co_u32_e32 v73, vcc, 0, v73, vcc
	v_lshl_add_u64 v[76:77], v[76:77], 0, v[176:177]
	global_load_dwordx4 v[72:75], v[72:73], off offset:2048
	s_nop 0
	global_load_dwordx4 v[76:79], v[76:77], off
	ds_read_b128 v[114:117], v150 offset:8192
	ds_read_b128 v[140:143], v150 offset:12288
	ds_read_b128 v[152:155], v149 offset:8192
	ds_read_b128 v[156:159], v149 offset:12288
	v_max_f32_e32 v113, v33, v33
	s_waitcnt lgkmcnt(3)
	v_mfma_f32_32x32x16_bf16 v[16:31], v[114:117], v[132:135], v[16:31]
	v_max_f32_e32 v114, v32, v32
	v_max_f32_e32 v113, v114, v113
	v_max3_f32 v113, v113, v34, v35
	v_max3_f32 v113, v113, v36, v37
	v_max3_f32 v113, v113, v38, v39
	s_waitcnt lgkmcnt(2)
	v_mfma_f32_32x32x16_bf16 v[0:15], v[140:143], v[132:135], v[0:15]
	ds_read_b128 v[114:117], v148 offset:8192
	ds_read_b128 v[132:135], v148 offset:12288
	v_max3_f32 v113, v113, v40, v41
	v_max3_f32 v113, v113, v42, v43
	v_max3_f32 v113, v113, v44, v45
	v_max3_f32 v113, v113, v46, v47
	s_waitcnt lgkmcnt(3)
	v_mfma_f32_32x32x16_bf16 v[16:31], v[152:155], v[128:131], v[16:31]
	ds_read_b128 v[140:143], v139 offset:8192
	ds_read_b128 v[152:155], v139 offset:12288
	v_max3_f32 v113, v113, v48, v49
	v_max3_f32 v113, v113, v50, v51
	v_max3_f32 v113, v113, v52, v53
	v_max3_f32 v113, v113, v54, v55
	v_max3_f32 v113, v113, v56, v57
	v_max3_f32 v113, v113, v58, v59
	s_waitcnt lgkmcnt(4)
	v_mfma_f32_32x32x16_bf16 v[0:15], v[156:159], v[128:131], v[0:15]
	v_max3_f32 v113, v113, v60, v61
	v_max3_f32 v113, v113, v62, v63
	v_mov_b32_e32 v118, v113
	s_nop 1
	v_permlane32_swap_b32_e32 v113, v118
	v_max_f32_e32 v118, v118, v118
	v_max_f32_e32 v113, v113, v113
	v_max_f32_e32 v113, v113, v118
	v_add_f32_e32 v118, 0x41000000, v160
	v_cmp_gt_f32_e32 vcc, v113, v118
	s_nop 1
	v_cndmask_b32_e32 v128, v160, v113, vcc
	v_sub_f32_e32 v113, v160, v128
	s_waitcnt lgkmcnt(3)
	v_mfma_f32_32x32x16_bf16 v[16:31], v[114:117], v[124:127], v[16:31]
	s_waitcnt lgkmcnt(2)
	v_mfma_f32_32x32x16_bf16 v[0:15], v[132:135], v[124:127], v[0:15]
	s_waitcnt lgkmcnt(1)
	v_mfma_f32_32x32x16_bf16 v[16:31], v[140:143], v[120:123], v[16:31]
	s_waitcnt lgkmcnt(0)
	v_mfma_f32_32x32x16_bf16 v[0:15], v[152:155], v[120:123], v[0:15]
	v_exp_f32_e32 v114, v113
	s_cbranch_vccz .LBB0_895
	s_nop 7
	v_mul_f32_e32 v30, v114, v30
	v_mul_f32_e32 v31, v114, v31
	v_mul_f32_e32 v28, v114, v28
	v_mul_f32_e32 v29, v114, v29
	v_mul_f32_e32 v26, v114, v26
	v_mul_f32_e32 v27, v114, v27
	v_mul_f32_e32 v24, v114, v24
	v_mul_f32_e32 v25, v114, v25
	v_mul_f32_e32 v22, v114, v22
	v_mul_f32_e32 v23, v114, v23
	v_mul_f32_e32 v20, v114, v20
	v_mul_f32_e32 v21, v114, v21
	v_mul_f32_e32 v18, v114, v18
	v_mul_f32_e32 v19, v114, v19
	v_mul_f32_e32 v16, v114, v16
	v_mul_f32_e32 v17, v114, v17
	v_mul_f32_e32 v14, v114, v14
	v_mul_f32_e32 v15, v114, v15
	v_mul_f32_e32 v12, v114, v12
	v_mul_f32_e32 v13, v114, v13
	v_mul_f32_e32 v10, v114, v10
	v_mul_f32_e32 v11, v114, v11
	v_mul_f32_e32 v8, v114, v8
	v_mul_f32_e32 v9, v114, v9
	v_mul_f32_e32 v6, v114, v6
	v_mul_f32_e32 v7, v114, v7
	v_mul_f32_e32 v4, v114, v4
	v_mul_f32_e32 v5, v114, v5
	v_mul_f32_e32 v2, v114, v2
	v_mul_f32_e32 v3, v114, v3
	v_mul_f32_e32 v0, v114, v0
	v_mul_f32_e32 v1, v114, v1
.LBB0_895:
	v_sub_f32_e32 v32, v32, v128
	v_exp_f32_e32 v129, v32
	v_sub_f32_e32 v32, v33, v128
	v_sub_f32_e32 v33, v34, v128
	v_exp_f32_e32 v131, v33
	v_sub_f32_e32 v33, v35, v128
	v_sub_f32_e32 v34, v36, v128
	v_sub_f32_e32 v35, v38, v128
	s_waitcnt lgkmcnt(0)
	s_barrier
	v_exp_f32_e32 v133, v34
	v_sub_f32_e32 v34, v37, v128
	v_exp_f32_e32 v135, v35
	v_sub_f32_e32 v35, v39, v128
	ds_read_b128 v[36:39], v150 offset:24576
	v_sub_f32_e32 v56, v56, v128
	v_sub_f32_e32 v48, v48, v128
	v_sub_f32_e32 v40, v40, v128
	v_exp_f32_e32 v116, v56
	v_sub_f32_e32 v56, v57, v128
	v_sub_f32_e32 v57, v58, v128
	v_exp_f32_e32 v120, v48
	v_sub_f32_e32 v48, v49, v128
	v_sub_f32_e32 v49, v50, v128
	v_exp_f32_e32 v124, v40
	v_sub_f32_e32 v40, v41, v128
	v_sub_f32_e32 v41, v42, v128
	v_exp_f32_e32 v118, v57
	v_sub_f32_e32 v57, v59, v128
	v_sub_f32_e32 v58, v60, v128
	v_sub_f32_e32 v59, v62, v128
	v_exp_f32_e32 v122, v49
	v_sub_f32_e32 v49, v51, v128
	v_sub_f32_e32 v50, v52, v128
	v_sub_f32_e32 v51, v54, v128
	v_exp_f32_e32 v126, v41
	v_sub_f32_e32 v41, v43, v128
	v_sub_f32_e32 v42, v44, v128
	v_sub_f32_e32 v43, v46, v128
	v_exp_f32_e32 v60, v58
	v_sub_f32_e32 v58, v61, v128
	v_exp_f32_e32 v62, v59
	v_sub_f32_e32 v59, v63, v128
	v_exp_f32_e32 v52, v50
	v_sub_f32_e32 v50, v53, v128
	v_exp_f32_e32 v54, v51
	v_sub_f32_e32 v51, v55, v128
	v_exp_f32_e32 v44, v42
	v_sub_f32_e32 v42, v45, v128
	v_exp_f32_e32 v46, v43
	v_sub_f32_e32 v43, v47, v128
	v_exp_f32_e32 v130, v32
	v_exp_f32_e32 v132, v33
	v_exp_f32_e32 v134, v34
	v_exp_f32_e32 v128, v35
	v_cvt_pk_bf16_f32 v32, v129, v130
	v_cvt_pk_bf16_f32 v33, v131, v132
	v_cvt_pk_bf16_f32 v34, v133, v134
	v_cvt_pk_bf16_f32 v35, v135, v128
	v_exp_f32_e32 v125, v40
	v_exp_f32_e32 v127, v41
	s_waitcnt lgkmcnt(0)
	v_mfma_f32_32x32x16_bf16 v[16:31], v[36:39], v[32:35], v[16:31]
	ds_read_b128 v[36:39], v150 offset:28672
	v_exp_f32_e32 v45, v42
	v_exp_f32_e32 v47, v43
	v_cvt_pk_bf16_f32 v40, v124, v125
	v_cvt_pk_bf16_f32 v41, v126, v127
	v_cvt_pk_bf16_f32 v42, v44, v45
	v_cvt_pk_bf16_f32 v43, v46, v47
	s_waitcnt lgkmcnt(0)
	v_mfma_f32_32x32x16_bf16 v[0:15], v[36:39], v[32:35], v[0:15]
	ds_read_b128 v[32:35], v149 offset:24576
	v_exp_f32_e32 v121, v48
	v_exp_f32_e32 v123, v49
	v_exp_f32_e32 v53, v50
	v_exp_f32_e32 v55, v51
	v_cvt_pk_bf16_f32 v48, v120, v121
	v_cvt_pk_bf16_f32 v49, v122, v123
	s_waitcnt lgkmcnt(0)
	v_mfma_f32_32x32x16_bf16 v[16:31], v[32:35], v[40:43], v[16:31]
	ds_read_b128 v[32:35], v149 offset:28672
	v_cvt_pk_bf16_f32 v50, v52, v53
	v_cvt_pk_bf16_f32 v51, v54, v55
	v_exp_f32_e32 v117, v56
	v_exp_f32_e32 v119, v57
	v_exp_f32_e32 v61, v58
	v_exp_f32_e32 v63, v59
	s_waitcnt lgkmcnt(0)
	v_mfma_f32_32x32x16_bf16 v[0:15], v[32:35], v[40:43], v[0:15]
	ds_read_b128 v[32:35], v148 offset:24576
	v_cvt_pk_bf16_f32 v56, v116, v117
	v_cvt_pk_bf16_f32 v57, v118, v119
	v_cvt_pk_bf16_f32 v58, v60, v61
	v_cvt_pk_bf16_f32 v59, v62, v63
	s_waitcnt vmcnt(11)
	v_mov_b32_e32 v40, v95
	s_nop 1
	v_permlane32_swap_b32_e32 v93, v40
	s_waitcnt lgkmcnt(0)
	v_mfma_f32_32x32x16_bf16 v[16:31], v[32:35], v[48:51], v[16:31]
	ds_read_b128 v[32:35], v148 offset:28672
	v_ashrrev_i32_e32 v113, 31, v112
	v_lshlrev_b32_e32 v115, 3, v147
	v_lshlrev_b32_e32 v176, 1, v115
	s_waitcnt lgkmcnt(0)
	v_mfma_f32_32x32x16_bf16 v[0:15], v[32:35], v[48:51], v[0:15]
	ds_read_b128 v[32:35], v139 offset:24576
	s_waitcnt lgkmcnt(0)
	v_mfma_f32_32x32x16_bf16 v[16:31], v[32:35], v[56:59], v[16:31]
	ds_read_b128 v[32:35], v139 offset:28672
	s_waitcnt lgkmcnt(0)
	v_mfma_f32_32x32x16_bf16 v[0:15], v[32:35], v[56:59], v[0:15]
	v_add_f32_e32 v32, 0, v129
	v_add_f32_e32 v32, v130, v32
	v_add_f32_e32 v32, v131, v32
	v_add_f32_e32 v32, v132, v32
	v_add_f32_e32 v32, v133, v32
	v_add_f32_e32 v32, v134, v32
	v_add_f32_e32 v32, v135, v32
	v_add_f32_e32 v32, v128, v32
	v_add_f32_e32 v32, v124, v32
	v_add_f32_e32 v32, v125, v32
	v_add_f32_e32 v32, v126, v32
	v_add_f32_e32 v32, v127, v32
	v_add_f32_e32 v32, v44, v32
	v_add_f32_e32 v32, v45, v32
	v_add_f32_e32 v32, v46, v32
	v_add_f32_e32 v32, v47, v32
	v_add_f32_e32 v32, v120, v32
	v_add_f32_e32 v32, v121, v32
	v_add_f32_e32 v32, v122, v32
	v_add_f32_e32 v32, v123, v32
	v_add_f32_e32 v32, v52, v32
	v_add_f32_e32 v32, v53, v32
	v_add_f32_e32 v32, v54, v32
	v_add_f32_e32 v32, v55, v32
	v_add_f32_e32 v32, v116, v32
	v_add_f32_e32 v32, v117, v32
	v_add_f32_e32 v32, v118, v32
	v_add_f32_e32 v32, v119, v32
	v_add_f32_e32 v32, v60, v32
	v_add_f32_e32 v32, v61, v32
	v_add_f32_e32 v32, v62, v32
	v_add_f32_e32 v32, v63, v32
	v_fmac_f32_e32 v32, v137, v114
	v_mov_b32_e32 v33, v32
	s_nop 1
	v_permlane32_swap_b32_e32 v32, v33
	v_add_f32_e32 v32, v32, v33
	v_div_scale_f32 v33, s[2:3], v32, v32, 1.0
	v_rcp_f32_e32 v34, v33
	s_mov_b64 s[2:3], 0x200
	v_fma_f32 v35, -v33, v34, 1.0
	v_fmac_f32_e32 v34, v35, v34
	v_div_scale_f32 v35, vcc, 1.0, v32, 1.0
	v_mul_f32_e32 v36, v35, v34
	v_fma_f32 v37, -v33, v36, v35
	v_fmac_f32_e32 v36, v37, v34
	v_fma_f32 v33, -v33, v36, v35
	v_div_fmas_f32 v33, v33, v34, v36
	v_mov_b32_e32 v35, v94
	v_div_fixup_f32 v34, v33, v32, 1.0
	s_nop 0
	v_permlane32_swap_b32_e32 v92, v35
	v_lshlrev_b32_e32 v38, 16, v92
	v_and_b32_e32 v39, 0xffff0000, v92
	v_mul_f32_e32 v16, v16, v34
	v_mul_f32_e32 v17, v17, v34
	v_mul_f32_e32 v18, v18, v34
	v_mul_f32_e32 v19, v19, v34
	v_mul_f32_e32 v16, v16, v38
	v_mul_f32_e32 v17, v17, v39
	v_lshlrev_b32_e32 v38, 16, v93
	v_and_b32_e32 v39, 0xffff0000, v93
	v_mul_f32_e32 v18, v18, v38
	v_mul_f32_e32 v19, v19, v39
	v_cvt_pk_bf16_f32 v16, v16, v17
	v_cvt_pk_bf16_f32 v17, v18, v19
	v_lshlrev_b32_e32 v18, 16, v35
	v_and_b32_e32 v19, 0xffff0000, v35
	v_mul_f32_e32 v20, v20, v34
	v_mul_f32_e32 v21, v21, v34
	v_mul_f32_e32 v22, v22, v34
	v_mul_f32_e32 v23, v23, v34
	v_mul_f32_e32 v18, v20, v18
	v_mul_f32_e32 v19, v21, v19
	v_lshlrev_b32_e32 v20, 16, v40
	v_and_b32_e32 v21, 0xffff0000, v40
	v_lshlrev_b64 v[32:33], 11, v[112:113]
	v_mul_f32_e32 v20, v22, v20
	v_mul_f32_e32 v21, v23, v21
	v_lshl_add_u64 v[32:33], s[6:7], 0, v[32:33]
	v_cvt_pk_bf16_f32 v18, v18, v19
	v_cvt_pk_bf16_f32 v19, v20, v21
	s_waitcnt vmcnt(10)
	v_mov_b32_e32 v22, v90
	v_lshl_add_u64 v[36:37], v[32:33], 0, v[176:177]
	v_permlane32_swap_b32_e32 v16, v18
	v_permlane32_swap_b32_e32 v17, v19
	v_permlane32_swap_b32_e32 v88, v22
	v_mov_b32_e32 v23, v91
	global_store_dwordx4 v[36:37], v[16:19], off offset:512
	s_nop 0
	v_permlane32_swap_b32_e32 v89, v23
	v_lshlrev_b32_e32 v16, 16, v88
	v_and_b32_e32 v17, 0xffff0000, v88
	v_mul_f32_e32 v18, v24, v34
	v_mul_f32_e32 v19, v25, v34
	v_mul_f32_e32 v20, v26, v34
	v_mul_f32_e32 v21, v27, v34
	v_mul_f32_e32 v16, v18, v16
	v_mul_f32_e32 v17, v19, v17
	v_lshlrev_b32_e32 v18, 16, v89
	v_and_b32_e32 v19, 0xffff0000, v89
	v_mul_f32_e32 v18, v20, v18
	v_mul_f32_e32 v19, v21, v19
	v_cvt_pk_bf16_f32 v16, v16, v17
	v_cvt_pk_bf16_f32 v17, v18, v19
	v_lshlrev_b32_e32 v18, 16, v22
	v_and_b32_e32 v19, 0xffff0000, v22
	v_mul_f32_e32 v20, v28, v34
	v_mul_f32_e32 v21, v29, v34
	v_mul_f32_e32 v0, v0, v34
	v_mul_f32_e32 v1, v1, v34
	v_mul_f32_e32 v18, v20, v18
	v_mul_f32_e32 v19, v21, v19
	v_lshlrev_b32_e32 v20, 16, v23
	v_and_b32_e32 v21, 0xffff0000, v23
	v_mul_f32_e32 v22, v30, v34
	v_mul_f32_e32 v23, v31, v34
	v_cvt_pk_bf16_f32 v18, v18, v19
	v_mul_f32_e32 v20, v22, v20
	v_mul_f32_e32 v21, v23, v21
	s_nop 0
	v_permlane32_swap_b32_e32 v16, v18
	v_cvt_pk_bf16_f32 v19, v20, v21
	s_nop 1
	v_permlane32_swap_b32_e32 v17, v19
	global_store_dwordx4 v[36:37], v[16:19], off offset:544
	v_mul_f32_e32 v2, v2, v34
	v_mul_f32_e32 v3, v3, v34
	v_mul_f32_e32 v4, v4, v34
	v_mul_f32_e32 v5, v5, v34
	s_waitcnt vmcnt(11)
	v_mov_b32_e32 v18, v86
	s_nop 1
	v_permlane32_swap_b32_e32 v84, v18
	v_mov_b32_e32 v19, v87
	s_nop 1
	v_permlane32_swap_b32_e32 v85, v19
	v_lshlrev_b32_e32 v16, 16, v84
	v_and_b32_e32 v17, 0xffff0000, v84
	v_mul_f32_e32 v0, v0, v16
	v_mul_f32_e32 v1, v1, v17
	v_lshlrev_b32_e32 v16, 16, v85
	v_and_b32_e32 v17, 0xffff0000, v85
	v_mul_f32_e32 v2, v2, v16
	v_mul_f32_e32 v3, v3, v17
	v_cvt_pk_bf16_f32 v0, v0, v1
	v_cvt_pk_bf16_f32 v1, v2, v3
	v_lshlrev_b32_e32 v2, 16, v18
	v_and_b32_e32 v3, 0xffff0000, v18
	v_mul_f32_e32 v2, v4, v2
	v_mul_f32_e32 v3, v5, v3
	v_lshlrev_b32_e32 v4, 16, v19
	v_and_b32_e32 v5, 0xffff0000, v19
	v_mul_f32_e32 v6, v6, v34
	v_mul_f32_e32 v7, v7, v34
	v_cvt_pk_bf16_f32 v2, v2, v3
	v_mul_f32_e32 v4, v6, v4
	v_mul_f32_e32 v5, v7, v5
	s_waitcnt vmcnt(10)
	v_mov_b32_e32 v6, v82
	v_cvt_pk_bf16_f32 v3, v4, v5
	v_permlane32_swap_b32_e32 v0, v2
	s_nop 0
	v_permlane32_swap_b32_e32 v1, v3
	v_permlane32_swap_b32_e32 v80, v6
	v_mov_b32_e32 v7, v83
	global_store_dwordx4 v[36:37], v[0:3], off offset:576
	s_nop 0
	v_permlane32_swap_b32_e32 v81, v7
	v_lshlrev_b32_e32 v0, 16, v80
	v_and_b32_e32 v1, 0xffff0000, v80
	v_mul_f32_e32 v2, v8, v34
	v_mul_f32_e32 v3, v9, v34
	v_mul_f32_e32 v4, v10, v34
	v_mul_f32_e32 v5, v11, v34
	v_mul_f32_e32 v0, v2, v0
	v_mul_f32_e32 v1, v3, v1
	v_lshlrev_b32_e32 v2, 16, v81
	v_and_b32_e32 v3, 0xffff0000, v81
	v_mul_f32_e32 v2, v4, v2
	v_mul_f32_e32 v3, v5, v3
	v_cvt_pk_bf16_f32 v0, v0, v1
	v_cvt_pk_bf16_f32 v1, v2, v3
	v_lshlrev_b32_e32 v2, 16, v6
	v_and_b32_e32 v3, 0xffff0000, v6
	v_mul_f32_e32 v4, v12, v34
	v_mul_f32_e32 v5, v13, v34
	v_lshl_add_u64 v[32:33], v[36:37], 0, s[2:3]
	v_mul_f32_e32 v2, v4, v2
	v_mul_f32_e32 v3, v5, v3
	v_lshlrev_b32_e32 v4, 16, v7
	v_and_b32_e32 v5, 0xffff0000, v7
	v_mul_f32_e32 v6, v14, v34
	v_mul_f32_e32 v7, v15, v34
	v_cvt_pk_bf16_f32 v2, v2, v3
	v_mul_f32_e32 v4, v6, v4
	v_mul_f32_e32 v5, v7, v5
	s_nop 0
	v_permlane32_swap_b32_e32 v0, v2
	v_cvt_pk_bf16_f32 v3, v4, v5
	s_nop 1
	v_permlane32_swap_b32_e32 v1, v3

.LBB0_898:
	s_add_i32 s9, s3, -1
	s_min_u32 s9, s9, s2
	s_lshl_b32 s9, s9, 6
	s_waitcnt vmcnt(1)
	ds_write_b128 v142, v[112:115] offset:16384
	s_waitcnt vmcnt(0)
	ds_write_b128 v142, v[116:119] offset:24576
	v_mad_u64_u32 v[64:65], s[18:19], s9, v237, v[132:133]
	global_load_dwordx4 v[120:123], v[64:65], off offset:2048
	global_load_dwordx4 v[124:127], v[136:137], off offset:-128
	ds_read_b128 v[64:67], v144 offset:8192
	ds_read_b128 v[68:71], v144 offset:12288
	ds_read_b128 v[72:75], v141 offset:8192
	ds_read_b128 v[76:79], v141 offset:12288
	v_exp_f32_e32 v151, v48
	v_exp_f32_e32 v152, v49
	s_waitcnt lgkmcnt(3)
	v_mfma_f32_32x32x16_bf16 v[16:31], v[64:67], v[80:83], v[16:31]
	v_exp_f32_e32 v153, v50
	v_add_f32_e32 v112, 0, v151
	v_add_f32_e32 v113, 0, v152
	v_exp_f32_e32 v154, v51
	ds_read_b128 v[48:51], v140 offset:8192
	ds_read_b128 v[64:67], v140 offset:12288
	v_exp_f32_e32 v155, v52
	s_waitcnt lgkmcnt(4)
	v_mfma_f32_32x32x16_bf16 v[0:15], v[68:71], v[80:83], v[0:15]
	v_exp_f32_e32 v156, v53
	v_exp_f32_e32 v159, v54
	v_exp_f32_e32 v160, v55
	v_add_f32_e32 v114, 0, v153
	v_add_f32_e32 v115, 0, v154
	v_exp_f32_e32 v162, v57
	s_waitcnt lgkmcnt(3)
	v_mfma_f32_32x32x16_bf16 v[16:31], v[72:75], v[84:87], v[16:31]
	ds_read_b128 v[68:71], v139 offset:8192
	ds_read_b128 v[80:83], v139 offset:12288
	v_add_f32_e32 v157, v155, v112
	v_add_f32_e32 v158, v156, v113
	v_add_u32_e32 v164, v143, v145
	ds_read_b128 v[52:55], v164
	ds_read_b128 v[72:75], v164 offset:4096
	v_add_f32_e32 v161, v159, v114
	s_waitcnt lgkmcnt(6)
	v_mfma_f32_32x32x16_bf16 v[0:15], v[76:79], v[84:87], v[0:15]
	v_exp_f32_e32 v77, v56
	v_add_f32_e32 v76, v160, v115
	v_exp_f32_e32 v62, v62
	v_add_u32_e32 v165, v143, v146
	ds_read_b128 v[112:115], v165
	ds_read_b128 v[116:119], v165 offset:4096
	v_cvt_pk_bf16_f32 v56, v151, v152
	s_waitcnt lgkmcnt(7)
	v_mfma_f32_32x32x16_bf16 v[16:31], v[48:51], v[88:91], v[16:31]
	v_exp_f32_e32 v49, v58
	v_exp_f32_e32 v50, v59
	v_add_f32_e32 v48, v77, v157
	v_add_f32_e32 v51, v162, v158
	v_add_f32_e32 v78, v49, v161
	v_add_f32_e32 v76, v50, v76
	s_waitcnt lgkmcnt(6)
	v_mfma_f32_32x32x16_bf16 v[0:15], v[64:67], v[88:91], v[0:15]
	v_exp_f32_e32 v60, v60
	v_add_f32_e32 v151, v62, v78
	v_exp_f32_e32 v61, v61
	v_exp_f32_e32 v63, v63
	v_cvt_pk_bf16_f32 v59, v159, v160
	v_exp_f32_e32 v160, v33
	s_waitcnt lgkmcnt(5)
	v_mfma_f32_32x32x16_bf16 v[16:31], v[68:71], v[92:95], v[16:31]
	v_cvt_pk_bf16_f32 v57, v153, v154
	v_cvt_pk_bf16_f32 v58, v155, v156
	v_add_f32_e32 v48, v60, v48
	v_add_f32_e32 v51, v61, v51
	v_cvt_pk_bf16_f32 v49, v49, v50
	s_waitcnt lgkmcnt(4)
	v_mfma_f32_32x32x16_bf16 v[0:15], v[80:83], v[92:95], v[0:15]
	v_exp_f32_e32 v95, v32
	v_add_f32_e32 v32, v63, v76
	v_add_f32_e32 v163, v160, v51
	v_add_f32_e32 v161, v95, v48
	v_cvt_pk_bf16_f32 v48, v77, v162
	v_cvt_pk_bf16_f32 v51, v62, v63
	s_waitcnt lgkmcnt(3)
	v_mfma_f32_32x32x16_bf16 v[78:93], v[52:55], v[96:99], 0
	v_cvt_pk_bf16_f32 v50, v60, v61
	v_exp_f32_e32 v60, v34
	v_exp_f32_e32 v61, v35
	v_exp_f32_e32 v36, v36
	v_exp_f32_e32 v37, v37
	v_exp_f32_e32 v38, v38
	v_exp_f32_e32 v39, v39
	s_waitcnt lgkmcnt(2)
	v_mfma_f32_32x32x16_bf16 v[62:77], v[72:75], v[96:99], 0
	v_add_u32_e32 v166, v143, v147
	ds_read_b128 v[52:55], v166
	ds_read_b128 v[152:155], v166 offset:4096
	v_add_f32_e32 v151, v60, v151
	v_add_f32_e32 v162, v61, v32
	s_waitcnt lgkmcnt(3)
	v_mfma_f32_32x32x16_bf16 v[78:93], v[112:115], v[100:103], v[78:93]
	v_add_u32_e32 v94, v143, v149
	v_add_f32_e32 v112, v36, v161
	v_add_f32_e32 v113, v37, v163
	v_add_f32_e32 v114, v38, v151
	v_exp_f32_e32 v115, v40
	v_add_f32_e32 v40, v39, v162
	ds_read_b128 v[32:35], v94
	ds_read_b128 v[156:159], v94 offset:4096
	s_waitcnt lgkmcnt(4)
	v_mfma_f32_32x32x16_bf16 v[62:77], v[116:119], v[100:103], v[62:77]
	v_exp_f32_e32 v116, v41
	v_add_f32_e32 v41, v115, v112
	s_min_u32 s9, s3, s2
	s_lshl_b32 s9, s9, 6
	v_add_f32_e32 v112, v116, v113
	s_waitcnt lgkmcnt(3)
	v_mfma_f32_32x32x16_bf16 v[78:93], v[52:55], v[104:107], v[78:93]
	v_cvt_pk_bf16_f32 v54, v36, v37
	v_exp_f32_e32 v37, v42
	v_cvt_pk_bf16_f32 v55, v38, v39
	v_exp_f32_e32 v38, v43
	v_exp_f32_e32 v39, v44
	v_exp_f32_e32 v44, v45
	v_exp_f32_e32 v45, v46
	v_exp_f32_e32 v46, v47
	v_cvt_pk_bf16_f32 v52, v95, v160
	v_cvt_pk_bf16_f32 v53, v60, v61
	v_add_f32_e32 v36, v37, v114
	v_add_f32_e32 v43, v38, v40
	v_add_f32_e32 v40, v39, v41
	v_add_f32_e32 v42, v44, v112
	v_add_f32_e32 v41, v45, v36
	v_add_f32_e32 v43, v46, v43
	v_cvt_pk_bf16_f32 v36, v115, v116
	v_cvt_pk_bf16_f32 v37, v37, v38
	v_cvt_pk_bf16_f32 v38, v39, v44
	v_cvt_pk_bf16_f32 v39, v45, v46
	s_waitcnt lgkmcnt(1)
	v_mfma_f32_32x32x16_bf16 v[78:93], v[32:35], v[108:111], v[78:93]
	s_waitcnt lgkmcnt(0)
	s_barrier
	v_mad_u64_u32 v[32:33], s[18:19], s9, v237, v[132:133]
	global_load_dwordx4 v[112:115], v[32:33], off offset:2048
	global_load_dwordx4 v[116:119], v[136:137], off
	v_add_f32_e64 v32, v40, v42
	v_add_f32_e64 v33, v41, v43
	s_waitcnt vmcnt(3)
	ds_write_b128 v142, v[120:123]
	s_waitcnt vmcnt(2)
	ds_write_b128 v142, v[124:127] offset:8192
	v_mfma_f32_32x32x16_bf16 v[62:77], v[152:155], v[104:107], v[62:77]
	v_add_f32_e32 v32, v32, v33
	v_add_f32_e32 v150, v150, v32
	s_waitcnt lgkmcnt(2)
	v_mfma_f32_32x32x16_bf16 v[62:77], v[156:159], v[108:111], v[62:77]
	ds_read_b128 v[32:35], v144 offset:24576
	ds_read_b128 v[40:43], v144 offset:28672
	ds_read_b128 v[44:47], v141 offset:24576
	ds_read_b128 v[120:123], v141 offset:28672
	v_exp_f32_e32 v60, v78
	s_waitcnt lgkmcnt(3)
	v_mfma_f32_32x32x16_bf16 v[16:31], v[32:35], v[56:59], v[16:31]
	v_exp_f32_e32 v61, v79
	v_exp_f32_e32 v95, v80
	v_add_f32_e32 v78, 0, v60
	v_exp_f32_e32 v81, v81
	v_add_f32_e32 v79, 0, v61
	ds_read_b128 v[152:155], v140 offset:24576
	ds_read_b128 v[156:159], v140 offset:28672
	s_waitcnt lgkmcnt(4)
	v_mfma_f32_32x32x16_bf16 v[0:15], v[40:43], v[56:59], v[0:15]
	v_exp_f32_e32 v82, v82
	v_exp_f32_e32 v83, v83
	v_add_f32_e32 v80, 0, v95
	v_add_f32_e32 v124, 0, v81
	v_add_f32_e32 v78, v82, v78
	v_add_f32_e32 v79, v83, v79
	s_waitcnt lgkmcnt(2)
	v_mfma_f32_32x32x16_bf16 v[0:15], v[120:123], v[48:51], v[0:15]
	ds_read_b128 v[56:59], v139 offset:24576
	ds_read_b128 v[160:163], v139 offset:28672
	ds_read_b128 v[40:43], v164 offset:16384
	ds_read_b128 v[32:35], v164 offset:20480
	v_cvt_pk_bf16_f32 v82, v82, v83
	v_exp_f32_e32 v151, v62
	v_exp_f32_e32 v64, v64
	v_exp_f32_e32 v65, v65
	v_mfma_f32_32x32x16_bf16 v[16:31], v[44:47], v[48:51], v[16:31]
	v_exp_f32_e32 v44, v84
	v_exp_f32_e32 v45, v85
	v_exp_f32_e32 v84, v86
	v_exp_f32_e32 v85, v87
	v_add_f32_e32 v46, v44, v80
	v_add_f32_e32 v47, v45, v124
	v_add_f32_e32 v48, v84, v78
	s_waitcnt lgkmcnt(4)
	v_mfma_f32_32x32x16_bf16 v[0:15], v[156:159], v[52:55], v[0:15]
	v_add_f32_e32 v49, v85, v79
	v_exp_f32_e32 v78, v88
	v_exp_f32_e32 v79, v89
	v_exp_f32_e32 v87, v92
	v_cvt_pk_bf16_f32 v83, v44, v45
	v_exp_f32_e32 v44, v90
	v_mfma_f32_32x32x16_bf16 v[16:31], v[152:155], v[52:55], v[16:31]
	v_exp_f32_e32 v45, v91
	v_exp_f32_e32 v92, v93
	v_add_f32_e32 v46, v78, v46
	v_add_f32_e32 v47, v79, v47
	ds_read_b128 v[124:127], v165 offset:16384
	ds_read_b128 v[120:123], v165 offset:20480
	s_waitcnt lgkmcnt(4)
	v_mfma_f32_32x32x16_bf16 v[0:15], v[160:163], v[36:39], v[0:15]
	v_exp_f32_e32 v160, v63
	v_cvt_pk_bf16_f32 v80, v60, v61
	v_cvt_pk_bf16_f32 v81, v95, v81
	v_add_f32_e32 v48, v44, v48
	v_add_f32_e32 v49, v45, v49
	v_add_f32_e32 v46, v87, v46
	v_add_f32_e32 v47, v92, v47
	v_mfma_f32_32x32x16_bf16 v[16:31], v[56:59], v[36:39], v[16:31]
	v_add_f32_e32 v161, v151, v48
	v_add_f32_e32 v162, v160, v49
	v_cvt_pk_bf16_f32 v84, v84, v85
	v_cvt_pk_bf16_f32 v85, v78, v79
	v_cvt_pk_bf16_f32 v86, v44, v45
	v_add_f32_e32 v78, v64, v46
	v_add_f32_e32 v79, v65, v47
	s_waitcnt lgkmcnt(3)
	v_mfma_f32_32x32x16_bf16 v[48:63], v[40:43], v[96:99], 0
	ds_read_b128 v[88:91], v166 offset:16384
	ds_read_b128 v[152:155], v166 offset:20480
	v_exp_f32_e32 v66, v66
	v_exp_f32_e32 v67, v67
	v_exp_f32_e32 v68, v68
	v_exp_f32_e32 v69, v69
	v_cvt_pk_bf16_f32 v87, v87, v92
	s_waitcnt lgkmcnt(4)
	v_mfma_f32_32x32x16_bf16 v[32:47], v[32:35], v[96:99], 0
	ds_read_b128 v[156:159], v94 offset:16384
	ds_read_b128 v[92:95], v94 offset:20480
	v_add_f32_e32 v161, v66, v161
	v_add_f32_e32 v162, v67, v162
	v_add_f32_e32 v78, v68, v78
	v_add_f32_e32 v79, v69, v79
	s_waitcnt lgkmcnt(5)
	v_mfma_f32_32x32x16_bf16 v[48:63], v[124:127], v[100:103], v[48:63]
	v_exp_f32_e32 v70, v70
	v_exp_f32_e32 v71, v71
	s_add_i32 s9, s3, 2
	s_add_i32 s3, s3, -2
	v_lshl_add_u64 v[136:137], v[136:137], 0, s[22:23]
	s_waitcnt lgkmcnt(4)
	v_mfma_f32_32x32x16_bf16 v[32:47], v[120:123], v[100:103], v[32:47]
	v_add_f32_e32 v120, v70, v161
	v_add_f32_e32 v121, v71, v162
	s_cmp_lt_u32 s3, s2
	s_mov_b32 s3, s9
	s_waitcnt lgkmcnt(3)
	v_mfma_f32_32x32x16_bf16 v[48:63], v[88:91], v[104:107], v[48:63]
	v_cvt_pk_bf16_f32 v91, v68, v69
	v_exp_f32_e32 v68, v72
	v_exp_f32_e32 v69, v73
	v_exp_f32_e32 v72, v74
	v_exp_f32_e32 v73, v75
	v_exp_f32_e32 v74, v76
	v_exp_f32_e32 v75, v77
	s_waitcnt lgkmcnt(2)
	v_mfma_f32_32x32x16_bf16 v[32:47], v[152:155], v[104:107], v[32:47]
	v_cvt_pk_bf16_f32 v88, v151, v160
	v_cvt_pk_bf16_f32 v89, v64, v65
	v_cvt_pk_bf16_f32 v90, v66, v67
	v_add_f32_e32 v65, v68, v78
	v_add_f32_e32 v67, v69, v79
	s_waitcnt lgkmcnt(1)
	v_mfma_f32_32x32x16_bf16 v[48:63], v[156:159], v[108:111], v[48:63]
	v_add_f32_e32 v64, v72, v120
	v_add_f32_e32 v66, v73, v121
	v_add_f32_e32 v65, v74, v65
	v_add_f32_e32 v67, v75, v67
	s_waitcnt lgkmcnt(0)
	v_mfma_f32_32x32x16_bf16 v[32:47], v[92:95], v[108:111], v[32:47]
	v_cvt_pk_bf16_f32 v92, v70, v71
	v_cvt_pk_bf16_f32 v93, v68, v69
	v_cvt_pk_bf16_f32 v94, v72, v73
	v_cvt_pk_bf16_f32 v95, v74, v75
	v_add_f32_e64 v64, v64, v66
	v_add_f32_e64 v65, v65, v67
	s_waitcnt lgkmcnt(0)
	s_barrier
	v_add_f32_e32 v64, v64, v65
	v_add_f32_e32 v150, v150, v64
	s_cbranch_scc1 .LBB0_898
	v_ashrrev_i32_e32 v64, 1, v129
	v_and_or_b32 v132, v64, s88, v148
	v_mov_b64_e32 v[64:65], s[12:13]
	v_mad_i64_i32 v[64:65], s[2:3], v132, s33, v[64:65]
	v_lshlrev_b32_e32 v176, 4, v138
	s_waitcnt vmcnt(1)
	ds_write_b128 v142, v[112:115] offset:16384
	s_waitcnt vmcnt(0)
	ds_write_b128 v142, v[116:119] offset:24576
	v_lshl_add_u64 v[64:65], v[64:65], 0, v[176:177]
	global_load_dwordx4 v[124:127], v[64:65], off offset:2560
	global_load_dwordx4 v[120:123], v[64:65], off offset:2592
	global_load_dwordx4 v[116:119], v[64:65], off offset:2624
	global_load_dwordx4 v[112:115], v[64:65], off offset:2656
	v_mov_b64_e32 v[64:65], s[14:15]
	v_mad_i64_i32 v[64:65], s[2:3], v132, s33, v[64:65]
	v_and_b32_e32 v66, 16, v131
	v_mov_b32_e32 v67, v177
	v_lshl_add_u64 v[64:65], v[64:65], 0, v[66:67]
	global_load_dwordx4 v[96:99], v[64:65], off offset:1024
	global_load_dwordx4 v[100:103], v[64:65], off offset:1056
	global_load_dwordx4 v[104:107], v[64:65], off offset:1088
	global_load_dwordx4 v[108:111], v[64:65], off offset:1120
	v_lshl_add_u64 v[64:65], s[34:35], 0, v[134:135]
	v_lshlrev_b32_e32 v76, 1, v130
	v_mov_b32_e32 v77, v177
	v_lshl_add_u64 v[72:73], v[64:65], 0, v[76:77]
	s_mov_b32 s2, 0x48000
	v_add_co_u32_e32 v68, vcc, s2, v72
	s_mov_b32 s2, 0x90000
	s_nop 0
	v_addc_co_u32_e32 v69, vcc, 0, v73, vcc
	global_load_dwordx4 v[64:67], v[72:73], off offset:2048
	v_ashrrev_i32_e32 v133, 31, v132
	global_load_dwordx4 v[68:71], v[68:69], off offset:2048
	v_add_co_u32_e32 v72, vcc, s2, v72
	v_mad_i64_i32 v[78:79], s[2:3], s8, v128, 0
	v_lshl_add_u64 v[78:79], v[78:79], 1, s[10:11]
	v_addc_co_u32_e32 v73, vcc, 0, v73, vcc
	v_lshl_add_u64 v[76:77], v[78:79], 0, v[76:77]
	global_load_dwordx4 v[72:75], v[72:73], off offset:2048
	s_nop 0
	global_load_dwordx4 v[76:79], v[76:77], off
	ds_read_b128 v[128:131], v144 offset:8192
	ds_read_b128 v[134:137], v144 offset:12288
	ds_read_b128 v[146:149], v141 offset:8192
	ds_read_b128 v[152:155], v141 offset:12288
	v_exp_f32_e32 v138, v48
	v_exp_f32_e32 v142, v49
	s_waitcnt lgkmcnt(3)
	v_mfma_f32_32x32x16_bf16 v[16:31], v[128:131], v[80:83], v[16:31]
	v_exp_f32_e32 v151, v50
	v_add_f32_e32 v143, 0, v138
	v_add_f32_e32 v145, 0, v142
	v_exp_f32_e32 v156, v51
	ds_read_b128 v[48:51], v140 offset:8192
	ds_read_b128 v[128:131], v140 offset:12288
	v_exp_f32_e32 v52, v52
	s_waitcnt lgkmcnt(4)
	v_mfma_f32_32x32x16_bf16 v[0:15], v[134:137], v[80:83], v[0:15]
	v_exp_f32_e32 v53, v53
	v_exp_f32_e32 v54, v54
	v_exp_f32_e32 v55, v55
	v_add_f32_e32 v157, 0, v151
	v_add_f32_e32 v158, 0, v156
	v_add_f32_e32 v143, v52, v143
	s_waitcnt lgkmcnt(3)
	v_mfma_f32_32x32x16_bf16 v[16:31], v[146:149], v[84:87], v[16:31]
	v_add_f32_e32 v145, v53, v145
	v_add_f32_e32 v146, v54, v157
	ds_read_b128 v[80:83], v139 offset:8192
	ds_read_b128 v[134:137], v139 offset:12288
	v_exp_f32_e32 v56, v56
	v_exp_f32_e32 v57, v57
	v_exp_f32_e32 v58, v58
	s_waitcnt lgkmcnt(4)
	v_mfma_f32_32x32x16_bf16 v[0:15], v[152:155], v[84:87], v[0:15]
	v_add_f32_e32 v84, v55, v158
	v_exp_f32_e32 v59, v59
	v_exp_f32_e32 v60, v60
	v_exp_f32_e32 v32, v32
	v_exp_f32_e32 v33, v33
	v_exp_f32_e32 v34, v34
	s_waitcnt lgkmcnt(3)
	v_mfma_f32_32x32x16_bf16 v[16:31], v[48:51], v[88:91], v[16:31]
	v_cvt_pk_bf16_f32 v51, v54, v55
	v_exp_f32_e32 v54, v61
	v_exp_f32_e32 v55, v62
	v_exp_f32_e32 v61, v63
	v_exp_f32_e32 v35, v35
	v_add_f32_e32 v85, v56, v143
	v_add_f32_e32 v86, v57, v145
	v_add_f32_e32 v87, v58, v146
	v_add_f32_e32 v84, v59, v84
	v_cvt_pk_bf16_f32 v48, v138, v142
	v_cvt_pk_bf16_f32 v49, v151, v156
	v_cvt_pk_bf16_f32 v50, v52, v53
	v_add_f32_e32 v52, v60, v85
	v_add_f32_e32 v53, v54, v86
	v_add_f32_e32 v62, v55, v87
	v_add_f32_e32 v63, v61, v84
	v_exp_f32_e32 v36, v36
	v_exp_f32_e32 v37, v37
	v_exp_f32_e32 v38, v38
	v_exp_f32_e32 v39, v39
	s_waitcnt lgkmcnt(1)
	v_mfma_f32_32x32x16_bf16 v[16:31], v[80:83], v[92:95], v[16:31]
	v_add_f32_e32 v80, v32, v52
	v_add_f32_e32 v81, v33, v53
	v_cvt_pk_bf16_f32 v52, v56, v57
	v_cvt_pk_bf16_f32 v53, v58, v59
	v_cvt_pk_bf16_f32 v54, v60, v54
	v_cvt_pk_bf16_f32 v55, v55, v61
	v_add_f32_e32 v56, v34, v62
	v_add_f32_e32 v57, v35, v63
	v_exp_f32_e32 v40, v40
	v_add_f32_e32 v58, v36, v80
	v_add_f32_e32 v59, v37, v81
	v_add_f32_e32 v56, v38, v56
	v_exp_f32_e32 v41, v41
	v_add_f32_e32 v57, v39, v57
	v_mfma_f32_32x32x16_bf16 v[0:15], v[128:131], v[88:91], v[0:15]
	v_cvt_pk_bf16_f32 v32, v32, v33
	v_cvt_pk_bf16_f32 v33, v34, v35
	v_cvt_pk_bf16_f32 v34, v36, v37
	v_exp_f32_e32 v37, v42
	v_cvt_pk_bf16_f32 v35, v38, v39
	v_exp_f32_e32 v38, v43
	v_exp_f32_e32 v39, v44
	v_exp_f32_e32 v43, v45
	v_exp_f32_e32 v44, v46
	v_exp_f32_e32 v45, v47
	v_add_f32_e32 v58, v40, v58
	v_add_f32_e32 v59, v41, v59
	v_add_f32_e32 v36, v37, v56
	v_add_f32_e32 v42, v38, v57
	v_add_f32_e32 v56, v39, v58
	v_add_f32_e32 v58, v43, v59
	s_waitcnt lgkmcnt(0)
	v_mfma_f32_32x32x16_bf16 v[0:15], v[134:137], v[92:95], v[0:15]
	v_add_f32_e32 v57, v44, v36
	v_add_f32_e32 v59, v45, v42
	v_cvt_pk_bf16_f32 v36, v40, v41
	v_cvt_pk_bf16_f32 v37, v37, v38
	v_cvt_pk_bf16_f32 v38, v39, v43
	v_cvt_pk_bf16_f32 v39, v44, v45
	s_waitcnt lgkmcnt(0)
	s_barrier
	ds_read_b128 v[40:43], v144 offset:24576
	ds_read_b128 v[44:47], v144 offset:28672
	s_waitcnt lgkmcnt(1)
	v_mfma_f32_32x32x16_bf16 v[16:31], v[40:43], v[48:51], v[16:31]
	s_waitcnt lgkmcnt(0)
	v_mfma_f32_32x32x16_bf16 v[0:15], v[44:47], v[48:51], v[0:15]
	ds_read_b128 v[40:43], v141 offset:24576
	ds_read_b128 v[44:47], v141 offset:28672
	s_waitcnt lgkmcnt(1)
	v_mfma_f32_32x32x16_bf16 v[16:31], v[40:43], v[52:55], v[16:31]
	s_waitcnt lgkmcnt(0)
	v_mfma_f32_32x32x16_bf16 v[0:15], v[44:47], v[52:55], v[0:15]
	ds_read_b128 v[40:43], v140 offset:24576
	ds_read_b128 v[44:47], v140 offset:28672
	s_waitcnt lgkmcnt(1)
	v_mfma_f32_32x32x16_bf16 v[16:31], v[40:43], v[32:35], v[16:31]
	s_waitcnt lgkmcnt(0)
	v_mfma_f32_32x32x16_bf16 v[0:15], v[44:47], v[32:35], v[0:15]
	ds_read_b128 v[32:35], v139 offset:24576
	ds_read_b128 v[40:43], v139 offset:28672
	s_waitcnt lgkmcnt(1)
	v_mfma_f32_32x32x16_bf16 v[16:31], v[32:35], v[36:39], v[16:31]
	v_add_f32_e64 v32, v56, v58
	v_add_f32_e64 v33, v57, v59
	v_add_f32_e32 v32, v32, v33
	v_add_f32_e32 v32, v150, v32
	v_mov_b32_e32 v33, v32
	s_nop 1
	v_permlane32_swap_b32_e32 v32, v33
	v_add_f32_e32 v32, v32, v33
	v_div_scale_f32 v33, s[2:3], v32, v32, 1.0
	v_rcp_f32_e32 v34, v33
	s_waitcnt lgkmcnt(0)
	v_mfma_f32_32x32x16_bf16 v[0:15], v[40:43], v[36:39], v[0:15]
	s_waitcnt vmcnt(11)
	v_mov_b32_e32 v40, v127
	s_nop 1
	v_permlane32_swap_b32_e32 v125, v40
	v_fma_f32 v35, -v33, v34, 1.0
	v_fmac_f32_e32 v34, v35, v34
	v_div_scale_f32 v35, vcc, 1.0, v32, 1.0
	v_mul_f32_e32 v36, v35, v34
	v_fma_f32 v37, -v33, v36, v35
	v_fmac_f32_e32 v36, v37, v34
	v_fma_f32 v33, -v33, v36, v35
	v_div_fmas_f32 v33, v33, v34, v36
	v_mov_b32_e32 v35, v126
	v_div_fixup_f32 v34, v33, v32, 1.0
	s_nop 0
	v_permlane32_swap_b32_e32 v124, v35
	v_lshlrev_b32_e32 v38, 16, v124
	v_and_b32_e32 v39, 0xffff0000, v124
	v_mul_f32_e32 v16, v16, v34
	v_mul_f32_e32 v17, v17, v34
	v_mul_f32_e32 v18, v18, v34
	v_mul_f32_e32 v19, v19, v34
	v_mul_f32_e32 v16, v16, v38
	v_mul_f32_e32 v17, v17, v39
	v_lshlrev_b32_e32 v38, 16, v125
	v_and_b32_e32 v39, 0xffff0000, v125
	v_mul_f32_e32 v18, v18, v38
	v_mul_f32_e32 v19, v19, v39
	v_cvt_pk_bf16_f32 v16, v16, v17
	v_cvt_pk_bf16_f32 v17, v18, v19
	v_lshlrev_b32_e32 v18, 16, v35
	v_and_b32_e32 v19, 0xffff0000, v35
	v_mul_f32_e32 v20, v20, v34
	v_mul_f32_e32 v21, v21, v34
	v_mul_f32_e32 v22, v22, v34
	v_mul_f32_e32 v23, v23, v34
	v_mul_f32_e32 v18, v20, v18
	v_mul_f32_e32 v19, v21, v19
	v_lshlrev_b32_e32 v20, 16, v40
	v_and_b32_e32 v21, 0xffff0000, v40
	v_lshlrev_b64 v[32:33], 11, v[132:133]
	v_mul_f32_e32 v20, v22, v20
	v_mul_f32_e32 v21, v23, v21
	v_lshl_add_u64 v[32:33], s[6:7], 0, v[32:33]
	v_cvt_pk_bf16_f32 v18, v18, v19
	v_cvt_pk_bf16_f32 v19, v20, v21
	s_waitcnt vmcnt(10)
	v_mov_b32_e32 v22, v122
	v_lshl_add_u64 v[36:37], v[32:33], 0, v[176:177]
	v_permlane32_swap_b32_e32 v16, v18
	v_permlane32_swap_b32_e32 v17, v19
	v_permlane32_swap_b32_e32 v120, v22
	v_mov_b32_e32 v23, v123
	global_store_dwordx4 v[36:37], v[16:19], off offset:512
	s_nop 0
	v_permlane32_swap_b32_e32 v121, v23
	v_lshlrev_b32_e32 v16, 16, v120
	v_and_b32_e32 v17, 0xffff0000, v120
	v_mul_f32_e32 v18, v24, v34
	v_mul_f32_e32 v19, v25, v34
	v_mul_f32_e32 v20, v26, v34
	v_mul_f32_e32 v21, v27, v34
	v_mul_f32_e32 v16, v18, v16
	v_mul_f32_e32 v17, v19, v17
	v_lshlrev_b32_e32 v18, 16, v121
	v_and_b32_e32 v19, 0xffff0000, v121
	v_mul_f32_e32 v18, v20, v18
	v_mul_f32_e32 v19, v21, v19
	v_cvt_pk_bf16_f32 v16, v16, v17
	v_cvt_pk_bf16_f32 v17, v18, v19
	v_lshlrev_b32_e32 v18, 16, v22
	v_and_b32_e32 v19, 0xffff0000, v22
	v_mul_f32_e32 v20, v28, v34
	v_mul_f32_e32 v21, v29, v34
	v_mul_f32_e32 v0, v0, v34
	v_mul_f32_e32 v1, v1, v34
	v_mul_f32_e32 v18, v20, v18
	v_mul_f32_e32 v19, v21, v19
	v_lshlrev_b32_e32 v20, 16, v23
	v_and_b32_e32 v21, 0xffff0000, v23
	v_mul_f32_e32 v22, v30, v34
	v_mul_f32_e32 v23, v31, v34
	v_cvt_pk_bf16_f32 v18, v18, v19
	v_mul_f32_e32 v20, v22, v20
	v_mul_f32_e32 v21, v23, v21
	s_nop 0
	v_permlane32_swap_b32_e32 v16, v18
	v_cvt_pk_bf16_f32 v19, v20, v21
	s_nop 1
	v_permlane32_swap_b32_e32 v17, v19
	global_store_dwordx4 v[36:37], v[16:19], off offset:544
	v_mul_f32_e32 v2, v2, v34
	v_mul_f32_e32 v3, v3, v34
	v_mul_f32_e32 v4, v4, v34
	v_mul_f32_e32 v5, v5, v34
	s_waitcnt vmcnt(11)
	v_mov_b32_e32 v18, v118
	s_nop 1
	v_permlane32_swap_b32_e32 v116, v18
	v_mov_b32_e32 v19, v119
	s_nop 1
	v_permlane32_swap_b32_e32 v117, v19
	v_lshlrev_b32_e32 v16, 16, v116
	v_and_b32_e32 v17, 0xffff0000, v116
	v_mul_f32_e32 v0, v0, v16
	v_mul_f32_e32 v1, v1, v17
	v_lshlrev_b32_e32 v16, 16, v117
	v_and_b32_e32 v17, 0xffff0000, v117
	v_mul_f32_e32 v2, v2, v16
	v_mul_f32_e32 v3, v3, v17
	v_cvt_pk_bf16_f32 v0, v0, v1
	v_cvt_pk_bf16_f32 v1, v2, v3
	v_lshlrev_b32_e32 v2, 16, v18
	v_and_b32_e32 v3, 0xffff0000, v18
	v_mul_f32_e32 v2, v4, v2
	v_mul_f32_e32 v3, v5, v3
	v_lshlrev_b32_e32 v4, 16, v19
	v_and_b32_e32 v5, 0xffff0000, v19
	v_mul_f32_e32 v6, v6, v34
	v_mul_f32_e32 v7, v7, v34
	v_cvt_pk_bf16_f32 v2, v2, v3
	v_mul_f32_e32 v4, v6, v4
	v_mul_f32_e32 v5, v7, v5
	s_waitcnt vmcnt(10)
	v_mov_b32_e32 v6, v114
	v_cvt_pk_bf16_f32 v3, v4, v5
	v_permlane32_swap_b32_e32 v0, v2
	s_nop 0
	v_permlane32_swap_b32_e32 v1, v3
	v_permlane32_swap_b32_e32 v112, v6
	v_mov_b32_e32 v7, v115
	global_store_dwordx4 v[36:37], v[0:3], off offset:576
	s_nop 0
	v_permlane32_swap_b32_e32 v113, v7
	v_lshlrev_b32_e32 v0, 16, v112
	v_and_b32_e32 v1, 0xffff0000, v112
	v_mul_f32_e32 v2, v8, v34
	v_mul_f32_e32 v3, v9, v34
	v_mul_f32_e32 v4, v10, v34
	v_mul_f32_e32 v5, v11, v34
	v_mul_f32_e32 v0, v2, v0
	v_mul_f32_e32 v1, v3, v1
	v_lshlrev_b32_e32 v2, 16, v113
	v_and_b32_e32 v3, 0xffff0000, v113
	v_mul_f32_e32 v2, v4, v2
	v_mul_f32_e32 v3, v5, v3
	v_cvt_pk_bf16_f32 v0, v0, v1
	v_cvt_pk_bf16_f32 v1, v2, v3
	v_lshlrev_b32_e32 v2, 16, v6
	v_and_b32_e32 v3, 0xffff0000, v6
	v_mul_f32_e32 v4, v12, v34
	v_mul_f32_e32 v5, v13, v34
	s_mov_b64 s[2:3], 0x200
	v_mul_f32_e32 v2, v4, v2
	v_mul_f32_e32 v3, v5, v3
	v_lshlrev_b32_e32 v4, 16, v7
	v_and_b32_e32 v5, 0xffff0000, v7
	v_mul_f32_e32 v6, v14, v34
	v_mul_f32_e32 v7, v15, v34
	v_cvt_pk_bf16_f32 v2, v2, v3
	v_mul_f32_e32 v4, v6, v4
	v_mul_f32_e32 v5, v7, v5
	v_lshl_add_u64 v[32:33], v[36:37], 0, s[2:3]
	v_cvt_pk_bf16_f32 v3, v4, v5
	v_permlane32_swap_b32_e32 v0, v2
	s_nop 0
	v_permlane32_swap_b32_e32 v1, v3
	s_branch .LBB0_876

.LBB0_902:
	s_and_b32 s8, s14, 3
	s_mul_i32 s6, s0, 0x120000
	s_mul_hi_i32 s3, s0, 0x120000
	s_add_u32 s6, s92, s6
	s_addc_u32 s3, s93, s3
	s_lshl_b32 s15, s8, 7
	s_add_u32 s18, s6, s15
	s_addc_u32 s19, s3, 0
	s_ashr_i32 s3, s2, 31
	s_lshl_b64 s[6:7], s[2:3], 17
	s_add_u32 s3, s10, s6
	s_addc_u32 s7, s11, s7
	s_add_u32 s6, s3, s15
	s_addc_u32 s7, s7, 0
	s_lshl_b32 s2, s2, 2
	s_or_b32 s2, s2, s8
	s_ashr_i32 s3, s2, 31
	s_lshl_b64 s[2:3], s[2:3], 15
	s_add_u32 s8, s12, s2
	s_addc_u32 s9, s13, s3
	s_lshl_b64 s[0:1], s[0:1], 19
	s_add_u32 s0, s94, s0
	s_addc_u32 s1, s95, s1
	s_add_u32 s0, s0, s15
	v_mov_b32_e32 v34, v250
	s_addc_u32 s1, s1, 0
	s_add_u32 s2, s18, 0x1000
	v_ashrrev_i32_e32 v0, 1, v34
	v_bfe_u32 v58, v34, 5, 1
	s_waitcnt vmcnt(0)
	v_bfi_b32 v98, s88, v0, v34
	v_mov_b64_e32 v[0:1], s[18:19]
	s_addc_u32 s3, s19, 0
	v_mad_i64_i32 v[0:1], s[18:19], v98, s33, v[0:1]
	v_lshlrev_b32_e32 v176, 4, v58
	v_lshl_add_u64 v[0:1], v[0:1], 0, v[176:177]
	global_load_dwordx4 v[94:97], v[0:1], off offset:3584
	global_load_dwordx4 v[90:93], v[0:1], off offset:3616
	global_load_dwordx4 v[86:89], v[0:1], off offset:3648
	global_load_dwordx4 v[82:85], v[0:1], off offset:3680
	v_ashrrev_i32_e32 v32, 3, v34
	v_lshlrev_b32_e32 v0, 4, v34
	v_and_b32_e32 v4, 0x70, v0
	v_mov_b32_e32 v5, v177
	v_ashrrev_i32_e32 v33, 31, v32
	v_xor_b32_e32 v37, v0, v34
	v_lshl_add_u64 v[0:1], s[6:7], 0, v[4:5]
	v_lshlrev_b64 v[2:3], 9, v[32:33]
	v_lshl_add_u64 v[24:25], v[0:1], 0, v[2:3]
	s_mov_b32 s6, 0x8000
	v_add_co_u32_e32 v8, vcc, s6, v24
	s_mov_b32 s6, 0x10000
	s_nop 0
	v_addc_co_u32_e32 v9, vcc, 0, v25, vcc
	v_lshl_add_u64 v[6:7], s[8:9], 0, v[2:3]
	v_add_co_u32_e32 v16, vcc, s6, v24
	v_lshl_add_u64 v[28:29], v[6:7], 0, v[4:5]
	s_nop 0
	v_addc_co_u32_e32 v17, vcc, 0, v25, vcc
	s_mov_b32 s6, 0x18000
	global_load_dwordx4 v[0:3], v[24:25], off
	global_load_dwordx4 v[4:7], v[28:29], off
	v_add_co_u32_e32 v24, vcc, s6, v24
	global_load_dwordx4 v[8:11], v[8:9], off
	s_nop 0
	global_load_dwordx4 v[12:15], v[28:29], off offset:128
	v_addc_co_u32_e32 v25, vcc, 0, v25, vcc
	global_load_dwordx4 v[16:19], v[16:17], off
	s_nop 0
	global_load_dwordx4 v[20:23], v[28:29], off offset:256
	s_nop 0
	global_load_dwordx4 v[24:27], v[24:25], off
	s_nop 0
	global_load_dwordx4 v[28:31], v[28:29], off offset:384
	v_lshlrev_b32_e32 v32, 7, v32
	s_movk_i32 s6, 0x70
	v_and_or_b32 v32, v37, s6, v32
	s_waitcnt lgkmcnt(0)
	s_barrier
	v_and_b32_e32 v35, 31, v34
	v_lshrrev_b32_e32 v36, 5, v34
	v_bfe_u32 v59, v34, 1, 3
	v_lshlrev_b32_e32 v60, 7, v35
	v_bitop3_b32 v36, v36, v59, 1 bitop3:0x6c
	v_lshl_or_b32 v163, v36, 4, v60
	v_ashrrev_i32_e32 v99, 31, v98
	s_add_i32 s14, s14, s90
	s_cmpk_gt_i32 s14, 0x2ff
	s_waitcnt vmcnt(7)
	ds_write_b128 v32, v[0:3]
	s_waitcnt vmcnt(6)
	ds_write_b128 v32, v[4:7] offset:8192
	s_waitcnt vmcnt(5)
	ds_write_b128 v32, v[8:11] offset:16384
	s_waitcnt vmcnt(4)
	ds_write_b128 v32, v[12:15] offset:24576
	s_waitcnt vmcnt(3)
	ds_write_b128 v32, v[16:19] offset:32768
	s_waitcnt vmcnt(2)
	ds_write_b128 v32, v[20:23] offset:40960
	s_waitcnt vmcnt(1)
	ds_write_b128 v32, v[24:27] offset:49152
	s_waitcnt vmcnt(0)
	ds_write_b128 v32, v[28:31] offset:57344
	v_mov_b64_e32 v[0:1], s[2:3]
	v_mad_i64_i32 v[0:1], s[2:3], v98, s33, v[0:1]
	v_lshl_add_u64 v[0:1], v[0:1], 0, v[176:177]
	global_load_dwordx4 v[78:81], v[0:1], off
	global_load_dwordx4 v[74:77], v[0:1], off offset:32
	global_load_dwordx4 v[70:73], v[0:1], off offset:64
	global_load_dwordx4 v[66:69], v[0:1], off offset:96
	v_lshlrev_b32_e32 v1, 1, v34
	v_lshrrev_b32_e32 v2, 1, v34
	v_and_b32_e32 v0, 19, v34
	v_and_b32_e32 v1, 8, v1
	v_and_b32_e32 v2, 4, v2
	v_or3_b32 v0, v1, v0, v2
	v_lshrrev_b32_e32 v37, 1, v0
	v_lshlrev_b32_e32 v38, 7, v0
	v_bitop3_b32 v0, v37, v58, 7 bitop3:0x6c
	v_lshl_or_b32 v103, v0, 4, v38
	s_waitcnt lgkmcnt(0)
	s_barrier
	ds_read_b128 v[0:3], v103
	ds_read_b128 v[16:19], v103 offset:4096
	v_or_b32_e32 v32, 2, v58
	v_bitop3_b32 v32, v37, v32, 7 bitop3:0x6c
	v_lshl_or_b32 v105, v32, 4, v38
	ds_read_b128 v[32:35], v105
	s_waitcnt lgkmcnt(2)
	v_mfma_f32_32x32x16_bf16 v[0:15], v[0:3], v[94:97], 0
	ds_read_b128 v[150:153], v163 offset:12288
	s_mov_b32 s2, 0xf149f2ca
	s_waitcnt lgkmcnt(1)
	v_mfma_f32_32x32x16_bf16 v[0:15], v[32:35], v[90:93], v[0:15]
	ds_read_b128 v[32:35], v105 offset:4096
	v_mfma_f32_32x32x16_bf16 v[16:31], v[16:19], v[94:97], 0
	s_waitcnt lgkmcnt(0)
	v_mfma_f32_32x32x16_bf16 v[16:31], v[32:35], v[90:93], v[16:31]
	v_or_b32_e32 v32, 4, v58
	v_bitop3_b32 v32, v37, v32, 7 bitop3:0x6c
	v_lshl_or_b32 v107, v32, 4, v38
	ds_read_b128 v[32:35], v107
	s_waitcnt lgkmcnt(0)
	v_mfma_f32_32x32x16_bf16 v[0:15], v[32:35], v[86:89], v[0:15]
	ds_read_b128 v[32:35], v107 offset:4096
	s_waitcnt lgkmcnt(0)
	v_mfma_f32_32x32x16_bf16 v[16:31], v[32:35], v[86:89], v[16:31]
	v_or_b32_e32 v32, 6, v58
	v_bitop3_b32 v32, v37, v32, 7 bitop3:0x6c
	v_lshl_or_b32 v101, v32, 4, v38
	ds_read_b128 v[32:35], v101
	s_waitcnt lgkmcnt(0)
	v_mfma_f32_32x32x16_bf16 v[0:15], v[32:35], v[82:85], v[0:15]
	ds_read_b128 v[32:35], v101 offset:4096
	s_waitcnt lgkmcnt(0)
	v_mfma_f32_32x32x16_bf16 v[16:31], v[32:35], v[82:85], v[16:31]
	s_nop 8
	v_max_f32_e32 v32, v1, v1
	v_max_f32_e32 v33, v0, v0
	v_max_f32_e32 v32, v33, v32
	v_max3_f32 v32, v32, v2, v3
	v_max3_f32 v32, v32, v4, v5
	v_max3_f32 v32, v32, v6, v7
	v_max3_f32 v32, v32, v8, v9
	v_max3_f32 v32, v32, v10, v11
	v_max3_f32 v32, v32, v12, v13
	v_max3_f32 v32, v32, v14, v15
	v_max3_f32 v32, v32, v16, v17
	v_max3_f32 v32, v32, v18, v19
	v_max3_f32 v32, v32, v20, v21
	v_max3_f32 v32, v32, v22, v23
	v_max3_f32 v32, v32, v24, v25
	v_max3_f32 v32, v32, v26, v27
	v_max3_f32 v32, v32, v28, v29
	v_max3_f32 v32, v32, v30, v31
	v_mov_b32_e32 v33, v32
	s_nop 1
	v_permlane32_swap_b32_e32 v32, v33
	v_max3_f32 v109, v32, v33, s2
	v_sub_f32_e32 v0, v0, v109
	v_exp_f32_e32 v38, v0
	v_sub_f32_e32 v0, v16, v109
	v_exp_f32_e32 v39, v0
	v_sub_f32_e32 v37, 0xf149f2ca, v109
	v_add_f32_e32 v0, v38, v39
	v_add_f32_e32 v33, 0, v0
	v_sub_f32_e32 v0, v1, v109
	v_exp_f32_e32 v40, v0
	v_sub_f32_e32 v0, v17, v109
	v_exp_f32_e32 v41, v0
	v_sub_f32_e32 v0, v2, v109
	v_exp_f32_e32 v16, v0
	v_sub_f32_e32 v0, v18, v109
	v_exp_f32_e32 v32, v0
	v_add_f32_e32 v17, v40, v41
	v_cvt_pk_bf16_f32 v62, v38, v40
	v_cvt_pk_bf16_f32 v54, v39, v41
	v_add_f32_e32 v0, v16, v32
	v_add_f32_e32 v1, v17, v33
	s_nop 0
	v_add_f32_e32 v34, v0, v0
	v_add_f32_e32 v35, v0, v1
	v_sub_f32_e32 v0, v3, v109
	v_exp_f32_e32 v17, v0
	v_sub_f32_e32 v0, v19, v109
	v_exp_f32_e32 v33, v0
	v_sub_f32_e32 v0, v4, v109
	v_exp_f32_e32 v18, v0
	v_sub_f32_e32 v0, v20, v109
	v_exp_f32_e32 v34, v0
	v_add_f32_e32 v19, v17, v33
	v_cvt_pk_bf16_f32 v63, v16, v17
	v_cvt_pk_bf16_f32 v55, v32, v33
	v_add_f32_e32 v0, v18, v34
	v_add_f32_e32 v1, v19, v35
	s_nop 0
	v_add_f32_e32 v144, v0, v1
	v_add_f32_e32 v145, v1, v0
	v_sub_f32_e32 v0, v5, v109
	v_exp_f32_e32 v104, v0
	v_sub_f32_e32 v0, v21, v109
	v_exp_f32_e32 v100, v0
	v_sub_f32_e32 v0, v6, v109
	v_exp_f32_e32 v108, v0
	v_sub_f32_e32 v0, v22, v109
	v_exp_f32_e32 v102, v0
	v_sub_f32_e32 v0, v7, v109
	v_exp_f32_e32 v112, v0
	v_sub_f32_e32 v0, v23, v109
	v_exp_f32_e32 v106, v0
	v_sub_f32_e32 v0, v8, v109
	v_exp_f32_e32 v116, v0
	v_sub_f32_e32 v0, v24, v109
	v_exp_f32_e32 v110, v0
	v_sub_f32_e32 v0, v9, v109
	v_exp_f32_e32 v120, v0
	v_sub_f32_e32 v0, v25, v109
	v_exp_f32_e32 v114, v0
	v_sub_f32_e32 v0, v10, v109
	v_exp_f32_e32 v122, v0
	v_sub_f32_e32 v0, v26, v109
	v_exp_f32_e32 v118, v0
	v_sub_f32_e32 v0, v11, v109
	v_exp_f32_e32 v128, v0
	v_sub_f32_e32 v0, v27, v109
	v_exp_f32_e32 v124, v0
	v_sub_f32_e32 v0, v12, v109
	v_exp_f32_e32 v132, v0
	v_sub_f32_e32 v0, v28, v109
	v_exp_f32_e32 v126, v0
	v_sub_f32_e32 v0, v13, v109
	v_exp_f32_e32 v136, v0
	v_sub_f32_e32 v0, v29, v109
	v_exp_f32_e32 v130, v0
	v_sub_f32_e32 v0, v14, v109
	v_exp_f32_e32 v140, v0
	v_sub_f32_e32 v0, v30, v109
	v_exp_f32_e32 v134, v0
	v_sub_f32_e32 v0, v15, v109
	v_exp_f32_e32 v142, v0
	v_sub_f32_e32 v0, v31, v109
	v_exp_f32_e32 v138, v0
	v_exp_f32_e32 v0, v37
	v_cvt_pk_bf16_f32 v56, v34, v100
	ds_read_b128 v[34:37], v163 offset:8192
	v_cvt_pk_bf16_f32 v64, v18, v104
	v_mul_f32_e32 v0, 0, v0
	v_mov_b32_e32 v1, v0
	v_mov_b32_e32 v2, v0
	v_mov_b32_e32 v3, v0
	v_mov_b32_e32 v4, v0
	v_mov_b32_e32 v5, v0
	v_mov_b32_e32 v6, v0
	v_mov_b32_e32 v7, v0
	v_mov_b32_e32 v8, v0
	v_mov_b32_e32 v9, v0
	v_mov_b32_e32 v10, v0
	v_mov_b32_e32 v11, v0
	v_mov_b32_e32 v12, v0
	v_mov_b32_e32 v13, v0
	v_mov_b32_e32 v14, v0
	v_mov_b32_e32 v15, v0
	v_cvt_pk_bf16_f32 v65, v108, v112
	v_cvt_pk_bf16_f32 v146, v116, v120
	v_cvt_pk_bf16_f32 v147, v122, v128
	s_waitcnt lgkmcnt(0)
	v_mfma_f32_32x32x16_bf16 v[18:33], v[34:37], v[62:65], v[0:15]
	v_mov_b64_e32 v[48:49], v[14:15]
	v_mov_b64_e32 v[46:47], v[12:13]
	v_mov_b64_e32 v[44:45], v[10:11]
	v_mov_b64_e32 v[42:43], v[8:9]
	v_mov_b64_e32 v[40:41], v[6:7]
	v_mov_b64_e32 v[38:39], v[4:5]
	v_mov_b64_e32 v[36:37], v[2:3]
	v_mov_b64_e32 v[34:35], v[0:1]
	v_bitop3_b32 v1, v58, v59, 2 bitop3:0x36
	v_lshl_or_b32 v162, v1, 4, v60
	ds_read_b128 v[2:5], v162 offset:8192
	v_cvt_pk_bf16_f32 v148, v132, v136
	v_cvt_pk_bf16_f32 v149, v140, v142
	v_mfma_f32_32x32x16_bf16 v[34:49], v[150:153], v[62:65], v[34:49]
	v_bitop3_b32 v1, v58, v59, 4 bitop3:0x36
	v_lshl_or_b32 v161, v1, 4, v60
	v_cvt_pk_bf16_f32 v57, v102, v106
	v_bitop3_b32 v1, v58, v59, 6 bitop3:0x36
	v_lshl_or_b32 v160, v1, 4, v60
	v_cvt_pk_bf16_f32 v50, v110, v114
	v_cvt_pk_bf16_f32 v51, v118, v124
	s_waitcnt lgkmcnt(0)
	v_mfma_f32_32x32x16_bf16 v[18:33], v[2:5], v[146:149], v[18:33]
	ds_read_b128 v[2:5], v162 offset:12288
	v_cvt_pk_bf16_f32 v52, v126, v130
	v_cvt_pk_bf16_f32 v53, v134, v138
	v_mov_b32_e32 v145, v177
	s_waitcnt lgkmcnt(0)
	v_mfma_f32_32x32x16_bf16 v[34:49], v[2:5], v[146:149], v[34:49]
	ds_read_b128 v[2:5], v161 offset:8192
	ds_read_b128 v[146:149], v105 offset:16384
	s_waitcnt lgkmcnt(1)
	v_mfma_f32_32x32x16_bf16 v[18:33], v[2:5], v[54:57], v[18:33]
	ds_read_b128 v[2:5], v161 offset:12288
	s_waitcnt lgkmcnt(0)
	v_mfma_f32_32x32x16_bf16 v[34:49], v[2:5], v[54:57], v[34:49]
	ds_read_b128 v[2:5], v160 offset:8192
	s_waitcnt lgkmcnt(0)
	v_mfma_f32_32x32x16_bf16 v[18:33], v[2:5], v[50:53], v[18:33]
	ds_read_b128 v[2:5], v160 offset:12288
	s_waitcnt lgkmcnt(0)
	v_mfma_f32_32x32x16_bf16 v[34:49], v[2:5], v[50:53], v[34:49]
	ds_read_b128 v[2:5], v103 offset:16384
	ds_read_b128 v[50:53], v103 offset:20480
	s_waitcnt lgkmcnt(1)
	v_mfma_f32_32x32x16_bf16 v[2:17], v[2:5], v[94:97], 0
	v_mfma_f32_32x32x16_bf16 v[2:17], v[146:149], v[90:93], v[2:17]
	ds_read_b128 v[146:149], v105 offset:20480
	s_waitcnt lgkmcnt(1)
	v_mfma_f32_32x32x16_bf16 v[50:65], v[50:53], v[94:97], 0
	s_waitcnt lgkmcnt(0)
	v_mfma_f32_32x32x16_bf16 v[50:65], v[146:149], v[90:93], v[50:65]
	ds_read_b128 v[146:149], v107 offset:16384
	s_waitcnt lgkmcnt(0)
	v_mfma_f32_32x32x16_bf16 v[2:17], v[146:149], v[86:89], v[2:17]
	ds_read_b128 v[146:149], v107 offset:20480
	s_waitcnt lgkmcnt(0)
	v_mfma_f32_32x32x16_bf16 v[50:65], v[146:149], v[86:89], v[50:65]
	ds_read_b128 v[146:149], v101 offset:16384
	s_waitcnt lgkmcnt(0)
	v_mfma_f32_32x32x16_bf16 v[2:17], v[146:149], v[82:85], v[2:17]
	ds_read_b128 v[146:149], v101 offset:20480
	s_waitcnt lgkmcnt(0)
	v_mfma_f32_32x32x16_bf16 v[50:65], v[146:149], v[82:85], v[50:65]
	s_nop 8
	v_max_f32_e32 v1, v3, v3
	v_max_f32_e32 v111, v2, v2
	v_max_f32_e32 v1, v111, v1
	v_max3_f32 v1, v1, v4, v5
	v_max3_f32 v1, v1, v6, v7
	v_max3_f32 v1, v1, v8, v9
	v_max3_f32 v1, v1, v10, v11
	v_max3_f32 v1, v1, v12, v13
	v_max3_f32 v1, v1, v14, v15
	v_max3_f32 v1, v1, v16, v17
	v_max3_f32 v1, v1, v50, v51
	v_max3_f32 v1, v1, v52, v53
	v_max3_f32 v1, v1, v54, v55
	v_max3_f32 v1, v1, v56, v57
	v_max3_f32 v1, v1, v58, v59
	v_max3_f32 v1, v1, v60, v61
	v_max3_f32 v1, v1, v62, v63
	v_max3_f32 v1, v1, v64, v65
	v_mov_b32_e32 v111, v1
	s_nop 1
	v_permlane32_swap_b32_e32 v1, v111
	v_max3_f32 v1, v109, v1, v111
	v_sub_f32_e32 v2, v2, v1
	v_exp_f32_e32 v111, v2
	v_sub_f32_e32 v2, v50, v1
	v_exp_f32_e32 v113, v2
	v_sub_f32_e32 v109, v109, v1
	v_exp_f32_e32 v150, v109
	v_add_f32_e32 v2, v111, v113
	v_add_f32_e32 v153, 0, v2
	v_sub_f32_e32 v2, v3, v1
	v_exp_f32_e32 v115, v2
	v_sub_f32_e32 v2, v51, v1
	v_exp_f32_e32 v117, v2
	v_sub_f32_e32 v2, v4, v1
	v_exp_f32_e32 v50, v2
	v_sub_f32_e32 v2, v52, v1
	v_exp_f32_e32 v152, v2
	v_add_f32_e32 v51, v115, v117
	v_add_f32_e32 v2, v50, v152
	v_add_f32_e32 v3, v51, v153
	s_nop 0
	v_add_f32_e32 v154, v2, v2
	v_add_f32_e32 v155, v2, v3
	v_sub_f32_e32 v2, v5, v1
	v_exp_f32_e32 v51, v2
	v_sub_f32_e32 v2, v53, v1
	v_exp_f32_e32 v119, v2
	v_sub_f32_e32 v2, v6, v1
	v_exp_f32_e32 v52, v2
	v_sub_f32_e32 v2, v54, v1
	v_exp_f32_e32 v154, v2
	v_add_f32_e32 v53, v51, v119
	v_mul_f32_e32 v4, v20, v150
	v_mul_f32_e32 v5, v21, v150
	v_mul_f32_e32 v20, v36, v150
	v_mul_f32_e32 v21, v37, v150
	v_add_f32_e32 v2, v52, v154
	v_add_f32_e32 v3, v53, v155
	s_nop 0
	v_add_f32_e32 v156, v2, v2
	v_add_f32_e32 v157, v2, v3
	v_sub_f32_e32 v2, v7, v1
	v_exp_f32_e32 v53, v2
	v_sub_f32_e32 v2, v55, v1
	v_exp_f32_e32 v121, v2
	v_sub_f32_e32 v2, v8, v1
	v_exp_f32_e32 v54, v2
	v_sub_f32_e32 v2, v56, v1
	v_exp_f32_e32 v156, v2
	v_add_f32_e32 v55, v53, v121
	v_mul_f32_e32 v6, v22, v150
	v_mul_f32_e32 v7, v23, v150
	v_mul_f32_e32 v22, v38, v150
	v_mul_f32_e32 v23, v39, v150
	v_add_f32_e32 v2, v54, v156
	v_add_f32_e32 v3, v55, v157
	v_cvt_pk_bf16_f32 v38, v113, v117
	v_add_f32_e32 v158, v2, v2
	v_add_f32_e32 v159, v2, v3
	v_sub_f32_e32 v2, v9, v1
	v_exp_f32_e32 v55, v2
	v_sub_f32_e32 v2, v57, v1
	v_exp_f32_e32 v123, v2
	v_sub_f32_e32 v2, v10, v1
	v_exp_f32_e32 v56, v2
	v_sub_f32_e32 v2, v58, v1
	v_exp_f32_e32 v158, v2
	v_add_f32_e32 v57, v55, v123
	v_mul_f32_e32 v8, v24, v150
	v_mul_f32_e32 v9, v25, v150
	v_mul_f32_e32 v24, v40, v150
	v_mul_f32_e32 v25, v41, v150
	v_add_f32_e32 v2, v56, v158
	v_add_f32_e32 v3, v57, v159
	v_cvt_pk_bf16_f32 v39, v152, v119
	v_add_f32_e32 v164, v2, v2
	v_add_f32_e32 v165, v2, v3
	v_sub_f32_e32 v2, v11, v1
	v_exp_f32_e32 v57, v2
	v_sub_f32_e32 v2, v59, v1
	v_exp_f32_e32 v125, v2
	v_sub_f32_e32 v2, v12, v1
	v_exp_f32_e32 v58, v2
	v_sub_f32_e32 v2, v60, v1
	v_exp_f32_e32 v164, v2
	v_add_f32_e32 v59, v57, v125
	v_mul_f32_e32 v10, v26, v150
	v_mul_f32_e32 v11, v27, v150
	v_mul_f32_e32 v26, v42, v150
	v_mul_f32_e32 v27, v43, v150
	v_add_f32_e32 v2, v58, v164
	v_add_f32_e32 v3, v59, v165
	v_cvt_pk_bf16_f32 v42, v56, v57
	v_add_f32_e32 v166, v2, v2
	v_add_f32_e32 v167, v2, v3
	v_sub_f32_e32 v2, v13, v1
	v_exp_f32_e32 v59, v2
	v_sub_f32_e32 v2, v61, v1
	v_exp_f32_e32 v127, v2
	v_sub_f32_e32 v2, v14, v1
	v_exp_f32_e32 v60, v2
	v_sub_f32_e32 v2, v62, v1
	v_exp_f32_e32 v166, v2
	v_add_f32_e32 v61, v59, v127
	v_mul_f32_e32 v12, v28, v150
	v_mul_f32_e32 v13, v29, v150
	v_mul_f32_e32 v28, v44, v150
	v_mul_f32_e32 v29, v45, v150
	v_add_f32_e32 v2, v60, v166
	v_add_f32_e32 v3, v61, v167
	v_cvt_pk_bf16_f32 v43, v58, v59
	v_add_f32_e32 v168, v2, v2
	v_add_f32_e32 v169, v2, v3
	v_sub_f32_e32 v2, v15, v1
	v_exp_f32_e32 v61, v2
	v_sub_f32_e32 v2, v63, v1
	v_exp_f32_e32 v129, v2
	v_sub_f32_e32 v2, v16, v1
	v_exp_f32_e32 v62, v2
	v_sub_f32_e32 v2, v64, v1
	v_exp_f32_e32 v168, v2
	v_sub_f32_e32 v2, v17, v1
	v_mul_f32_e32 v16, v32, v150
	v_mul_f32_e32 v17, v33, v150
	v_mul_f32_e32 v14, v30, v150
	v_mul_f32_e32 v15, v31, v150
	v_mul_f32_e32 v32, v48, v150
	v_mul_f32_e32 v33, v49, v150
	v_mul_f32_e32 v30, v46, v150
	v_mul_f32_e32 v31, v47, v150
	v_cvt_pk_bf16_f32 v47, v50, v51
	v_cvt_pk_bf16_f32 v48, v52, v53
	ds_read_b128 v[50:53], v163 offset:24576
	v_add_f32_e32 v63, v61, v129
	v_add_f32_e32 v148, v62, v168
	v_add_f32_e32 v149, v63, v169
	v_exp_f32_e32 v63, v2
	v_sub_f32_e32 v2, v65, v1
	v_exp_f32_e32 v64, v2
	v_mul_f32_e32 v2, v18, v150
	v_mul_f32_e32 v3, v19, v150
	v_cvt_pk_bf16_f32 v46, v111, v115
	v_cvt_pk_bf16_f32 v49, v54, v55
	v_mul_f32_e32 v18, v34, v150
	v_mul_f32_e32 v19, v35, v150
	v_cvt_pk_bf16_f32 v44, v60, v61
	s_waitcnt lgkmcnt(0)
	v_mfma_f32_32x32x16_bf16 v[2:17], v[50:53], v[46:49], v[2:17]
	ds_read_b128 v[50:53], v163 offset:28672
	v_cvt_pk_bf16_f32 v45, v62, v63
	v_cvt_pk_bf16_f32 v40, v154, v121
	v_cvt_pk_bf16_f32 v41, v156, v123
	v_cvt_pk_bf16_f32 v34, v158, v125
	v_cvt_pk_bf16_f32 v35, v164, v127
	v_cvt_pk_bf16_f32 v36, v166, v129
	s_waitcnt lgkmcnt(0)
	v_mfma_f32_32x32x16_bf16 v[18:33], v[50:53], v[46:49], v[18:33]
	ds_read_b128 v[46:49], v162 offset:24576
	v_cvt_pk_bf16_f32 v37, v168, v64
	ds_read_b128 v[152:155], v105 offset:32768
	ds_read_b128 v[50:53], v103 offset:36864
	v_add_f32_e32 v146, v63, v64
	s_waitcnt lgkmcnt(2)
	v_mfma_f32_32x32x16_bf16 v[2:17], v[46:49], v[42:45], v[2:17]
	ds_read_b128 v[46:49], v162 offset:28672
	s_waitcnt lgkmcnt(0)
	v_mfma_f32_32x32x16_bf16 v[18:33], v[46:49], v[42:45], v[18:33]
	ds_read_b128 v[42:45], v161 offset:24576
	s_waitcnt lgkmcnt(0)
	v_mfma_f32_32x32x16_bf16 v[2:17], v[42:45], v[38:41], v[2:17]
	ds_read_b128 v[42:45], v161 offset:28672
	s_waitcnt lgkmcnt(0)
	v_mfma_f32_32x32x16_bf16 v[18:33], v[42:45], v[38:41], v[18:33]
	ds_read_b128 v[38:41], v160 offset:24576
	s_waitcnt lgkmcnt(0)
	v_mfma_f32_32x32x16_bf16 v[2:17], v[38:41], v[34:37], v[2:17]
	ds_read_b128 v[38:41], v160 offset:28672
	s_waitcnt lgkmcnt(0)
	v_mfma_f32_32x32x16_bf16 v[18:33], v[38:41], v[34:37], v[18:33]
	ds_read_b128 v[34:37], v103 offset:32768
	s_waitcnt lgkmcnt(0)
	v_mfma_f32_32x32x16_bf16 v[34:49], v[34:37], v[94:97], 0
	v_mfma_f32_32x32x16_bf16 v[34:49], v[152:155], v[90:93], v[34:49]
	ds_read_b128 v[152:155], v105 offset:36864
	v_mfma_f32_32x32x16_bf16 v[50:65], v[50:53], v[94:97], 0
	s_waitcnt lgkmcnt(0)
	v_mfma_f32_32x32x16_bf16 v[50:65], v[152:155], v[90:93], v[50:65]
	ds_read_b128 v[152:155], v107 offset:32768
	s_waitcnt lgkmcnt(0)
	v_mfma_f32_32x32x16_bf16 v[34:49], v[152:155], v[86:89], v[34:49]
	ds_read_b128 v[152:155], v107 offset:36864
	s_waitcnt lgkmcnt(0)
	v_mfma_f32_32x32x16_bf16 v[50:65], v[152:155], v[86:89], v[50:65]
	ds_read_b128 v[152:155], v101 offset:32768
	s_waitcnt lgkmcnt(0)
	v_mfma_f32_32x32x16_bf16 v[34:49], v[152:155], v[82:85], v[34:49]
	ds_read_b128 v[152:155], v101 offset:36864
	s_waitcnt lgkmcnt(0)
	v_mfma_f32_32x32x16_bf16 v[50:65], v[152:155], v[82:85], v[50:65]
	s_nop 8
	v_max_f32_e32 v109, v35, v35
	v_max_f32_e32 v111, v34, v34
	v_max_f32_e32 v109, v111, v109
	v_max3_f32 v109, v109, v36, v37
	v_max3_f32 v109, v109, v38, v39
	v_max3_f32 v109, v109, v40, v41
	v_max3_f32 v109, v109, v42, v43
	v_max3_f32 v109, v109, v44, v45
	v_max3_f32 v109, v109, v46, v47
	v_max3_f32 v109, v109, v48, v49
	v_max3_f32 v109, v109, v50, v51
	v_max3_f32 v109, v109, v52, v53
	v_max3_f32 v109, v109, v54, v55
	v_max3_f32 v109, v109, v56, v57
	v_max3_f32 v109, v109, v58, v59
	v_max3_f32 v109, v109, v60, v61
	v_max3_f32 v109, v109, v62, v63
	v_max3_f32 v109, v109, v64, v65
	v_mov_b32_e32 v111, v109
	s_nop 1
	v_permlane32_swap_b32_e32 v109, v111
	v_max3_f32 v109, v1, v109, v111
	v_sub_f32_e32 v34, v34, v109
	v_exp_f32_e32 v111, v34
	v_sub_f32_e32 v34, v50, v109
	v_exp_f32_e32 v113, v34
	v_sub_f32_e32 v1, v1, v109
	v_exp_f32_e32 v156, v1
	v_add_f32_e32 v34, v111, v113
	v_add_f32_e32 v159, 0, v34
	v_sub_f32_e32 v34, v35, v109
	v_exp_f32_e32 v115, v34
	v_sub_f32_e32 v34, v51, v109
	v_exp_f32_e32 v117, v34
	v_sub_f32_e32 v34, v36, v109
	v_sub_f32_e32 v36, v52, v109
	v_exp_f32_e32 v34, v34
	v_exp_f32_e32 v158, v36
	v_add_f32_e32 v35, v115, v117
	v_sub_f32_e32 v36, v53, v109
	v_exp_f32_e32 v119, v36
	v_add_f32_e32 v50, v34, v158
	v_add_f32_e32 v51, v35, v159
	v_sub_f32_e32 v35, v37, v109
	v_add_f32_e32 v51, v50, v51
	v_add_f32_e32 v50, v50, v50
	v_exp_f32_e32 v35, v35
	v_sub_f32_e32 v36, v38, v109
	v_sub_f32_e32 v38, v54, v109
	v_exp_f32_e32 v36, v36
	v_exp_f32_e32 v50, v38
	v_add_f32_e32 v37, v35, v119
	v_sub_f32_e32 v38, v55, v109
	v_mul_f32_e32 v16, v16, v156
	v_mul_f32_e32 v17, v17, v156
	v_add_f32_e32 v52, v36, v50
	v_add_f32_e32 v53, v37, v51
	v_sub_f32_e32 v37, v39, v109
	v_add_f32_e32 v53, v52, v53
	v_add_f32_e32 v52, v52, v52
	v_exp_f32_e32 v37, v37
	v_exp_f32_e32 v51, v38
	v_sub_f32_e32 v38, v40, v109
	v_sub_f32_e32 v40, v56, v109
	v_exp_f32_e32 v38, v38
	v_exp_f32_e32 v52, v40
	v_add_f32_e32 v39, v37, v51
	v_sub_f32_e32 v40, v57, v109
	v_mul_f32_e32 v14, v14, v156
	v_mul_f32_e32 v15, v15, v156
	v_add_f32_e32 v54, v38, v52
	v_add_f32_e32 v55, v39, v53
	v_sub_f32_e32 v39, v41, v109
	v_add_f32_e32 v55, v54, v55
	v_add_f32_e32 v54, v54, v54
	v_exp_f32_e32 v39, v39
	v_exp_f32_e32 v53, v40
	v_sub_f32_e32 v40, v42, v109
	v_sub_f32_e32 v42, v58, v109
	v_exp_f32_e32 v40, v40
	v_exp_f32_e32 v54, v42
	v_add_f32_e32 v41, v39, v53
	v_sub_f32_e32 v42, v59, v109
	v_mul_f32_e32 v12, v12, v156
	v_mul_f32_e32 v13, v13, v156
	v_add_f32_e32 v56, v40, v54
	v_add_f32_e32 v57, v41, v55
	v_sub_f32_e32 v41, v43, v109
	v_exp_f32_e32 v55, v42
	v_sub_f32_e32 v42, v44, v109
	v_add_f32_e32 v57, v56, v57
	v_add_f32_e32 v56, v56, v56
	v_exp_f32_e32 v41, v41
	v_exp_f32_e32 v58, v42
	v_sub_f32_e32 v42, v60, v109
	v_exp_f32_e32 v56, v42
	v_add_f32_e32 v59, v41, v55
	v_mul_f32_e32 v10, v10, v156
	v_mul_f32_e32 v11, v11, v156
	v_mul_f32_e32 v8, v8, v156
	v_mul_f32_e32 v9, v9, v156
	v_add_f32_e32 v42, v58, v56
	v_add_f32_e32 v43, v59, v57
	v_mul_f32_e32 v6, v6, v156
	v_mul_f32_e32 v7, v7, v156
	v_add_f32_e32 v164, v42, v42
	v_add_f32_e32 v165, v42, v43
	v_sub_f32_e32 v42, v45, v109
	v_exp_f32_e32 v57, v42
	v_sub_f32_e32 v42, v61, v109
	v_exp_f32_e32 v59, v42
	v_sub_f32_e32 v42, v46, v109
	v_exp_f32_e32 v44, v42
	v_sub_f32_e32 v42, v62, v109
	v_exp_f32_e32 v164, v42
	v_add_f32_e32 v45, v57, v59
	v_mul_f32_e32 v4, v4, v156
	v_mul_f32_e32 v5, v5, v156
	v_mul_f32_e32 v2, v2, v156
	v_mul_f32_e32 v3, v3, v156
	v_add_f32_e32 v42, v44, v164
	v_add_f32_e32 v43, v45, v165
	v_cvt_pk_bf16_f32 v46, v111, v115
	v_add_f32_e32 v60, v42, v42
	v_add_f32_e32 v61, v42, v43
	v_sub_f32_e32 v42, v47, v109
	v_exp_f32_e32 v45, v42
	v_sub_f32_e32 v42, v63, v109
	v_exp_f32_e32 v121, v42
	v_sub_f32_e32 v42, v48, v109
	v_exp_f32_e32 v62, v42
	v_sub_f32_e32 v42, v64, v109
	v_exp_f32_e32 v60, v42
	v_add_f32_e32 v63, v45, v121
	v_sub_f32_e32 v42, v49, v109
	v_cvt_pk_bf16_f32 v47, v34, v35
	v_add_f32_e32 v154, v62, v60
	v_add_f32_e32 v155, v63, v61
	v_exp_f32_e32 v61, v42
	v_sub_f32_e32 v42, v65, v109
	v_exp_f32_e32 v63, v42
	v_cvt_pk_bf16_f32 v42, v40, v41
	v_cvt_pk_bf16_f32 v40, v50, v51
	v_cvt_pk_bf16_f32 v41, v52, v53
	ds_read_b128 v[50:53], v163 offset:40960
	v_cvt_pk_bf16_f32 v48, v36, v37
	v_cvt_pk_bf16_f32 v49, v38, v39
	v_mul_f32_e32 v32, v32, v156
	v_mul_f32_e32 v33, v33, v156
	v_mul_f32_e32 v30, v30, v156
	v_mul_f32_e32 v31, v31, v156
	s_waitcnt lgkmcnt(0)
	v_mfma_f32_32x32x16_bf16 v[2:17], v[50:53], v[46:49], v[2:17]
	ds_read_b128 v[50:53], v163 offset:45056
	v_mul_f32_e64 v28, v28, v156
	v_mul_f32_e64 v29, v29, v156
	v_mul_f32_e64 v26, v26, v156
	v_mul_f32_e64 v27, v27, v156
	v_mul_f32_e32 v24, v24, v156
	v_mul_f32_e32 v25, v25, v156
	v_mul_f32_e32 v22, v22, v156
	v_mul_f32_e32 v23, v23, v156
	v_mul_f32_e32 v20, v20, v156
	v_mul_f32_e32 v21, v21, v156
	v_mul_f32_e32 v18, v18, v156
	v_mul_f32_e32 v19, v19, v156
	v_cvt_pk_bf16_f32 v43, v58, v57
	v_cvt_pk_bf16_f32 v44, v44, v45
	s_waitcnt lgkmcnt(0)
	v_mfma_f32_32x32x16_bf16 v[18:33], v[50:53], v[46:49], v[18:33]
	ds_read_b128 v[46:49], v162 offset:40960
	v_cvt_pk_bf16_f32 v45, v62, v61
	v_cvt_pk_bf16_f32 v38, v113, v117
	v_cvt_pk_bf16_f32 v39, v158, v119
	v_cvt_pk_bf16_f32 v34, v54, v55
	v_cvt_pk_bf16_f32 v35, v56, v59
	v_cvt_pk_bf16_f32 v36, v164, v121
	s_waitcnt lgkmcnt(0)
	v_mfma_f32_32x32x16_bf16 v[2:17], v[46:49], v[42:45], v[2:17]
	ds_read_b128 v[46:49], v162 offset:45056
	v_cvt_pk_bf16_f32 v37, v60, v63
	ds_read_b128 v[50:53], v103 offset:53248
	v_add_f32_e32 v152, v61, v63
	s_waitcnt lgkmcnt(1)
	v_mfma_f32_32x32x16_bf16 v[18:33], v[46:49], v[42:45], v[18:33]
	ds_read_b128 v[42:45], v161 offset:40960
	s_waitcnt lgkmcnt(0)
	v_mfma_f32_32x32x16_bf16 v[2:17], v[42:45], v[38:41], v[2:17]
	ds_read_b128 v[42:45], v161 offset:45056
	s_waitcnt lgkmcnt(0)
	v_mfma_f32_32x32x16_bf16 v[18:33], v[42:45], v[38:41], v[18:33]
	ds_read_b128 v[38:41], v160 offset:40960
	s_waitcnt lgkmcnt(0)
	v_mfma_f32_32x32x16_bf16 v[2:17], v[38:41], v[34:37], v[2:17]
	ds_read_b128 v[38:41], v160 offset:45056
	s_waitcnt lgkmcnt(0)
	v_mfma_f32_32x32x16_bf16 v[18:33], v[38:41], v[34:37], v[18:33]
	ds_read_b128 v[34:37], v103 offset:49152
	s_waitcnt lgkmcnt(0)
	v_mfma_f32_32x32x16_bf16 v[34:49], v[34:37], v[94:97], 0
	v_mfma_f32_32x32x16_bf16 v[50:65], v[50:53], v[94:97], 0
	ds_read_b128 v[94:97], v105 offset:49152
	s_waitcnt lgkmcnt(0)
	v_mfma_f32_32x32x16_bf16 v[34:49], v[94:97], v[90:93], v[34:49]
	ds_read_b128 v[94:97], v105 offset:53248
	s_waitcnt lgkmcnt(0)
	v_mfma_f32_32x32x16_bf16 v[50:65], v[94:97], v[90:93], v[50:65]
	ds_read_b128 v[90:93], v107 offset:49152
	s_waitcnt lgkmcnt(0)
	v_mfma_f32_32x32x16_bf16 v[34:49], v[90:93], v[86:89], v[34:49]
	ds_read_b128 v[90:93], v107 offset:53248
	s_waitcnt lgkmcnt(0)
	v_mfma_f32_32x32x16_bf16 v[50:65], v[90:93], v[86:89], v[50:65]
	ds_read_b128 v[86:89], v101 offset:49152
	s_waitcnt lgkmcnt(0)
	v_mfma_f32_32x32x16_bf16 v[34:49], v[86:89], v[82:85], v[34:49]
	ds_read_b128 v[86:89], v101 offset:53248
	s_waitcnt lgkmcnt(0)
	v_mfma_f32_32x32x16_bf16 v[50:65], v[86:89], v[82:85], v[50:65]
	s_nop 8
	v_max_f32_e32 v1, v35, v35
	v_max_f32_e32 v82, v34, v34
	v_max_f32_e32 v1, v82, v1
	v_max3_f32 v1, v1, v36, v37
	v_max3_f32 v1, v1, v38, v39
	v_max3_f32 v1, v1, v40, v41
	v_max3_f32 v1, v1, v42, v43
	v_max3_f32 v1, v1, v44, v45
	v_max3_f32 v1, v1, v46, v47
	v_max3_f32 v1, v1, v48, v49
	v_max3_f32 v1, v1, v50, v51
	v_max3_f32 v1, v1, v52, v53
	v_max3_f32 v1, v1, v54, v55
	v_max3_f32 v1, v1, v56, v57
	v_max3_f32 v1, v1, v58, v59
	v_max3_f32 v1, v1, v60, v61
	v_max3_f32 v1, v1, v62, v63
	v_max3_f32 v1, v1, v64, v65
	v_mov_b32_e32 v82, v1
	s_nop 1
	v_permlane32_swap_b32_e32 v1, v82
	v_max3_f32 v82, v109, v1, v82
	v_sub_f32_e32 v1, v34, v82
	v_exp_f32_e32 v105, v1
	v_sub_f32_e32 v1, v50, v82
	v_exp_f32_e32 v101, v1
	v_sub_f32_e32 v1, v35, v82
	v_sub_f32_e32 v83, v109, v82
	v_exp_f32_e32 v109, v1
	v_sub_f32_e32 v1, v51, v82
	v_exp_f32_e32 v103, v1
	v_sub_f32_e32 v1, v36, v82
	v_exp_f32_e32 v113, v1
	v_sub_f32_e32 v1, v52, v82
	v_exp_f32_e32 v107, v1
	v_sub_f32_e32 v1, v37, v82
	v_exp_f32_e32 v117, v1
	v_sub_f32_e32 v1, v53, v82
	v_exp_f32_e32 v111, v1
	v_sub_f32_e32 v1, v38, v82
	v_exp_f32_e32 v121, v1
	v_sub_f32_e32 v1, v54, v82
	v_exp_f32_e32 v115, v1
	v_sub_f32_e32 v1, v39, v82
	v_exp_f32_e32 v123, v1
	v_sub_f32_e32 v1, v55, v82
	v_exp_f32_e32 v119, v1
	v_sub_f32_e32 v1, v40, v82
	v_exp_f32_e32 v129, v1
	v_sub_f32_e32 v1, v56, v82
	v_exp_f32_e32 v125, v1
	v_sub_f32_e32 v1, v41, v82
	v_exp_f32_e32 v133, v1
	v_sub_f32_e32 v1, v57, v82
	v_exp_f32_e32 v127, v1
	v_sub_f32_e32 v1, v42, v82
	v_add_f32_e32 v34, v104, v100
	v_add_f32_e32 v35, v105, v101
	v_exp_f32_e32 v137, v1
	v_sub_f32_e32 v1, v58, v82
	v_add_f32_e32 v34, v34, v144
	v_add_f32_e32 v35, v35, v145
	v_add_f32_e32 v36, v108, v102
	v_add_f32_e32 v37, v109, v103
	v_exp_f32_e32 v131, v1
	v_sub_f32_e32 v1, v43, v82
	v_add_f32_e32 v34, v36, v34
	v_add_f32_e32 v35, v37, v35
	v_add_f32_e32 v36, v112, v106
	v_add_f32_e32 v37, v113, v107
	v_exp_f32_e32 v141, v1
	v_sub_f32_e32 v1, v59, v82
	v_add_f32_e32 v34, v36, v34
	v_add_f32_e32 v35, v37, v35
	v_add_f32_e32 v36, v116, v110
	v_add_f32_e32 v37, v117, v111
	v_exp_f32_e32 v135, v1
	v_sub_f32_e32 v1, v44, v82
	v_add_f32_e32 v34, v36, v34
	v_add_f32_e32 v35, v37, v35
	v_add_f32_e32 v36, v120, v114
	v_add_f32_e32 v37, v121, v115
	v_exp_f32_e32 v143, v1
	v_sub_f32_e32 v1, v60, v82
	v_exp_f32_e32 v139, v1
	v_sub_f32_e32 v1, v45, v82
	v_add_f32_e32 v34, v36, v34
	v_add_f32_e32 v35, v37, v35
	v_add_f32_e32 v36, v122, v118
	v_add_f32_e32 v37, v123, v119
	v_exp_f32_e32 v53, v1
	v_sub_f32_e32 v1, v61, v82
	v_sub_f32_e32 v38, v46, v82
	v_add_f32_e32 v34, v36, v34
	v_add_f32_e32 v35, v37, v35
	v_add_f32_e32 v36, v128, v124
	v_add_f32_e32 v37, v129, v125
	v_exp_f32_e32 v54, v1
	v_exp_f32_e32 v55, v38
	v_sub_f32_e32 v38, v62, v82
	v_add_f32_e32 v34, v36, v34
	v_add_f32_e32 v35, v37, v35
	v_add_f32_e32 v36, v132, v126
	v_add_f32_e32 v37, v133, v127
	v_exp_f32_e32 v56, v38
	v_add_f32_e32 v34, v36, v34
	v_add_f32_e32 v35, v37, v35
	v_add_f32_e32 v36, v136, v130
	v_add_f32_e32 v37, v137, v131
	v_sub_f32_e32 v38, v47, v82
	v_add_f32_e32 v34, v36, v34
	v_add_f32_e32 v35, v37, v35
	v_add_f32_e32 v36, v140, v134
	v_add_f32_e32 v37, v141, v135
	v_exp_f32_e32 v147, v38
	v_sub_f32_e32 v38, v63, v82
	v_add_f32_e32 v34, v36, v34
	v_add_f32_e32 v35, v37, v35
	v_add_f32_e32 v36, v142, v138
	v_add_f32_e32 v37, v143, v139
	v_add_f32_e32 v1, v53, v54
	v_exp_f32_e32 v57, v38
	v_sub_f32_e32 v38, v48, v82
	v_add_f32_e32 v34, v36, v34
	v_add_f32_e32 v35, v37, v35
	v_add_f32_e32 v151, v55, v56
	v_exp_f32_e32 v58, v38
	v_sub_f32_e32 v38, v64, v82
	v_add_f32_e32 v0, v0, v34
	v_add_f32_e32 v1, v1, v35
	v_exp_f32_e32 v59, v38
	v_mul_f32_e32 v34, v0, v150
	v_mul_f32_e32 v35, v1, v151
	v_add_f32_e32 v0, v0, v150
	v_add_f32_e32 v1, v1, v151
	v_sub_f32_e32 v38, v49, v82
	v_mov_b32_e32 v35, v1
	v_add_f32_e32 v0, v148, v149
	v_add_f32_e32 v1, v149, v148
	v_exp_f32_e32 v153, v38
	v_sub_f32_e32 v38, v65, v82
	v_mov_b32_e32 v1, v57
	v_exp_f32_e32 v60, v38
	v_add_f32_e32 v0, v146, v0
	v_add_f32_e32 v1, v147, v1
	v_add_f32_e32 v157, v58, v59
	v_add_f32_e32 v0, v34, v0
	v_add_f32_e32 v1, v35, v1
	v_exp_f32_e32 v52, v83
	v_mul_f32_e32 v34, v0, v156
	v_mul_f32_e32 v35, v1, v157
	v_add_f32_e32 v0, v0, v156
	v_add_f32_e32 v1, v1, v157
	v_mul_f32_e32 v48, v16, v52
	v_mul_f32_e32 v49, v17, v52
	v_mov_b32_e32 v35, v1
	v_add_f32_e32 v0, v154, v155
	v_add_f32_e32 v1, v155, v154
	v_mul_f32_e32 v40, v8, v52
	v_mul_f32_e32 v41, v9, v52
	v_mov_b32_e32 v1, v60
	v_add_f32_e32 v0, v152, v0
	v_add_f32_e32 v1, v153, v1
	v_mul_f32_e32 v8, v26, v52
	v_mul_f32_e32 v9, v27, v52
	v_add_f32_e32 v50, v34, v0
	v_add_f32_e32 v51, v35, v1
	v_mul_f32_e32 v0, v18, v52
	v_mul_f32_e32 v1, v19, v52
	v_cvt_pk_bf16_f32 v26, v55, v147
	v_cvt_pk_bf16_f32 v17, v139, v54
	v_cvt_pk_bf16_f32 v18, v56, v57
	ds_read_b128 v[54:57], v163 offset:57344
	v_mul_f32_e32 v46, v14, v52
	v_mul_f32_e32 v47, v15, v52
	v_mul_f32_e32 v44, v12, v52
	v_mul_f32_e32 v45, v13, v52
	v_mul_f32_e32 v42, v10, v52
	v_mul_f32_e32 v43, v11, v52
	v_mul_f32_e32 v38, v6, v52
	v_mul_f32_e32 v39, v7, v52
	v_mul_f32_e32 v36, v4, v52
	v_mul_f32_e32 v37, v5, v52
	v_mul_f32_e32 v34, v2, v52
	v_mul_f32_e32 v35, v3, v52
	v_mul_f32_e32 v12, v30, v52
	v_mul_f32_e32 v13, v31, v52
	v_mul_f32_e32 v10, v28, v52
	v_mul_f32_e32 v11, v29, v52
	v_cvt_pk_bf16_f32 v28, v105, v109
	v_cvt_pk_bf16_f32 v29, v113, v117
	v_cvt_pk_bf16_f32 v30, v121, v123
	v_cvt_pk_bf16_f32 v31, v129, v133
	v_mul_f32_e32 v14, v32, v52
	v_mul_f32_e32 v15, v33, v52
	v_mul_f32_e32 v6, v24, v52
	v_mul_f32_e32 v7, v25, v52
	s_waitcnt lgkmcnt(0)
	v_mfma_f32_32x32x16_bf16 v[34:49], v[54:57], v[28:31], v[34:49]
	ds_read_b128 v[54:57], v163 offset:61440
	v_mul_f32_e64 v4, v22, v52
	v_mul_f32_e64 v5, v23, v52
	v_mul_f32_e64 v2, v20, v52
	v_mul_f32_e64 v3, v21, v52
	v_cvt_pk_bf16_f32 v24, v137, v141
	v_cvt_pk_bf16_f32 v25, v143, v53
	v_cvt_pk_bf16_f32 v27, v58, v153
	v_cvt_pk_bf16_f32 v20, v101, v103
	s_waitcnt lgkmcnt(0)
	v_mfma_f32_32x32x16_bf16 v[0:15], v[54:57], v[28:31], v[0:15]
	ds_read_b128 v[28:31], v162 offset:57344
	v_cvt_pk_bf16_f32 v21, v107, v111
	v_cvt_pk_bf16_f32 v22, v115, v119
	v_cvt_pk_bf16_f32 v23, v125, v127
	v_cvt_pk_bf16_f32 v16, v131, v135
	v_cvt_pk_bf16_f32 v19, v59, v60
	v_fmac_f32_e32 v51, v50, v52
	s_waitcnt lgkmcnt(0)
	v_mfma_f32_32x32x16_bf16 v[34:49], v[28:31], v[24:27], v[34:49]
	ds_read_b128 v[28:31], v162 offset:61440
	s_waitcnt lgkmcnt(0)
	v_mfma_f32_32x32x16_bf16 v[0:15], v[28:31], v[24:27], v[0:15]
	ds_read_b128 v[24:27], v161 offset:57344
	s_waitcnt lgkmcnt(0)
	v_mfma_f32_32x32x16_bf16 v[34:49], v[24:27], v[20:23], v[34:49]
	ds_read_b128 v[24:27], v161 offset:61440
	s_waitcnt lgkmcnt(0)
	v_mfma_f32_32x32x16_bf16 v[0:15], v[24:27], v[20:23], v[0:15]
	ds_read_b128 v[20:23], v160 offset:57344
	s_waitcnt vmcnt(3)
	v_mov_b32_e32 v26, v81
	s_nop 1
	v_permlane32_swap_b32_e32 v79, v26
	s_waitcnt lgkmcnt(0)
	v_mfma_f32_32x32x16_bf16 v[34:49], v[20:23], v[16:19], v[34:49]
	ds_read_b128 v[20:23], v160 offset:61440
	s_waitcnt lgkmcnt(0)
	v_mfma_f32_32x32x16_bf16 v[0:15], v[20:23], v[16:19], v[0:15]
	v_mov_b32_e32 v16, v51
	s_nop 1
	v_permlane32_swap_b32_e32 v51, v16
	v_add_f32_e32 v16, v51, v16
	v_div_scale_f32 v17, s[2:3], v16, v16, 1.0
	v_rcp_f32_e32 v18, v17
	s_nop 0
	v_fma_f32 v19, -v17, v18, 1.0
	v_fmac_f32_e32 v18, v19, v18
	v_div_scale_f32 v19, vcc, 1.0, v16, 1.0
	v_mul_f32_e32 v20, v19, v18
	v_fma_f32 v21, -v17, v20, v19
	v_fmac_f32_e32 v20, v21, v18
	v_fma_f32 v17, -v17, v20, v19
	v_div_fmas_f32 v17, v17, v18, v20
	v_div_fixup_f32 v20, v17, v16, 1.0
	v_lshlrev_b64 v[16:17], 11, v[98:99]
	v_mov_b32_e32 v21, v80
	v_lshl_add_u64 v[16:17], s[0:1], 0, v[16:17]
	s_nop 0
	v_permlane32_swap_b32_e32 v78, v21
	v_lshl_add_u64 v[22:23], v[16:17], 0, v[176:177]
	v_lshlrev_b32_e32 v16, 16, v78
	v_and_b32_e32 v17, 0xffff0000, v78
	v_mul_f32_e32 v18, v34, v20
	v_mul_f32_e32 v19, v35, v20
	v_mul_f32_e32 v24, v36, v20
	v_mul_f32_e32 v25, v37, v20
	v_mul_f32_e32 v16, v18, v16
	v_mul_f32_e32 v17, v19, v17
	v_lshlrev_b32_e32 v18, 16, v79
	v_and_b32_e32 v19, 0xffff0000, v79
	v_mul_f32_e32 v18, v24, v18
	v_mul_f32_e32 v19, v25, v19
	v_cvt_pk_bf16_f32 v16, v16, v17
	v_cvt_pk_bf16_f32 v17, v18, v19
	v_lshlrev_b32_e32 v18, 16, v21
	v_and_b32_e32 v19, 0xffff0000, v21
	v_mul_f32_e32 v24, v38, v20
	v_mul_f32_e32 v25, v39, v20
	s_nop 0
	v_mul_f32_e32 v18, v24, v18
	v_mul_f32_e32 v19, v25, v19
	v_lshlrev_b32_e32 v24, 16, v26
	v_and_b32_e32 v25, 0xffff0000, v26
	v_mul_f32_e32 v26, v40, v20
	v_mul_f32_e32 v27, v41, v20
	v_cvt_pk_bf16_f32 v18, v18, v19
	v_mul_f32_e32 v24, v26, v24
	v_mul_f32_e32 v25, v27, v25
	s_waitcnt vmcnt(2)
	v_mov_b32_e32 v21, v76
	v_cvt_pk_bf16_f32 v19, v24, v25
	v_permlane32_swap_b32_e32 v16, v18
	s_nop 0
	v_permlane32_swap_b32_e32 v17, v19
	v_permlane32_swap_b32_e32 v74, v21
	v_mov_b32_e32 v26, v77
	global_store_dwordx4 v[22:23], v[16:19], off offset:1536
	s_nop 0
	v_permlane32_swap_b32_e32 v75, v26
	v_lshlrev_b32_e32 v16, 16, v74
	v_and_b32_e32 v17, 0xffff0000, v74
	v_mul_f32_e32 v18, v42, v20
	v_mul_f32_e32 v19, v43, v20
	v_mul_f32_e32 v24, v44, v20
	v_mul_f32_e32 v25, v45, v20
	v_mul_f32_e32 v16, v18, v16
	v_mul_f32_e32 v17, v19, v17
	v_lshlrev_b32_e32 v18, 16, v75
	v_and_b32_e32 v19, 0xffff0000, v75
	v_mul_f32_e32 v18, v24, v18
	v_mul_f32_e32 v19, v25, v19
	v_cvt_pk_bf16_f32 v16, v16, v17
	v_cvt_pk_bf16_f32 v17, v18, v19
	v_lshlrev_b32_e32 v18, 16, v21
	v_and_b32_e32 v19, 0xffff0000, v21
	v_mul_f32_e32 v24, v46, v20
	v_mul_f32_e32 v25, v47, v20
	v_mul_f32_e32 v0, v0, v20
	v_mul_f32_e32 v1, v1, v20
	v_mul_f32_e32 v18, v24, v18
	v_mul_f32_e32 v19, v25, v19
	v_lshlrev_b32_e32 v24, 16, v26
	v_and_b32_e32 v25, 0xffff0000, v26
	v_mul_f32_e32 v26, v48, v20
	v_mul_f32_e32 v27, v49, v20
	v_cvt_pk_bf16_f32 v18, v18, v19
	v_mul_f32_e32 v24, v26, v24
	v_mul_f32_e32 v25, v27, v25
	s_nop 0
	v_permlane32_swap_b32_e32 v16, v18
	v_cvt_pk_bf16_f32 v19, v24, v25
	s_nop 1
	v_permlane32_swap_b32_e32 v17, v19
	global_store_dwordx4 v[22:23], v[16:19], off offset:1568
	v_mul_f32_e32 v2, v2, v20
	v_mul_f32_e32 v3, v3, v20
	v_mul_f32_e32 v4, v4, v20
	v_mul_f32_e32 v5, v5, v20
	s_waitcnt vmcnt(3)
	v_mov_b32_e32 v18, v72
	s_nop 1
	v_permlane32_swap_b32_e32 v70, v18
	v_mov_b32_e32 v19, v73
	s_nop 1
	v_permlane32_swap_b32_e32 v71, v19
	v_lshlrev_b32_e32 v16, 16, v70
	v_and_b32_e32 v17, 0xffff0000, v70
	v_mul_f32_e32 v0, v0, v16
	v_mul_f32_e32 v1, v1, v17
	v_lshlrev_b32_e32 v16, 16, v71
	v_and_b32_e32 v17, 0xffff0000, v71
	v_mul_f32_e32 v2, v2, v16
	v_mul_f32_e32 v3, v3, v17
	v_cvt_pk_bf16_f32 v0, v0, v1
	v_cvt_pk_bf16_f32 v1, v2, v3
	v_lshlrev_b32_e32 v2, 16, v18
	v_and_b32_e32 v3, 0xffff0000, v18
	v_mul_f32_e32 v2, v4, v2
	v_mul_f32_e32 v3, v5, v3
	v_lshlrev_b32_e32 v4, 16, v19
	v_and_b32_e32 v5, 0xffff0000, v19
	v_mul_f32_e32 v6, v6, v20
	v_mul_f32_e32 v7, v7, v20
	v_cvt_pk_bf16_f32 v2, v2, v3
	v_mul_f32_e32 v4, v6, v4
	v_mul_f32_e32 v5, v7, v5
	s_waitcnt vmcnt(2)
	v_mov_b32_e32 v6, v68
	v_cvt_pk_bf16_f32 v3, v4, v5
	v_permlane32_swap_b32_e32 v0, v2
	s_nop 0
	v_permlane32_swap_b32_e32 v1, v3
	v_permlane32_swap_b32_e32 v66, v6
	v_mov_b32_e32 v7, v69
	global_store_dwordx4 v[22:23], v[0:3], off offset:1600
	s_nop 0
	v_permlane32_swap_b32_e32 v67, v7
	v_lshlrev_b32_e32 v0, 16, v66
	v_and_b32_e32 v1, 0xffff0000, v66
	v_mul_f32_e32 v2, v8, v20
	v_mul_f32_e32 v3, v9, v20
	v_mul_f32_e32 v4, v10, v20
	v_mul_f32_e32 v5, v11, v20
	v_mul_f32_e32 v0, v2, v0
	v_mul_f32_e32 v1, v3, v1
	v_lshlrev_b32_e32 v2, 16, v67
	v_and_b32_e32 v3, 0xffff0000, v67
	v_mul_f32_e32 v2, v4, v2
	v_mul_f32_e32 v3, v5, v3
	v_cvt_pk_bf16_f32 v0, v0, v1
	v_cvt_pk_bf16_f32 v1, v2, v3
	v_lshlrev_b32_e32 v2, 16, v6
	v_and_b32_e32 v3, 0xffff0000, v6
	v_mul_f32_e32 v4, v12, v20
	v_mul_f32_e32 v5, v13, v20
	s_nop 0
	v_mul_f32_e32 v2, v4, v2
	v_mul_f32_e32 v3, v5, v3
	v_lshlrev_b32_e32 v4, 16, v7
	v_and_b32_e32 v5, 0xffff0000, v7
	v_mul_f32_e32 v6, v14, v20
	v_mul_f32_e32 v7, v15, v20
	v_cvt_pk_bf16_f32 v2, v2, v3
	v_mul_f32_e32 v4, v6, v4
	v_mul_f32_e32 v5, v7, v5
	s_nop 0
	v_permlane32_swap_b32_e32 v0, v2
	v_cvt_pk_bf16_f32 v3, v4, v5
	s_nop 1
	v_permlane32_swap_b32_e32 v1, v3
	global_store_dwordx4 v[22:23], v[0:3], off offset:1632
	s_cbranch_scc1 .LBB0_907

.LBB0_919:
	s_or_b64 exec, exec, s[6:7]
	ds_read_b128 v[160:163], v154
	ds_read_b128 v[164:167], v155
	ds_read_b128 v[168:171], v159
	v_mov_b32_e32 v197, v196
	v_mov_b32_e32 v193, v177
	s_add_i32 s8, s8, s5
	s_waitcnt lgkmcnt(0)
	v_lshlrev_b32_e32 v154, 16, v160
	v_and_b32_e32 v155, 0xffff0000, v160
	v_add_f32_e32 v154, v222, v154
	v_add_f32_e32 v155, v223, v155
	v_lshlrev_b32_e32 v158, 16, v164
	v_and_b32_e32 v159, 0xffff0000, v164
	v_add_f32_e32 v154, v154, v158
	v_add_f32_e32 v155, v155, v159
	v_lshlrev_b32_e32 v158, 16, v168
	v_and_b32_e32 v159, 0xffff0000, v168
	v_add_f32_e32 v154, v154, v158
	v_add_f32_e32 v155, v155, v159
	v_lshlrev_b32_e32 v158, 16, v161
	v_and_b32_e32 v159, 0xffff0000, v161
	v_add_f32_e32 v148, v148, v158
	v_add_f32_e32 v149, v149, v159
	v_lshlrev_b32_e32 v158, 16, v165
	v_and_b32_e32 v159, 0xffff0000, v165
	v_add_f32_e32 v148, v148, v158
	v_add_f32_e32 v149, v149, v159
	v_lshlrev_b32_e32 v158, 16, v169
	v_and_b32_e32 v159, 0xffff0000, v169
	v_add_f32_e32 v148, v148, v158
	v_add_f32_e32 v149, v149, v159
	v_fma_f32 v154, v196, v154, -v206
	v_fma_f32 v155, v197, v155, -v207
	v_fma_f32 v144, v196, v148, -v144
	v_fma_f32 v145, v197, v149, -v145
	v_cvt_pk_bf16_f32 v154, v154, v155
	v_cvt_pk_bf16_f32 v155, v144, v145
	v_lshlrev_b32_e32 v144, 16, v162
	v_and_b32_e32 v145, 0xffff0000, v162
	v_add_f32_e32 v144, v156, v144
	v_add_f32_e32 v145, v157, v145
	v_lshlrev_b32_e32 v148, 16, v166
	v_and_b32_e32 v149, 0xffff0000, v166
	v_add_f32_e32 v144, v144, v148
	v_add_f32_e32 v145, v145, v149
	v_lshlrev_b32_e32 v148, 16, v170
	v_and_b32_e32 v149, 0xffff0000, v170
	v_add_f32_e32 v144, v144, v148
	v_add_f32_e32 v145, v145, v149
	v_lshlrev_b32_e32 v148, 16, v167
	v_fma_f32 v144, v196, v144, -v152
	v_fma_f32 v145, v197, v145, -v153
	v_and_b32_e32 v149, 0xffff0000, v167
	v_cvt_pk_bf16_f32 v156, v144, v145
	v_lshlrev_b32_e32 v144, 16, v163
	v_and_b32_e32 v145, 0xffff0000, v163
	v_add_f32_e32 v144, v150, v144
	v_add_f32_e32 v145, v151, v145
	v_lshlrev_b32_e32 v152, 16, v171
	v_add_f32_e32 v144, v144, v148
	v_add_f32_e32 v145, v145, v149
	v_and_b32_e32 v153, 0xffff0000, v171
	v_mfma_f32_16x16x32_bf16 v[148:151], v[48:51], v[140:143], 0
	v_add_f32_e64 v144, v144, v152
	v_add_f32_e64 v145, v145, v153
	v_lshl_add_u64 v[152:153], v[194:195], 0, v[192:193]
	v_fma_f32 v144, v196, v144, -v146
	v_fma_f32 v145, v197, v145, -v147
	v_mfma_f32_16x16x32_bf16 v[158:161], v[72:75], v[140:143], 0
	v_cvt_pk_bf16_f32 v157, v144, v145
	s_and_b64 vcc, exec, s[0:1]
	s_mov_b32 s6, s9
	v_mfma_f32_16x16x32_bf16 v[144:147], v[52:55], v[154:157], v[148:151]
	v_mfma_f32_16x16x32_bf16 v[148:151], v[64:67], v[140:143], 0
	v_mfma_f32_16x16x32_bf16 v[140:143], v[88:91], v[140:143], 0
	s_nop 5
	v_mul_f32_e64 v144, v60, v144
	v_mul_f32_e64 v145, v61, v145
	v_mul_f32_e32 v146, v62, v146
	v_mul_f32_e32 v147, v63, v147
	v_mfma_f32_16x16x32_bf16 v[148:151], v[68:71], v[154:157], v[148:151]
	v_mfma_f32_16x16x32_bf16 v[158:161], v[76:79], v[154:157], v[158:161]
	v_mfma_f32_16x16x32_bf16 v[140:143], v[92:95], v[154:157], v[140:143]
	v_lshlrev_b32_e32 v154, 16, v120
	v_and_b32_e32 v155, 0xffff0000, v120
	v_mul_f32_e32 v144, v144, v154
	v_mul_f32_e32 v145, v145, v155
	s_nop 0
	v_cvt_pk_bf16_f32 v120, v144, v145
	v_lshlrev_b32_e32 v144, 16, v121
	v_and_b32_e32 v145, 0xffff0000, v121
	v_mul_f32_e32 v144, v146, v144
	v_mul_f32_e32 v145, v147, v145
	v_mul_f32_e32 v146, v56, v148
	v_mul_f32_e32 v147, v57, v149
	v_lshlrev_b32_e32 v148, 16, v122
	v_and_b32_e32 v149, 0xffff0000, v122
	v_mul_f32_e32 v146, v146, v148
	v_mul_f32_e32 v147, v147, v149
	v_cvt_pk_bf16_f32 v121, v144, v145
	v_mul_f32_e32 v144, v58, v150
	v_mul_f32_e32 v145, v59, v151
	v_cvt_pk_bf16_f32 v122, v146, v147
	v_lshlrev_b32_e32 v146, 16, v123
	v_and_b32_e32 v147, 0xffff0000, v123
	v_mul_f32_e32 v144, v144, v146
	v_mul_f32_e32 v145, v145, v147
	s_nop 0
	v_cvt_pk_bf16_f32 v123, v144, v145
	global_store_dwordx4 v[152:153], v[120:123], off
	v_lshlrev_b32_e32 v144, 16, v112
	v_and_b32_e32 v145, 0xffff0000, v112
	v_mul_f32_e32 v122, v84, v158
	v_mul_f32_e32 v123, v85, v159
	v_mul_f32_e32 v120, v86, v160
	v_mul_f32_e32 v121, v87, v161
	v_mul_f32_e32 v122, v122, v144
	v_mul_f32_e32 v123, v123, v145
	s_waitcnt vmcnt(6)
	v_mov_b64_e32 v[146:147], v[126:127]
	v_cvt_pk_bf16_f32 v112, v122, v123
	v_lshlrev_b32_e32 v122, 16, v113
	v_and_b32_e32 v123, 0xffff0000, v113
	v_mul_f32_e32 v120, v120, v122
	v_mul_f32_e32 v121, v121, v123
	v_mul_f32_e32 v122, v80, v140
	v_mul_f32_e32 v123, v81, v141
	v_lshlrev_b32_e32 v140, 16, v114
	v_and_b32_e32 v141, 0xffff0000, v114
	v_mul_f32_e32 v122, v122, v140
	v_mul_f32_e32 v123, v123, v141
	v_cvt_pk_bf16_f32 v113, v120, v121
	v_mul_f32_e32 v120, v82, v142
	v_mul_f32_e32 v121, v83, v143
	v_cvt_pk_bf16_f32 v114, v122, v123
	v_lshlrev_b32_e32 v122, 16, v115
	v_and_b32_e32 v123, 0xffff0000, v115
	v_mul_f32_e32 v120, v120, v122
	v_mul_f32_e32 v121, v121, v123
	s_waitcnt vmcnt(5)
	v_mov_b64_e32 v[142:143], v[130:131]
	v_cvt_pk_bf16_f32 v115, v120, v121
	global_store_dwordx4 v[152:153], v[112:115], off offset:64
	s_waitcnt vmcnt(5)
	v_mov_b64_e32 v[120:121], v[132:133]
	v_mov_b64_e32 v[144:145], v[124:125]
	s_waitcnt vmcnt(4)
	v_mov_b64_e32 v[112:113], v[136:137]
	v_mov_b64_e32 v[140:141], v[128:129]
	v_mov_b64_e32 v[122:123], v[134:135]
	v_mov_b64_e32 v[114:115], v[138:139]
	s_cbranch_vccnz .LBB0_938

.LBB0_930:
	s_or_b64 exec, exec, s[2:3]
	v_or_b32_e32 v124, s7, v188
	v_mad_i64_i32 v[132:133], s[2:3], v124, s33, v[190:191]
	v_lshl_add_u64 v[128:129], v[132:133], 0, v[184:185]
	v_lshl_add_u64 v[136:137], v[132:133], 0, v[182:183]
	global_load_dwordx4 v[124:127], v[128:129], off offset:512
	s_nop 0
	global_load_dwordx4 v[128:131], v[128:129], off offset:576
	s_nop 0
	global_load_dwordx4 v[132:135], v[136:137], off offset:512
	s_nop 0
	global_load_dwordx4 v[136:139], v[136:137], off offset:576
	s_cmpk_lt_i32 s6, 0x200
	s_cselect_b32 s2, s89, 0x1000
	s_add_i32 s3, s2, -1
	s_waitcnt lgkmcnt(0)
	s_barrier
	s_and_b32 s3, s3, s8
	v_or_b32_e32 v158, s3, v188
	v_add_u32_e32 v159, v243, v178
	s_and_saveexec_b64 s[6:7], s[36:37]
	s_xor_b64 s[6:7], exec, s[6:7]
	s_cbranch_execz .LBB0_932
	v_add_u32_e32 v148, 2, v158
	v_min_u32_e32 v148, s2, v148
	v_sub_u32_e64 v149, v158, 2 clamp
	v_sub_u32_e32 v148, v148, v149
	v_cvt_f32_i32_e32 v148, v148
	v_div_scale_f32 v149, s[10:11], v148, v148, 1.0
	v_rcp_f32_e32 v150, v149
	s_nop 0
	v_fma_f32 v151, -v149, v150, 1.0
	v_fmac_f32_e32 v150, v151, v150
	v_div_scale_f32 v151, vcc, 1.0, v148, 1.0
	v_mul_f32_e32 v152, v151, v150
	v_fma_f32 v153, -v149, v152, v151
	v_fmac_f32_e32 v152, v153, v150
	v_fma_f32 v149, -v149, v152, v151
	v_div_fmas_f32 v149, v149, v150, v152
	v_div_fixup_f32 v156, v149, v148, 1.0
	ds_read_b128 v[148:151], v159 offset:3296
	ds_read_b128 v[152:155], v159 offset:3824
	ds_read_b128 v[160:163], v159 offset:4352
	ds_read_b128 v[164:167], v159 offset:4880
	s_waitcnt lgkmcnt(0)
	v_lshlrev_b32_e32 v168, 16, v148
	v_and_b32_e32 v169, 0xffff0000, v148
	v_add_f32_e32 v168, 0, v168
	v_add_f32_e32 v169, 0, v169
	v_lshlrev_b32_e32 v170, 16, v152
	v_and_b32_e32 v171, 0xffff0000, v152
	v_add_f32_e32 v168, v168, v170
	v_add_f32_e32 v169, v169, v171
	v_lshlrev_b32_e32 v170, 16, v160
	v_and_b32_e32 v171, 0xffff0000, v160
	v_add_f32_e32 v168, v168, v170
	v_add_f32_e32 v169, v169, v171
	v_lshlrev_b32_e32 v172, 16, v164
	v_and_b32_e32 v173, 0xffff0000, v164
	v_add_f32_e32 v168, v168, v172
	v_add_f32_e32 v169, v169, v173
	v_lshlrev_b32_e32 v152, 16, v153
	v_fma_f32 v168, v156, v168, -v170
	v_fma_f32 v169, v156, v169, -v171
	v_cvt_pk_bf16_f32 v148, v168, v169
	v_lshlrev_b32_e32 v168, 16, v149
	v_and_b32_e32 v169, 0xffff0000, v149
	v_add_f32_e32 v168, 0, v168
	v_add_f32_e32 v169, 0, v169
	v_and_b32_e32 v153, 0xffff0000, v153
	v_add_f32_e32 v152, v168, v152
	v_add_f32_e32 v153, v169, v153
	v_lshlrev_b32_e32 v160, 16, v161
	v_and_b32_e32 v161, 0xffff0000, v161
	v_add_f32_e32 v152, v152, v160
	v_add_f32_e32 v153, v153, v161
	v_lshlrev_b32_e32 v164, 16, v165
	v_and_b32_e32 v165, 0xffff0000, v165
	v_add_f32_e32 v152, v152, v164
	v_add_f32_e32 v153, v153, v165
	v_lshlrev_b32_e32 v164, 16, v166
	v_fma_f32 v152, v156, v152, -v160
	v_fma_f32 v153, v156, v153, -v161
	v_cvt_pk_bf16_f32 v149, v152, v153
	v_lshlrev_b32_e32 v152, 16, v150
	v_and_b32_e32 v153, 0xffff0000, v150
	v_add_f32_e32 v152, 0, v152
	v_add_f32_e32 v153, 0, v153
	v_lshlrev_b32_e32 v160, 16, v154
	v_and_b32_e32 v161, 0xffff0000, v154
	v_add_f32_e32 v152, v152, v160
	v_add_f32_e32 v153, v153, v161
	v_lshlrev_b32_e32 v160, 16, v162
	v_and_b32_e32 v161, 0xffff0000, v162
	v_add_f32_e32 v152, v152, v160
	v_add_f32_e32 v153, v153, v161
	v_and_b32_e32 v165, 0xffff0000, v166
	v_add_f32_e32 v152, v152, v164
	v_add_f32_e32 v153, v153, v165
	v_lshlrev_b32_e32 v154, 16, v155
	v_fma_f32 v152, v156, v152, -v160
	v_fma_f32 v153, v156, v153, -v161
	v_cvt_pk_bf16_f32 v150, v152, v153
	v_lshlrev_b32_e32 v152, 16, v151
	v_and_b32_e32 v153, 0xffff0000, v151
	v_add_f32_e32 v152, 0, v152
	v_add_f32_e32 v153, 0, v153
	v_and_b32_e32 v155, 0xffff0000, v155
	v_add_f32_e32 v152, v152, v154
	v_add_f32_e32 v153, v153, v155
	v_lshlrev_b32_e32 v154, 16, v163
	v_and_b32_e32 v155, 0xffff0000, v163
	v_add_f32_e32 v152, v152, v154
	v_add_f32_e32 v153, v153, v155
	v_lshlrev_b32_e32 v160, 16, v167
	v_and_b32_e32 v161, 0xffff0000, v167
	v_add_f32_e32 v152, v152, v160
	v_add_f32_e32 v153, v153, v161
	s_nop 0
	v_fma_f32 v152, v156, v152, -v154
	v_fma_f32 v153, v156, v153, -v155
	v_cvt_pk_bf16_f32 v151, v152, v153
	ds_read_b128 v[152:155], v159 offset:3360
	ds_read_b128 v[160:163], v159 offset:3888
	ds_read_b128 v[164:167], v159 offset:4416
	ds_read_b128 v[168:171], v159 offset:4944
	s_waitcnt lgkmcnt(3)
	v_lshlrev_b32_e32 v172, 16, v152
	v_and_b32_e32 v173, 0xffff0000, v152
	v_add_f32_e32 v172, 0, v172
	v_add_f32_e32 v173, 0, v173
	s_waitcnt lgkmcnt(2)
	v_lshlrev_b32_e32 v174, 16, v160
	v_and_b32_e32 v175, 0xffff0000, v160
	v_add_f32_e32 v172, v172, v174
	v_add_f32_e32 v173, v173, v175
	s_waitcnt lgkmcnt(1)
	v_lshlrev_b32_e32 v174, 16, v164
	v_and_b32_e32 v175, 0xffff0000, v164
	v_add_f32_e32 v172, v172, v174
	v_add_f32_e32 v173, v173, v175
	s_waitcnt lgkmcnt(0)
	v_lshlrev_b32_e32 v194, 16, v168
	v_and_b32_e32 v195, 0xffff0000, v168
	v_add_f32_e32 v172, v172, v194
	v_add_f32_e32 v173, v173, v195
	v_lshlrev_b32_e32 v160, 16, v161
	v_fma_f32 v172, v156, v172, -v174
	v_fma_f32 v173, v156, v173, -v175
	v_cvt_pk_bf16_f32 v152, v172, v173
	v_lshlrev_b32_e32 v172, 16, v153
	v_and_b32_e32 v173, 0xffff0000, v153
	v_add_f32_e32 v172, 0, v172
	v_add_f32_e32 v173, 0, v173
	v_and_b32_e32 v161, 0xffff0000, v161
	v_add_f32_e32 v160, v172, v160
	v_add_f32_e32 v161, v173, v161
	v_lshlrev_b32_e32 v164, 16, v165
	v_and_b32_e32 v165, 0xffff0000, v165
	v_add_f32_e32 v160, v160, v164
	v_add_f32_e32 v161, v161, v165
	v_lshlrev_b32_e32 v168, 16, v169
	v_and_b32_e32 v169, 0xffff0000, v169
	v_add_f32_e32 v160, v160, v168
	v_add_f32_e32 v161, v161, v169
	v_lshlrev_b32_e32 v168, 16, v170
	v_fma_f32 v160, v156, v160, -v164
	v_fma_f32 v161, v156, v161, -v165
	v_cvt_pk_bf16_f32 v153, v160, v161
	v_lshlrev_b32_e32 v160, 16, v154
	v_and_b32_e32 v161, 0xffff0000, v154
	v_add_f32_e32 v160, 0, v160
	v_add_f32_e32 v161, 0, v161
	v_lshlrev_b32_e32 v164, 16, v162
	v_and_b32_e32 v165, 0xffff0000, v162
	v_add_f32_e32 v160, v160, v164
	v_add_f32_e32 v161, v161, v165
	v_lshlrev_b32_e32 v164, 16, v166
	v_and_b32_e32 v165, 0xffff0000, v166
	v_add_f32_e32 v160, v160, v164
	v_add_f32_e32 v161, v161, v165
	v_and_b32_e32 v169, 0xffff0000, v170
	v_add_f32_e32 v160, v160, v168
	v_add_f32_e32 v161, v161, v169
	v_lshlrev_b32_e32 v162, 16, v163
	v_fma_f32 v160, v156, v160, -v164
	v_fma_f32 v161, v156, v161, -v165
	v_cvt_pk_bf16_f32 v154, v160, v161
	v_lshlrev_b32_e32 v160, 16, v155
	v_and_b32_e32 v161, 0xffff0000, v155
	v_add_f32_e32 v160, 0, v160
	v_add_f32_e32 v161, 0, v161
	v_and_b32_e32 v163, 0xffff0000, v163
	v_add_f32_e32 v160, v160, v162
	v_add_f32_e32 v161, v161, v163
	v_lshlrev_b32_e32 v162, 16, v167
	v_and_b32_e32 v163, 0xffff0000, v167
	v_add_f32_e32 v160, v160, v162
	v_add_f32_e32 v161, v161, v163
	v_lshlrev_b32_e32 v164, 16, v171
	v_and_b32_e32 v165, 0xffff0000, v171
	v_add_f32_e32 v160, v160, v164
	v_add_f32_e32 v161, v161, v165
	s_nop 0
	v_fma_f32 v157, v156, v161, -v163
	v_fma_f32 v156, v156, v160, -v162
.LBB0_932:
	s_andn2_saveexec_b64 s[6:7], s[6:7]
	s_cbranch_execz .LBB0_934
	v_add_u32_e32 v148, 1, v158
	v_min_u32_e32 v148, s2, v148
	v_sub_u32_e64 v149, v158, 1 clamp
	v_sub_u32_e32 v148, v148, v149
	v_cvt_f32_i32_e32 v148, v148
	v_div_scale_f32 v149, s[10:11], v148, v148, 1.0
	v_rcp_f32_e32 v150, v149
	s_nop 0
	v_fma_f32 v151, -v149, v150, 1.0
	v_fmac_f32_e32 v150, v151, v150
	v_div_scale_f32 v151, vcc, 1.0, v148, 1.0
	v_mul_f32_e32 v152, v151, v150
	v_fma_f32 v153, -v149, v152, v151
	v_fmac_f32_e32 v152, v153, v150
	v_fma_f32 v149, -v149, v152, v151
	v_div_fmas_f32 v149, v149, v150, v152
	v_div_fixup_f32 v156, v149, v148, 1.0
	ds_read_b128 v[148:151], v159 offset:3696
	ds_read_b128 v[152:155], v159 offset:4224
	s_waitcnt lgkmcnt(0)
	v_lshlrev_b32_e32 v160, 16, v148
	v_and_b32_e32 v161, 0xffff0000, v148
	v_add_f32_e32 v160, 0, v160
	v_add_f32_e32 v161, 0, v161
	v_lshlrev_b32_e32 v162, 16, v152
	v_and_b32_e32 v163, 0xffff0000, v152
	v_add_f32_e32 v160, v160, v162
	v_add_f32_e32 v161, v161, v163
	v_lshlrev_b32_e32 v152, 16, v153
	v_fma_f32 v160, v156, v160, -v162
	v_fma_f32 v161, v156, v161, -v163
	v_cvt_pk_bf16_f32 v148, v160, v161
	v_lshlrev_b32_e32 v160, 16, v149
	v_and_b32_e32 v161, 0xffff0000, v149
	v_add_f32_e32 v160, 0, v160
	v_add_f32_e32 v161, 0, v161
	v_and_b32_e32 v153, 0xffff0000, v153
	v_add_f32_e32 v160, v160, v152
	v_add_f32_e32 v161, v161, v153
	s_nop 0
	v_fma_f32 v152, v156, v160, -v152
	v_fma_f32 v153, v156, v161, -v153
	v_cvt_pk_bf16_f32 v149, v152, v153
	v_lshlrev_b32_e32 v152, 16, v150
	v_and_b32_e32 v153, 0xffff0000, v150
	v_add_f32_e32 v152, 0, v152
	v_add_f32_e32 v153, 0, v153
	v_lshlrev_b32_e32 v160, 16, v154
	v_and_b32_e32 v161, 0xffff0000, v154
	v_add_f32_e32 v152, v152, v160
	v_add_f32_e32 v153, v153, v161
	v_lshlrev_b32_e32 v154, 16, v155
	v_fma_f32 v152, v156, v152, -v160
	v_fma_f32 v153, v156, v153, -v161
	v_cvt_pk_bf16_f32 v150, v152, v153
	v_lshlrev_b32_e32 v152, 16, v151
	v_and_b32_e32 v153, 0xffff0000, v151
	v_add_f32_e32 v152, 0, v152
	v_add_f32_e32 v153, 0, v153
	v_and_b32_e32 v155, 0xffff0000, v155
	v_add_f32_e32 v152, v152, v154
	v_add_f32_e32 v153, v153, v155
	s_nop 0
	v_fma_f32 v152, v156, v152, -v154
	v_fma_f32 v153, v156, v153, -v155
	v_cvt_pk_bf16_f32 v151, v152, v153
	ds_read_b128 v[152:155], v159 offset:3760
	ds_read_b128 v[160:163], v159 offset:4288
	s_waitcnt lgkmcnt(1)
	v_lshlrev_b32_e32 v164, 16, v152
	v_and_b32_e32 v165, 0xffff0000, v152
	v_add_f32_e32 v164, 0, v164
	v_add_f32_e32 v165, 0, v165
	s_waitcnt lgkmcnt(0)
	v_lshlrev_b32_e32 v166, 16, v160
	v_and_b32_e32 v167, 0xffff0000, v160
	v_add_f32_e32 v164, v164, v166
	v_add_f32_e32 v165, v165, v167
	v_lshlrev_b32_e32 v160, 16, v161
	v_fma_f32 v164, v156, v164, -v166
	v_fma_f32 v165, v156, v165, -v167
	v_cvt_pk_bf16_f32 v152, v164, v165
	v_lshlrev_b32_e32 v164, 16, v153
	v_and_b32_e32 v165, 0xffff0000, v153
	v_add_f32_e32 v164, 0, v164
	v_add_f32_e32 v165, 0, v165
	v_and_b32_e32 v161, 0xffff0000, v161
	v_add_f32_e32 v164, v164, v160
	v_add_f32_e32 v165, v165, v161
	s_nop 0
	v_fma_f32 v160, v156, v164, -v160
	v_fma_f32 v161, v156, v165, -v161
	v_cvt_pk_bf16_f32 v153, v160, v161
	v_lshlrev_b32_e32 v160, 16, v154
	v_and_b32_e32 v161, 0xffff0000, v154
	v_add_f32_e32 v160, 0, v160
	v_add_f32_e32 v161, 0, v161
	v_lshlrev_b32_e32 v164, 16, v162
	v_and_b32_e32 v165, 0xffff0000, v162
	v_add_f32_e32 v160, v160, v164
	v_add_f32_e32 v161, v161, v165
	v_lshlrev_b32_e32 v162, 16, v163
	v_fma_f32 v160, v156, v160, -v164
	v_fma_f32 v161, v156, v161, -v165
	v_cvt_pk_bf16_f32 v154, v160, v161
	v_lshlrev_b32_e32 v160, 16, v155
	v_and_b32_e32 v161, 0xffff0000, v155
	v_add_f32_e32 v160, 0, v160
	v_add_f32_e32 v161, 0, v161
	v_and_b32_e32 v163, 0xffff0000, v163
	v_add_f32_e32 v160, v160, v162
	v_add_f32_e32 v161, v161, v163
	s_nop 0
	v_fma_f32 v157, v156, v161, -v163
	v_fma_f32 v156, v156, v160, -v162
.LBB0_934:
	s_or_b64 exec, exec, s[6:7]
	s_ashr_i32 s3, s8, 31
	v_mov_b32_e32 v161, s3
	v_or_b32_e32 v160, s8, v188
	v_lshlrev_b64 v[160:161], 11, v[160:161]
	v_lshl_add_u64 v[194:195], v[186:187], 0, v[160:161]
	v_mfma_f32_16x16x32_bf16 v[160:163], v[0:3], v[148:151], 0
	v_cvt_pk_bf16_f32 v155, v156, v157
	v_mfma_f32_16x16x32_bf16 v[164:167], v[16:19], v[148:151], 0
	s_nop 0
	v_mfma_f32_16x16x32_bf16 v[160:163], v[4:7], v[152:155], v[160:163]
	v_mfma_f32_16x16x32_bf16 v[168:171], v[24:27], v[148:151], 0
	v_mfma_f32_16x16x32_bf16 v[148:151], v[40:43], v[148:151], 0
	s_nop 5
	v_mul_f32_e64 v156, v12, v160
	v_mul_f32_e64 v157, v13, v161
	v_lshlrev_b32_e32 v160, 16, v144
	v_and_b32_e32 v161, 0xffff0000, v144
	v_mfma_f32_16x16x32_bf16 v[164:167], v[20:23], v[152:155], v[164:167]
	v_mul_f32_e64 v156, v156, v160
	v_mul_f32_e64 v157, v157, v161
	v_lshlrev_b32_e32 v160, 16, v146
	v_cvt_pk_bf16_f32 v144, v156, v157
	v_mfma_f32_16x16x32_bf16 v[168:171], v[28:31], v[152:155], v[168:171]
	v_lshlrev_b32_e32 v156, 16, v145
	v_and_b32_e32 v157, 0xffff0000, v145
	v_and_b32_e32 v161, 0xffff0000, v146
	v_mfma_f32_16x16x32_bf16 v[148:151], v[44:47], v[152:155], v[148:151]
	v_mul_f32_e64 v154, v14, v162
	v_mul_f32_e64 v155, v15, v163
	v_lshl_add_u64 v[152:153], v[194:195], 0, v[176:177]
	v_mul_f32_e32 v154, v154, v156
	v_mul_f32_e32 v155, v155, v157
	v_mul_f32_e32 v156, v8, v164
	v_mul_f32_e32 v157, v9, v165
	v_cvt_pk_bf16_f32 v145, v154, v155
	v_mul_f32_e32 v156, v156, v160
	v_mul_f32_e32 v157, v157, v161
	v_mul_f32_e32 v154, v10, v166
	v_mul_f32_e32 v155, v11, v167
	v_cvt_pk_bf16_f32 v146, v156, v157
	v_lshlrev_b32_e32 v156, 16, v147
	v_and_b32_e32 v157, 0xffff0000, v147
	v_mul_f32_e32 v154, v154, v156
	v_mul_f32_e32 v155, v155, v157
	s_nop 0
	v_cvt_pk_bf16_f32 v147, v154, v155
	global_store_dwordx4 v[152:153], v[144:147], off
	v_lshlrev_b32_e32 v154, 16, v140
	v_and_b32_e32 v155, 0xffff0000, v140
	v_mul_f32_e32 v146, v36, v168
	v_mul_f32_e32 v147, v37, v169
	v_mul_f32_e32 v144, v38, v170
	v_mul_f32_e32 v145, v39, v171
	v_mul_f32_e32 v146, v146, v154
	v_mul_f32_e32 v147, v147, v155
	s_nop 0
	v_cvt_pk_bf16_f32 v140, v146, v147
	v_lshlrev_b32_e32 v146, 16, v141
	v_and_b32_e32 v147, 0xffff0000, v141
	v_mul_f32_e32 v144, v144, v146
	v_mul_f32_e32 v145, v145, v147
	v_mul_f32_e32 v146, v32, v148
	v_mul_f32_e32 v147, v33, v149
	v_lshlrev_b32_e32 v148, 16, v142
	v_and_b32_e32 v149, 0xffff0000, v142
	v_mul_f32_e32 v146, v146, v148
	v_mul_f32_e32 v147, v147, v149
	v_cvt_pk_bf16_f32 v141, v144, v145
	v_mul_f32_e32 v144, v34, v150
	v_mul_f32_e32 v145, v35, v151
	v_cvt_pk_bf16_f32 v142, v146, v147
	v_lshlrev_b32_e32 v146, 16, v143
	v_and_b32_e32 v147, 0xffff0000, v143
	v_mul_f32_e32 v144, v144, v146
	v_mul_f32_e32 v145, v145, v147
	s_nop 0
	v_cvt_pk_bf16_f32 v143, v144, v145
	global_store_dwordx4 v[152:153], v[140:143], off offset:64
	s_and_saveexec_b64 s[6:7], s[36:37]
	s_xor_b64 s[6:7], exec, s[6:7]
	s_cbranch_execz .LBB0_936
	v_add_u32_e32 v140, 4, v158
	v_min_u32_e32 v140, s2, v140
	v_sub_u32_e64 v141, v158, 4 clamp
	v_sub_u32_e32 v140, v140, v141
	v_cvt_f32_i32_e32 v140, v140
	v_div_scale_f32 v141, s[10:11], v140, v140, 1.0
	v_rcp_f32_e32 v142, v141
	s_nop 0
	v_fma_f32 v143, -v141, v142, 1.0
	v_fmac_f32_e32 v142, v143, v142
	v_div_scale_f32 v143, vcc, 1.0, v140, 1.0
	v_mul_f32_e32 v144, v143, v142
	v_fma_f32 v145, -v141, v144, v143
	v_fmac_f32_e32 v144, v145, v142
	v_fma_f32 v141, -v141, v144, v143
	v_div_fmas_f32 v141, v141, v142, v144
	v_div_fixup_f32 v196, v141, v140, 1.0
	ds_read_b128 v[140:143], v244 offset:2112
	s_waitcnt lgkmcnt(0)
	v_lshlrev_b32_e32 v164, 16, v140
	v_and_b32_e32 v165, 0xffff0000, v140
	v_lshlrev_b32_e32 v166, 16, v141
	v_and_b32_e32 v167, 0xffff0000, v141
	v_lshlrev_b32_e32 v168, 16, v142
	v_and_b32_e32 v169, 0xffff0000, v142
	v_lshlrev_b32_e32 v170, 16, v143
	v_and_b32_e32 v171, 0xffff0000, v143
	ds_read_b128 v[140:143], v244 offset:2640
	v_add_f32_e32 v164, 0, v164
	v_add_f32_e32 v165, 0, v165
	s_waitcnt lgkmcnt(0)
	v_lshlrev_b32_e32 v172, 16, v140
	v_and_b32_e32 v173, 0xffff0000, v140
	v_lshlrev_b32_e32 v174, 16, v141
	v_and_b32_e32 v175, 0xffff0000, v141
	v_lshlrev_b32_e32 v198, 16, v142
	v_and_b32_e32 v199, 0xffff0000, v142
	v_lshlrev_b32_e32 v200, 16, v143
	v_and_b32_e32 v201, 0xffff0000, v143
	ds_read_b128 v[140:143], v244 offset:3168
	ds_read_b128 v[144:147], v244 offset:3696
	ds_read_b128 v[148:151], v244 offset:4224
	ds_read_b128 v[152:155], v244 offset:4752
	ds_read_b128 v[156:159], v244 offset:5280
	ds_read_b128 v[160:163], v244 offset:5808
	v_add_f32_e32 v164, v164, v172
	v_add_f32_e32 v165, v165, v173
	s_waitcnt lgkmcnt(5)
	v_lshlrev_b32_e32 v172, 16, v140
	v_and_b32_e32 v173, 0xffff0000, v140
	v_add_f32_e32 v164, v164, v172
	v_add_f32_e32 v165, v165, v173
	s_waitcnt lgkmcnt(4)
	v_lshlrev_b32_e32 v172, 16, v144
	v_and_b32_e32 v173, 0xffff0000, v144
	v_add_f32_e32 v164, v164, v172
	v_add_f32_e32 v165, v165, v173
	s_waitcnt lgkmcnt(3)
	v_lshlrev_b32_e32 v172, 16, v148
	v_and_b32_e32 v173, 0xffff0000, v148
	v_add_f32_e32 v164, v164, v172
	v_add_f32_e32 v165, v165, v173
	s_waitcnt lgkmcnt(2)
	v_lshlrev_b32_e32 v202, 16, v152
	v_and_b32_e32 v203, 0xffff0000, v152
	v_add_f32_e32 v164, v164, v202
	v_add_f32_e32 v165, v165, v203
	s_waitcnt lgkmcnt(1)
	v_lshlrev_b32_e32 v202, 16, v156
	v_and_b32_e32 v203, 0xffff0000, v156
	v_add_f32_e32 v164, v164, v202
	v_add_f32_e32 v165, v165, v203
	s_waitcnt lgkmcnt(0)
	v_lshlrev_b32_e32 v202, 16, v160
	v_and_b32_e32 v203, 0xffff0000, v160
	v_add_f32_e32 v164, v164, v202
	v_add_f32_e32 v165, v165, v203
	v_lshlrev_b32_e32 v144, 16, v145
	v_fma_f32 v164, v196, v164, -v172
	v_fma_f32 v165, v196, v165, -v173
	v_cvt_pk_bf16_f32 v140, v164, v165
	v_add_f32_e32 v164, 0, v166
	v_add_f32_e32 v165, 0, v167
	v_lshlrev_b32_e32 v166, 16, v141
	v_add_f32_e32 v164, v164, v174
	v_add_f32_e32 v165, v165, v175
	v_and_b32_e32 v167, 0xffff0000, v141
	v_add_f32_e32 v164, v164, v166
	v_add_f32_e32 v165, v165, v167
	v_and_b32_e32 v145, 0xffff0000, v145
	v_add_f32_e32 v144, v164, v144
	v_add_f32_e32 v145, v165, v145
	v_lshlrev_b32_e32 v148, 16, v149
	v_and_b32_e32 v149, 0xffff0000, v149
	v_add_f32_e32 v144, v144, v148
	v_add_f32_e32 v145, v145, v149
	v_lshlrev_b32_e32 v152, 16, v153
	v_and_b32_e32 v153, 0xffff0000, v153
	v_add_f32_e32 v144, v144, v152
	v_add_f32_e32 v145, v145, v153
	v_lshlrev_b32_e32 v152, 16, v157
	v_and_b32_e32 v153, 0xffff0000, v157
	v_add_f32_e32 v144, v144, v152
	v_add_f32_e32 v145, v145, v153
	v_lshlrev_b32_e32 v152, 16, v161
	v_and_b32_e32 v153, 0xffff0000, v161
	v_add_f32_e32 v144, v144, v152
	v_add_f32_e32 v145, v145, v153
	v_lshlrev_b32_e32 v152, 16, v154
	v_fma_f32 v144, v196, v144, -v148
	v_fma_f32 v145, v196, v145, -v149
	v_cvt_pk_bf16_f32 v141, v144, v145
	v_add_f32_e32 v144, 0, v168
	v_add_f32_e32 v145, 0, v169
	v_lshlrev_b32_e32 v148, 16, v142
	v_add_f32_e32 v144, v144, v198
	v_add_f32_e32 v145, v145, v199
	v_and_b32_e32 v149, 0xffff0000, v142
	v_add_f32_e32 v144, v144, v148
	v_add_f32_e32 v145, v145, v149
	v_lshlrev_b32_e32 v148, 16, v146
	v_and_b32_e32 v149, 0xffff0000, v146
	v_add_f32_e32 v144, v144, v148
	v_add_f32_e32 v145, v145, v149
	v_lshlrev_b32_e32 v148, 16, v150
	v_and_b32_e32 v149, 0xffff0000, v150
	v_add_f32_e32 v144, v144, v148
	v_add_f32_e32 v145, v145, v149
	v_and_b32_e32 v153, 0xffff0000, v154
	v_add_f32_e32 v144, v144, v152
	v_add_f32_e32 v145, v145, v153
	v_lshlrev_b32_e32 v152, 16, v158
	v_and_b32_e32 v153, 0xffff0000, v158
	v_add_f32_e32 v144, v144, v152
	v_add_f32_e32 v145, v145, v153
	v_lshlrev_b32_e32 v152, 16, v162
	v_and_b32_e32 v153, 0xffff0000, v162
	v_add_f32_e32 v144, v144, v152
	v_add_f32_e32 v145, v145, v153
	v_lshlrev_b32_e32 v146, 16, v147
	v_fma_f32 v144, v196, v144, -v148
	v_fma_f32 v145, v196, v145, -v149
	v_cvt_pk_bf16_f32 v142, v144, v145
	v_add_f32_e32 v144, 0, v170
	v_add_f32_e32 v145, 0, v171
	v_lshlrev_b32_e32 v148, 16, v143
	v_add_f32_e32 v144, v144, v200
	v_add_f32_e32 v145, v145, v201
	v_and_b32_e32 v149, 0xffff0000, v143
	v_add_f32_e32 v144, v144, v148
	v_add_f32_e32 v145, v145, v149
	v_and_b32_e32 v147, 0xffff0000, v147
	v_add_f32_e32 v144, v144, v146
	v_add_f32_e32 v145, v145, v147
	v_lshlrev_b32_e32 v146, 16, v151
	v_and_b32_e32 v147, 0xffff0000, v151
	v_add_f32_e32 v144, v144, v146
	v_add_f32_e32 v145, v145, v147
	v_lshlrev_b32_e32 v148, 16, v155
	v_and_b32_e32 v149, 0xffff0000, v155
	v_add_f32_e32 v144, v144, v148
	v_add_f32_e32 v145, v145, v149
	v_lshlrev_b32_e32 v148, 16, v159
	v_and_b32_e32 v149, 0xffff0000, v159
	v_add_f32_e32 v144, v144, v148
	v_add_f32_e32 v145, v145, v149
	v_lshlrev_b32_e32 v148, 16, v163
	v_and_b32_e32 v149, 0xffff0000, v163
	v_add_f32_e32 v144, v144, v148
	v_add_f32_e32 v145, v145, v149
	s_nop 0
	v_fma_f32 v144, v196, v144, -v146
	v_fma_f32 v145, v196, v145, -v147
	v_cvt_pk_bf16_f32 v143, v144, v145
	ds_read_b128 v[144:147], v244 offset:2176
	ds_read_b128 v[148:151], v244 offset:2704
	ds_read_b128 v[152:155], v244 offset:3232
	ds_read_b128 v[156:159], v244 offset:3760
	ds_read_b128 v[160:163], v244 offset:4288
	s_waitcnt lgkmcnt(4)
	v_lshlrev_b32_e32 v164, 16, v144
	v_and_b32_e32 v165, 0xffff0000, v144
	v_lshlrev_b32_e32 v144, 16, v145
	v_and_b32_e32 v145, 0xffff0000, v145
	v_add_f32_e32 v164, 0, v164
	v_add_f32_e32 v165, 0, v165
	s_waitcnt lgkmcnt(3)
	v_lshlrev_b32_e32 v166, 16, v148
	v_and_b32_e32 v167, 0xffff0000, v148
	v_add_f32_e32 v144, 0, v144
	v_add_f32_e32 v145, 0, v145
	v_lshlrev_b32_e32 v148, 16, v149
	v_and_b32_e32 v149, 0xffff0000, v149
	v_add_f32_e32 v164, v164, v166
	v_add_f32_e32 v165, v165, v167
	s_waitcnt lgkmcnt(2)
	v_lshlrev_b32_e32 v166, 16, v152
	v_and_b32_e32 v167, 0xffff0000, v152
	v_add_f32_e32 v144, v144, v148
	v_add_f32_e32 v145, v145, v149
	v_lshlrev_b32_e32 v148, 16, v153
	v_and_b32_e32 v149, 0xffff0000, v153
	v_lshlrev_b32_e32 v152, 16, v146
	v_and_b32_e32 v153, 0xffff0000, v146
	v_lshlrev_b32_e32 v146, 16, v147
	v_and_b32_e32 v147, 0xffff0000, v147
	v_add_f32_e32 v164, v164, v166
	v_add_f32_e32 v165, v165, v167
	s_waitcnt lgkmcnt(1)
	v_lshlrev_b32_e32 v166, 16, v156
	v_and_b32_e32 v167, 0xffff0000, v156
	v_add_f32_e32 v144, v144, v148
	v_add_f32_e32 v145, v145, v149
	v_lshlrev_b32_e32 v148, 16, v157
	v_and_b32_e32 v149, 0xffff0000, v157
	v_add_f32_e32 v152, 0, v152
	v_add_f32_e32 v153, 0, v153
	v_lshlrev_b32_e32 v156, 16, v150
	v_and_b32_e32 v157, 0xffff0000, v150
	v_add_f32_e32 v146, 0, v146
	v_add_f32_e32 v147, 0, v147
	v_lshlrev_b32_e32 v150, 16, v151
	v_and_b32_e32 v151, 0xffff0000, v151
	v_add_f32_e32 v152, v152, v156
	v_add_f32_e32 v153, v153, v157
	v_lshlrev_b32_e32 v156, 16, v154
	v_and_b32_e32 v157, 0xffff0000, v154
	v_add_f32_e32 v146, v146, v150
	v_add_f32_e32 v147, v147, v151
	v_lshlrev_b32_e32 v150, 16, v155
	v_and_b32_e32 v151, 0xffff0000, v155
	v_add_f32_e32 v152, v152, v156
	v_add_f32_e32 v153, v153, v157
	v_lshlrev_b32_e32 v156, 16, v158
	v_and_b32_e32 v157, 0xffff0000, v158
	v_add_f32_e32 v146, v146, v150
	v_add_f32_e32 v147, v147, v151
	v_lshlrev_b32_e32 v150, 16, v159
	v_and_b32_e32 v151, 0xffff0000, v159
	v_add_f32_e32 v164, v164, v166
	v_add_f32_e32 v165, v165, v167
	s_waitcnt lgkmcnt(0)
	v_lshlrev_b32_e32 v206, 16, v160
	v_and_b32_e32 v207, 0xffff0000, v160
	v_add_f32_e32 v148, v144, v148
	v_add_f32_e32 v149, v145, v149
	v_lshlrev_b32_e32 v144, 16, v161
	v_and_b32_e32 v145, 0xffff0000, v161
	v_add_f32_e32 v156, v152, v156
	v_add_f32_e32 v157, v153, v157
	v_lshlrev_b32_e32 v152, 16, v162
	v_and_b32_e32 v153, 0xffff0000, v162
	v_add_f32_e32 v150, v146, v150
	v_add_f32_e32 v151, v147, v151
	v_lshlrev_b32_e32 v146, 16, v163
	v_and_b32_e32 v147, 0xffff0000, v163
	v_add_f32_e32 v222, v164, v206
	v_add_f32_e32 v223, v165, v207
	v_add_f32_e32 v148, v148, v144
	v_add_f32_e32 v149, v149, v145
	v_add_f32_e32 v156, v156, v152
	v_add_f32_e32 v157, v157, v153
	v_add_f32_e32 v150, v150, v146
	v_add_f32_e32 v151, v151, v147
.LBB0_936:
	s_or_saveexec_b64 s[6:7], s[6:7]
	v_mov_b32_e32 v154, v245
	v_mov_b32_e32 v155, v246
	v_mov_b32_e32 v159, v247
	s_xor_b64 exec, exec, s[6:7]
	s_cbranch_execz .LBB0_919
	v_add_u32_e32 v140, 8, v158
	v_min_u32_e32 v140, s2, v140
	v_sub_u32_e64 v141, v158, 8 clamp
	v_sub_u32_e32 v140, v140, v141
	v_cvt_f32_i32_e32 v140, v140
	v_div_scale_f32 v141, s[2:3], v140, v140, 1.0
	v_rcp_f32_e32 v142, v141
	s_nop 0
	v_fma_f32 v143, -v141, v142, 1.0
	v_fmac_f32_e32 v142, v143, v142
	v_div_scale_f32 v143, vcc, 1.0, v140, 1.0
	v_mul_f32_e32 v144, v143, v142
	v_fma_f32 v145, -v141, v144, v143
	v_fmac_f32_e32 v144, v145, v142
	v_fma_f32 v141, -v141, v144, v143
	v_div_fmas_f32 v141, v141, v142, v144
	v_div_fixup_f32 v196, v141, v140, 1.0
	ds_read_b128 v[140:143], v244
	ds_read_b128 v[144:147], v244 offset:528
	ds_read_b128 v[148:151], v244 offset:1056
	ds_read_b128 v[152:155], v244 offset:1584
	ds_read_b128 v[156:159], v244 offset:2112
	ds_read_b128 v[160:163], v244 offset:2640
	ds_read_b128 v[164:167], v244 offset:3168
	s_waitcnt lgkmcnt(0)
	v_lshlrev_b32_e32 v168, 16, v140
	v_and_b32_e32 v169, 0xffff0000, v140
	v_lshlrev_b32_e32 v140, 16, v141
	v_and_b32_e32 v141, 0xffff0000, v141
	v_lshlrev_b32_e32 v170, 16, v144
	v_and_b32_e32 v171, 0xffff0000, v144
	v_add_f32_e32 v140, 0, v140
	v_add_f32_e32 v141, 0, v141
	v_lshlrev_b32_e32 v144, 16, v145
	v_and_b32_e32 v145, 0xffff0000, v145
	v_add_f32_e32 v168, 0, v168
	v_add_f32_e32 v169, 0, v169
	v_add_f32_e32 v140, v140, v144
	v_add_f32_e32 v141, v141, v145
	v_lshlrev_b32_e32 v144, 16, v149
	v_and_b32_e32 v145, 0xffff0000, v149
	v_add_f32_e32 v168, v168, v170
	v_add_f32_e32 v169, v169, v171
	v_lshlrev_b32_e32 v170, 16, v148
	v_and_b32_e32 v171, 0xffff0000, v148
	v_add_f32_e32 v140, v140, v144
	v_add_f32_e32 v141, v141, v145
	v_lshlrev_b32_e32 v144, 16, v153
	v_and_b32_e32 v145, 0xffff0000, v153
	v_add_f32_e32 v168, v168, v170
	v_add_f32_e32 v169, v169, v171
	v_lshlrev_b32_e32 v170, 16, v152
	v_and_b32_e32 v171, 0xffff0000, v152
	v_add_f32_e32 v140, v140, v144
	v_add_f32_e32 v141, v141, v145
	v_lshlrev_b32_e32 v144, 16, v157
	v_and_b32_e32 v145, 0xffff0000, v157
	v_add_f32_e32 v168, v168, v170
	v_add_f32_e32 v169, v169, v171
	v_lshlrev_b32_e32 v170, 16, v156
	v_and_b32_e32 v171, 0xffff0000, v156
	v_add_f32_e32 v140, v140, v144
	v_add_f32_e32 v141, v141, v145
	v_lshlrev_b32_e32 v144, 16, v161
	v_and_b32_e32 v145, 0xffff0000, v161
	v_add_f32_e32 v168, v168, v170
	v_add_f32_e32 v169, v169, v171
	v_lshlrev_b32_e32 v170, 16, v160
	v_and_b32_e32 v171, 0xffff0000, v160
	v_add_f32_e32 v140, v140, v144
	v_add_f32_e32 v141, v141, v145
	v_lshlrev_b32_e32 v144, 16, v165
	v_and_b32_e32 v145, 0xffff0000, v165
	v_add_f32_e32 v168, v168, v170
	v_add_f32_e32 v169, v169, v171
	v_lshlrev_b32_e32 v170, 16, v164
	v_and_b32_e32 v171, 0xffff0000, v164
	v_add_f32_e32 v164, v140, v144
	v_add_f32_e32 v165, v141, v145
	v_lshlrev_b32_e32 v140, 16, v142
	v_and_b32_e32 v141, 0xffff0000, v142
	v_add_f32_e32 v140, 0, v140
	v_add_f32_e32 v141, 0, v141
	v_lshlrev_b32_e32 v144, 16, v146
	v_and_b32_e32 v145, 0xffff0000, v146
	v_add_f32_e32 v140, v140, v144
	v_add_f32_e32 v141, v141, v145
	v_lshlrev_b32_e32 v144, 16, v150
	v_and_b32_e32 v145, 0xffff0000, v150
	v_add_f32_e32 v140, v140, v144
	v_add_f32_e32 v141, v141, v145
	v_lshlrev_b32_e32 v144, 16, v154
	v_and_b32_e32 v145, 0xffff0000, v154
	v_add_f32_e32 v140, v140, v144
	v_add_f32_e32 v141, v141, v145
	v_lshlrev_b32_e32 v144, 16, v158
	v_and_b32_e32 v145, 0xffff0000, v158
	v_add_f32_e32 v140, v140, v144
	v_add_f32_e32 v141, v141, v145
	v_lshlrev_b32_e32 v144, 16, v162
	v_and_b32_e32 v145, 0xffff0000, v162
	v_add_f32_e32 v140, v140, v144
	v_add_f32_e32 v141, v141, v145
	v_lshlrev_b32_e32 v144, 16, v166
	v_and_b32_e32 v145, 0xffff0000, v166
	v_add_f32_e32 v168, v168, v170
	v_add_f32_e32 v169, v169, v171
	v_add_f32_e32 v170, v140, v144
	v_add_f32_e32 v171, v141, v145
	v_lshlrev_b32_e32 v140, 16, v143
	v_and_b32_e32 v141, 0xffff0000, v143
	v_add_f32_e32 v140, 0, v140
	v_add_f32_e32 v141, 0, v141
	v_lshlrev_b32_e32 v142, 16, v147
	v_and_b32_e32 v143, 0xffff0000, v147
	v_add_f32_e32 v140, v140, v142
	v_add_f32_e32 v141, v141, v143
	v_lshlrev_b32_e32 v142, 16, v151
	v_and_b32_e32 v143, 0xffff0000, v151
	v_add_f32_e32 v140, v140, v142
	v_add_f32_e32 v141, v141, v143
	v_lshlrev_b32_e32 v142, 16, v155
	v_and_b32_e32 v143, 0xffff0000, v155
	v_add_f32_e32 v140, v140, v142
	v_add_f32_e32 v141, v141, v143
	v_lshlrev_b32_e32 v142, 16, v159
	v_and_b32_e32 v143, 0xffff0000, v159
	v_add_f32_e32 v140, v140, v142
	v_add_f32_e32 v141, v141, v143
	v_lshlrev_b32_e32 v142, 16, v163
	v_and_b32_e32 v143, 0xffff0000, v163
	v_add_f32_e32 v140, v140, v142
	v_add_f32_e32 v141, v141, v143
	v_lshlrev_b32_e32 v142, 16, v167
	v_and_b32_e32 v143, 0xffff0000, v167
	v_add_f32_e32 v166, v140, v142
	v_add_f32_e32 v167, v141, v143
	ds_read_b128 v[140:143], v244 offset:3696
	s_waitcnt lgkmcnt(0)
	v_lshlrev_b32_e32 v172, 16, v140
	v_and_b32_e32 v173, 0xffff0000, v140
	v_lshlrev_b32_e32 v174, 16, v141
	v_and_b32_e32 v175, 0xffff0000, v141
	v_lshlrev_b32_e32 v198, 16, v142
	v_and_b32_e32 v199, 0xffff0000, v142
	v_lshlrev_b32_e32 v200, 16, v143
	v_and_b32_e32 v201, 0xffff0000, v143
	ds_read_b128 v[140:143], v244 offset:4224
	v_add_f32_e32 v168, v168, v172
	v_add_f32_e32 v169, v169, v173
	v_add_f32_e32 v164, v164, v174
	v_add_f32_e32 v165, v165, v175
	s_waitcnt lgkmcnt(0)
	v_lshlrev_b32_e32 v202, 16, v140
	v_and_b32_e32 v203, 0xffff0000, v140
	v_lshlrev_b32_e32 v204, 16, v141
	v_and_b32_e32 v205, 0xffff0000, v141
	v_lshlrev_b32_e32 v206, 16, v142
	v_and_b32_e32 v207, 0xffff0000, v142
	v_lshlrev_b32_e32 v208, 16, v143
	v_and_b32_e32 v209, 0xffff0000, v143
	ds_read_b128 v[140:143], v244 offset:4752
	v_add_f32_e32 v168, v168, v202
	v_add_f32_e32 v169, v169, v203
	v_add_f32_e32 v164, v164, v204
	v_add_f32_e32 v165, v165, v205
	s_waitcnt lgkmcnt(0)
	v_lshlrev_b32_e32 v210, 16, v140
	v_and_b32_e32 v211, 0xffff0000, v140
	v_lshlrev_b32_e32 v212, 16, v141
	v_and_b32_e32 v213, 0xffff0000, v141
	v_lshlrev_b32_e32 v214, 16, v142
	v_and_b32_e32 v215, 0xffff0000, v142
	v_lshlrev_b32_e32 v216, 16, v143
	v_and_b32_e32 v217, 0xffff0000, v143
	ds_read_b128 v[140:143], v244 offset:5280
	ds_read_b128 v[144:147], v244 offset:5808
	ds_read_b128 v[148:151], v244 offset:6336
	ds_read_b128 v[152:155], v244 offset:6864
	ds_read_b128 v[156:159], v244 offset:7392
	ds_read_b128 v[160:163], v244 offset:7920
	v_add_f32_e32 v168, v168, v210
	v_add_f32_e32 v169, v169, v211
	s_waitcnt lgkmcnt(5)
	v_lshlrev_b32_e32 v172, 16, v140
	v_and_b32_e32 v173, 0xffff0000, v140
	v_add_f32_e32 v168, v168, v172
	v_add_f32_e32 v169, v169, v173
	s_waitcnt lgkmcnt(4)
	v_lshlrev_b32_e32 v172, 16, v144
	v_and_b32_e32 v173, 0xffff0000, v144
	v_add_f32_e32 v168, v168, v172
	v_add_f32_e32 v169, v169, v173
	s_waitcnt lgkmcnt(3)
	v_lshlrev_b32_e32 v172, 16, v148
	v_and_b32_e32 v173, 0xffff0000, v148
	v_add_f32_e32 v168, v168, v172
	v_add_f32_e32 v169, v169, v173
	s_waitcnt lgkmcnt(2)
	v_lshlrev_b32_e32 v172, 16, v152
	v_and_b32_e32 v173, 0xffff0000, v152
	v_add_f32_e32 v168, v168, v172
	v_add_f32_e32 v169, v169, v173
	s_waitcnt lgkmcnt(1)
	v_lshlrev_b32_e32 v172, 16, v156
	v_and_b32_e32 v173, 0xffff0000, v156
	v_add_f32_e32 v168, v168, v172
	v_add_f32_e32 v169, v169, v173
	s_waitcnt lgkmcnt(0)
	v_lshlrev_b32_e32 v172, 16, v160
	v_and_b32_e32 v173, 0xffff0000, v160
	v_add_f32_e32 v168, v168, v172
	v_add_f32_e32 v169, v169, v173
	v_add_f32_e32 v164, v164, v212
	v_add_f32_e32 v165, v165, v213
	v_fma_f32 v168, v196, v168, -v202
	v_fma_f32 v169, v196, v169, -v203
	v_cvt_pk_bf16_f32 v140, v168, v169
	v_lshlrev_b32_e32 v168, 16, v141
	v_and_b32_e32 v169, 0xffff0000, v141
	v_add_f32_e32 v164, v164, v168
	v_add_f32_e32 v165, v165, v169
	v_lshlrev_b32_e32 v144, 16, v145
	v_and_b32_e32 v145, 0xffff0000, v145
	v_add_f32_e32 v144, v164, v144
	v_add_f32_e32 v145, v165, v145
	v_lshlrev_b32_e32 v148, 16, v149
	v_and_b32_e32 v149, 0xffff0000, v149
	v_add_f32_e32 v144, v144, v148
	v_add_f32_e32 v145, v145, v149
	v_lshlrev_b32_e32 v148, 16, v153
	v_and_b32_e32 v149, 0xffff0000, v153
	v_add_f32_e32 v144, v144, v148
	v_add_f32_e32 v145, v145, v149
	v_lshlrev_b32_e32 v148, 16, v157
	v_and_b32_e32 v149, 0xffff0000, v157
	v_add_f32_e32 v144, v144, v148
	v_add_f32_e32 v145, v145, v149
	v_lshlrev_b32_e32 v148, 16, v161
	v_and_b32_e32 v149, 0xffff0000, v161
	v_add_f32_e32 v144, v144, v148
	v_add_f32_e32 v145, v145, v149
	v_lshlrev_b32_e32 v148, 16, v142
	v_fma_f32 v144, v196, v144, -v204
	v_fma_f32 v145, v196, v145, -v205
	v_cvt_pk_bf16_f32 v141, v144, v145
	v_add_f32_e32 v144, v170, v198
	v_add_f32_e32 v145, v171, v199
	v_and_b32_e32 v149, 0xffff0000, v142
	v_add_f32_e32 v144, v144, v206
	v_add_f32_e32 v145, v145, v207
	s_nop 0
	v_add_f32_e32 v144, v144, v214
	v_add_f32_e32 v145, v145, v215
	s_nop 0
	v_add_f32_e32 v144, v144, v148
	v_add_f32_e32 v145, v145, v149
	v_lshlrev_b32_e32 v148, 16, v146
	v_and_b32_e32 v149, 0xffff0000, v146
	v_add_f32_e32 v144, v144, v148
	v_add_f32_e32 v145, v145, v149
	v_lshlrev_b32_e32 v148, 16, v150
	v_and_b32_e32 v149, 0xffff0000, v150
	v_add_f32_e32 v144, v144, v148
	v_add_f32_e32 v145, v145, v149
	v_lshlrev_b32_e32 v148, 16, v154
	v_and_b32_e32 v149, 0xffff0000, v154
	v_add_f32_e32 v144, v144, v148
	v_add_f32_e32 v145, v145, v149
	v_lshlrev_b32_e32 v148, 16, v158
	v_and_b32_e32 v149, 0xffff0000, v158
	v_add_f32_e32 v144, v144, v148
	v_add_f32_e32 v145, v145, v149
	v_lshlrev_b32_e32 v148, 16, v162
	v_and_b32_e32 v149, 0xffff0000, v162
	v_add_f32_e32 v144, v144, v148
	v_add_f32_e32 v145, v145, v149
	v_lshlrev_b32_e32 v148, 16, v143
	v_fma_f32 v144, v196, v144, -v206
	v_fma_f32 v145, v196, v145, -v207
	v_cvt_pk_bf16_f32 v142, v144, v145
	v_add_f32_e32 v144, v166, v200
	v_add_f32_e32 v145, v167, v201
	v_and_b32_e32 v149, 0xffff0000, v143
	v_add_f32_e32 v144, v144, v208
	v_add_f32_e32 v145, v145, v209
	v_lshlrev_b32_e32 v146, 16, v147
	v_add_f32_e32 v144, v144, v216
	v_add_f32_e32 v145, v145, v217
	v_and_b32_e32 v147, 0xffff0000, v147
	v_add_f32_e32 v144, v144, v148
	v_add_f32_e32 v145, v145, v149
	s_nop 0
	v_add_f32_e32 v144, v144, v146
	v_add_f32_e32 v145, v145, v147
	v_lshlrev_b32_e32 v146, 16, v151
	v_and_b32_e32 v147, 0xffff0000, v151
	v_add_f32_e32 v144, v144, v146
	v_add_f32_e32 v145, v145, v147
	v_lshlrev_b32_e32 v146, 16, v155
	v_and_b32_e32 v147, 0xffff0000, v155
	v_add_f32_e32 v144, v144, v146
	v_add_f32_e32 v145, v145, v147
	v_lshlrev_b32_e32 v146, 16, v159
	v_and_b32_e32 v147, 0xffff0000, v159
	v_add_f32_e32 v144, v144, v146
	v_add_f32_e32 v145, v145, v147
	v_lshlrev_b32_e32 v146, 16, v163
	v_and_b32_e32 v147, 0xffff0000, v163
	v_add_f32_e32 v144, v144, v146
	v_add_f32_e32 v145, v145, v147
	s_nop 0
	v_fma_f32 v144, v196, v144, -v208
	v_fma_f32 v145, v196, v145, -v209
	v_cvt_pk_bf16_f32 v143, v144, v145
	ds_read_b128 v[144:147], v244 offset:64
	ds_read_b128 v[148:151], v244 offset:592
	s_waitcnt lgkmcnt(1)
	v_lshlrev_b32_e32 v152, 16, v144
	v_and_b32_e32 v153, 0xffff0000, v144
	v_lshlrev_b32_e32 v144, 16, v145
	v_and_b32_e32 v145, 0xffff0000, v145
	s_waitcnt lgkmcnt(0)
	v_lshlrev_b32_e32 v154, 16, v148
	v_and_b32_e32 v155, 0xffff0000, v148
	v_add_f32_e32 v144, 0, v144
	v_add_f32_e32 v145, 0, v145
	v_lshlrev_b32_e32 v148, 16, v149
	v_and_b32_e32 v149, 0xffff0000, v149
	v_add_f32_e32 v202, v144, v148
	v_add_f32_e32 v203, v145, v149
	v_lshlrev_b32_e32 v144, 16, v146
	v_and_b32_e32 v145, 0xffff0000, v146
	v_add_f32_e32 v144, 0, v144
	v_add_f32_e32 v145, 0, v145
	v_lshlrev_b32_e32 v148, 16, v150
	v_and_b32_e32 v149, 0xffff0000, v150
	v_add_f32_e32 v200, v144, v148
	v_add_f32_e32 v201, v145, v149
	v_lshlrev_b32_e32 v144, 16, v147
	v_and_b32_e32 v145, 0xffff0000, v147
	v_add_f32_e32 v144, 0, v144
	v_add_f32_e32 v145, 0, v145
	v_lshlrev_b32_e32 v146, 16, v151
	v_and_b32_e32 v147, 0xffff0000, v151
	v_add_f32_e32 v198, v144, v146
	v_add_f32_e32 v199, v145, v147
	ds_read_b128 v[144:147], v244 offset:1120
	v_add_f32_e32 v152, 0, v152
	v_add_f32_e32 v153, 0, v153
	s_waitcnt lgkmcnt(0)
	v_lshlrev_b32_e32 v222, 16, v144
	v_and_b32_e32 v223, 0xffff0000, v144
	v_lshlrev_b32_e32 v216, 16, v145
	v_and_b32_e32 v217, 0xffff0000, v145
	v_lshlrev_b32_e32 v210, 16, v146
	v_and_b32_e32 v211, 0xffff0000, v146
	v_lshlrev_b32_e32 v204, 16, v147
	v_and_b32_e32 v205, 0xffff0000, v147
	ds_read_b128 v[144:147], v244 offset:1648
	v_add_f32_e32 v206, v152, v154
	v_add_f32_e32 v207, v153, v155
	v_add_f32_e32 v202, v202, v216
	v_add_f32_e32 v203, v203, v217
	v_add_f32_e32 v206, v206, v222
	v_add_f32_e32 v207, v207, v223
	s_waitcnt lgkmcnt(0)
	v_lshlrev_b32_e32 v226, 16, v144
	v_and_b32_e32 v227, 0xffff0000, v144
	v_lshlrev_b32_e32 v220, 16, v145
	v_and_b32_e32 v221, 0xffff0000, v145
	v_lshlrev_b32_e32 v214, 16, v146
	v_and_b32_e32 v215, 0xffff0000, v146
	v_lshlrev_b32_e32 v208, 16, v147
	v_and_b32_e32 v209, 0xffff0000, v147
	ds_read_b128 v[144:147], v244 offset:2176
	v_add_f32_e32 v206, v206, v226
	v_add_f32_e32 v207, v207, v227
	v_add_f32_e32 v202, v202, v220
	v_add_f32_e32 v203, v203, v221
	s_waitcnt lgkmcnt(0)
	v_lshlrev_b32_e32 v228, 16, v144
	v_and_b32_e32 v229, 0xffff0000, v144
	v_lshlrev_b32_e32 v224, 16, v145
	v_and_b32_e32 v225, 0xffff0000, v145
	v_lshlrev_b32_e32 v218, 16, v146
	v_and_b32_e32 v219, 0xffff0000, v146
	v_lshlrev_b32_e32 v212, 16, v147
	v_and_b32_e32 v213, 0xffff0000, v147
	ds_read_b128 v[144:147], v244 offset:2704
	ds_read_b128 v[148:151], v244 offset:3232
	ds_read_b128 v[152:155], v244 offset:3760
	ds_read_b128 v[156:159], v244 offset:4288
	ds_read_b128 v[160:163], v244 offset:4816
	ds_read_b128 v[164:167], v244 offset:5344
	ds_read_b128 v[168:171], v244 offset:5872
	ds_read_b128 v[172:175], v244 offset:6400
	v_add_f32_e32 v206, v206, v228
	v_add_f32_e32 v207, v207, v229
	s_waitcnt lgkmcnt(7)
	v_lshlrev_b32_e32 v222, 16, v144
	v_and_b32_e32 v223, 0xffff0000, v144
	v_add_f32_e32 v202, v202, v224
	v_add_f32_e32 v203, v203, v225
	v_lshlrev_b32_e32 v144, 16, v145
	v_and_b32_e32 v145, 0xffff0000, v145
	v_add_f32_e32 v206, v206, v222
	v_add_f32_e32 v207, v207, v223
	s_waitcnt lgkmcnt(6)
	v_lshlrev_b32_e32 v222, 16, v148
	v_and_b32_e32 v223, 0xffff0000, v148
	v_add_f32_e32 v144, v202, v144
	v_add_f32_e32 v145, v203, v145
	v_lshlrev_b32_e32 v148, 16, v149
	v_and_b32_e32 v149, 0xffff0000, v149
	v_add_f32_e32 v144, v144, v148
	v_add_f32_e32 v145, v145, v149
	s_waitcnt lgkmcnt(5)
	v_lshlrev_b32_e32 v148, 16, v153
	v_and_b32_e32 v149, 0xffff0000, v153
	v_add_f32_e32 v148, v144, v148
	v_add_f32_e32 v149, v145, v149
	s_waitcnt lgkmcnt(4)
	v_lshlrev_b32_e32 v144, 16, v157
	v_and_b32_e32 v145, 0xffff0000, v157
	v_add_f32_e32 v206, v206, v222
	v_add_f32_e32 v207, v207, v223
	v_lshlrev_b32_e32 v222, 16, v152
	v_and_b32_e32 v223, 0xffff0000, v152
	v_add_f32_e32 v148, v148, v144
	v_add_f32_e32 v149, v149, v145
	s_waitcnt lgkmcnt(3)
	v_lshlrev_b32_e32 v152, 16, v161
	v_and_b32_e32 v153, 0xffff0000, v161
	v_add_f32_e32 v148, v148, v152
	v_add_f32_e32 v149, v149, v153
	s_waitcnt lgkmcnt(2)
	v_lshlrev_b32_e32 v152, 16, v165
	v_and_b32_e32 v153, 0xffff0000, v165
	v_add_f32_e32 v148, v148, v152
	v_add_f32_e32 v149, v149, v153
	s_waitcnt lgkmcnt(1)
	v_lshlrev_b32_e32 v152, 16, v169
	v_and_b32_e32 v153, 0xffff0000, v169
	v_add_f32_e32 v148, v148, v152
	v_add_f32_e32 v149, v149, v153
	s_waitcnt lgkmcnt(0)
	v_lshlrev_b32_e32 v152, 16, v173
	v_and_b32_e32 v153, 0xffff0000, v173
	v_add_f32_e32 v148, v148, v152
	v_add_f32_e32 v149, v149, v153
	v_add_f32_e32 v152, v200, v210
	v_add_f32_e32 v153, v201, v211
	v_add_f32_e32 v222, v206, v222
	v_add_f32_e32 v223, v207, v223
	v_add_f32_e32 v152, v152, v214
	v_add_f32_e32 v153, v153, v215
	v_lshlrev_b32_e32 v206, 16, v156
	v_and_b32_e32 v207, 0xffff0000, v156
	v_add_f32_e32 v152, v152, v218
	v_add_f32_e32 v153, v153, v219
	v_lshlrev_b32_e32 v156, 16, v146
	v_and_b32_e32 v157, 0xffff0000, v146
	v_add_f32_e32 v152, v152, v156
	v_add_f32_e32 v153, v153, v157
	v_lshlrev_b32_e32 v156, 16, v150
	v_and_b32_e32 v157, 0xffff0000, v150
	v_add_f32_e32 v152, v152, v156
	v_add_f32_e32 v153, v153, v157
	v_lshlrev_b32_e32 v156, 16, v154
	v_and_b32_e32 v157, 0xffff0000, v154
	v_add_f32_e32 v156, v152, v156
	v_add_f32_e32 v157, v153, v157
	v_lshlrev_b32_e32 v152, 16, v158
	v_and_b32_e32 v153, 0xffff0000, v158
	v_lshlrev_b32_e32 v226, 16, v160
	v_and_b32_e32 v227, 0xffff0000, v160
	v_add_f32_e32 v156, v156, v152
	v_add_f32_e32 v157, v157, v153
	v_lshlrev_b32_e32 v160, 16, v162
	v_and_b32_e32 v161, 0xffff0000, v162
	v_add_f32_e32 v156, v156, v160
	v_add_f32_e32 v157, v157, v161
	v_lshlrev_b32_e32 v160, 16, v166
	v_and_b32_e32 v161, 0xffff0000, v166
	v_add_f32_e32 v156, v156, v160
	v_add_f32_e32 v157, v157, v161
	v_lshlrev_b32_e32 v160, 16, v170
	v_and_b32_e32 v161, 0xffff0000, v170
	v_add_f32_e32 v156, v156, v160
	v_add_f32_e32 v157, v157, v161
	v_lshlrev_b32_e32 v160, 16, v174
	v_and_b32_e32 v161, 0xffff0000, v174
	v_add_f32_e32 v156, v156, v160
	v_add_f32_e32 v157, v157, v161
	v_add_f32_e32 v160, v198, v204
	v_add_f32_e32 v161, v199, v205
	v_lshlrev_b32_e32 v146, 16, v147
	v_add_f32_e32 v160, v160, v208
	v_add_f32_e32 v161, v161, v209
	v_and_b32_e32 v147, 0xffff0000, v147
	v_add_f32_e32 v160, v160, v212
	v_add_f32_e32 v161, v161, v213
	v_lshlrev_b32_e32 v150, 16, v151
	v_add_f32_e32 v146, v160, v146
	v_add_f32_e32 v147, v161, v147
	v_and_b32_e32 v151, 0xffff0000, v151
	v_add_f32_e32 v146, v146, v150
	v_add_f32_e32 v147, v147, v151
	v_lshlrev_b32_e32 v150, 16, v155
	v_and_b32_e32 v151, 0xffff0000, v155
	v_add_f32_e32 v150, v146, v150
	v_add_f32_e32 v151, v147, v151
	v_lshlrev_b32_e32 v146, 16, v159
	v_and_b32_e32 v147, 0xffff0000, v159
	v_add_f32_e32 v222, v222, v206
	v_add_f32_e32 v223, v223, v207
	v_add_f32_e32 v150, v150, v146
	v_add_f32_e32 v151, v151, v147
	v_lshlrev_b32_e32 v154, 16, v163
	v_and_b32_e32 v155, 0xffff0000, v163
	v_add_f32_e32 v222, v222, v226
	v_add_f32_e32 v223, v223, v227
	v_lshlrev_b32_e32 v226, 16, v164
	v_and_b32_e32 v227, 0xffff0000, v164
	v_add_f32_e32 v150, v150, v154
	v_add_f32_e32 v151, v151, v155
	v_lshlrev_b32_e32 v154, 16, v167
	v_and_b32_e32 v155, 0xffff0000, v167
	v_add_f32_e32 v222, v222, v226
	v_add_f32_e32 v223, v223, v227
	v_lshlrev_b32_e32 v226, 16, v168
	v_and_b32_e32 v227, 0xffff0000, v168
	v_add_f32_e32 v150, v150, v154
	v_add_f32_e32 v151, v151, v155
	v_lshlrev_b32_e32 v154, 16, v171
	v_and_b32_e32 v155, 0xffff0000, v171
	v_add_f32_e32 v222, v222, v226
	v_add_f32_e32 v223, v223, v227
	v_lshlrev_b32_e32 v226, 16, v172
	v_and_b32_e32 v227, 0xffff0000, v172
	v_add_f32_e32 v150, v150, v154
	v_add_f32_e32 v151, v151, v155
	v_lshlrev_b32_e32 v154, 16, v175
	v_and_b32_e32 v155, 0xffff0000, v175
	v_add_f32_e32 v222, v222, v226
	v_add_f32_e32 v223, v223, v227
	v_add_f32_e32 v150, v150, v154
	v_add_f32_e32 v151, v151, v155
	v_mov_b32_e32 v154, v248
	v_mov_b32_e32 v155, v249
	v_mov_b32_e32 v159, v233
	s_branch .LBB0_919

.LBB0_984:
	s_or_b64 exec, exec, s[2:3]
	v_lshlrev_b32_e32 v176, 2, v34
	v_lshl_add_u64 v[60:61], v[50:51], 0, v[176:177]
	global_load_dwordx4 v[52:55], v[60:61], off
	global_load_dwordx4 v[56:59], v[60:61], off offset:16
	s_waitcnt vmcnt(0)
	v_mul_f32_e32 v18, v13, v13
	v_mul_f32_e32 v19, v9, v9
	v_mul_f32_e32 v20, v5, v5
	v_fmac_f32_e32 v18, v12, v12
	v_fmac_f32_e32 v19, v8, v8
	v_mul_f32_e32 v21, v1, v1
	v_fmac_f32_e32 v20, v4, v4
	v_fmac_f32_e32 v18, v14, v14
	v_fmac_f32_e32 v19, v10, v10
	v_fmac_f32_e32 v21, v0, v0
	v_fmac_f32_e32 v20, v6, v6
	v_fmac_f32_e32 v18, v15, v15
	v_fmac_f32_e32 v19, v11, v11
	v_lshl_add_u64 v[28:29], v[16:17], 0, v[176:177]
	v_fmac_f32_e32 v21, v2, v2
	v_fmac_f32_e32 v20, v7, v7
	v_add_f32_e32 v16, v18, v19
	v_fmac_f32_e32 v21, v3, v3
	v_add_f32_e32 v16, v16, v20
	v_add_f32_e32 v16, v16, v21
	v_lshlrev_b32_e32 v50, 1, v34
	v_mov_b32_e32 v51, v177
	v_add_f32_dpp v16, v16, v16 quad_perm:[1,0,3,2] row_mask:0xf bank_mask:0xf bound_ctrl:1
	v_lshl_add_u64 v[62:63], v[48:49], 0, v[50:51]
	s_nop 0
	v_add_f32_dpp v16, v16, v16 quad_perm:[2,3,0,1] row_mask:0xf bank_mask:0xf bound_ctrl:1
	s_nop 1
	v_add_f32_dpp v16, v16, v16 row_half_mirror row_mask:0xf bank_mask:0xf bound_ctrl:1
	s_nop 1
	v_add_f32_dpp v16, v16, v16 row_mirror row_mask:0xf bank_mask:0xf bound_ctrl:1
	v_mov_b32_e32 v17, v16
	s_nop 1
	v_permlane16_swap_b32_e32 v16, v17
	v_add_f32_e32 v16, v16, v17
	v_mov_b32_e32 v17, v16
	s_nop 1
	v_permlane32_swap_b32_e32 v16, v17
	v_add_f32_e32 v16, v16, v17
	v_fmamk_f32 v16, v16, 0x3a800000, v230
	v_mul_f32_e32 v17, 0x4b800000, v16
	v_cmp_gt_f32_e32 vcc, s91, v16
	s_nop 1
	v_cndmask_b32_e32 v16, v16, v17, vcc
	v_rsq_f32_e32 v33, v16
	global_load_dwordx4 v[16:19], v[28:29], off offset:16
	global_load_dwordx4 v[20:23], v[28:29], off
	global_load_dwordx4 v[24:27], v[28:29], off offset:2064
	s_nop 0
	global_load_dwordx4 v[28:31], v[28:29], off offset:2048
	v_mul_f32_e32 v35, 0x45800000, v33
	v_cndmask_b32_e32 v64, v33, v35, vcc
	v_mul_f32_e32 v48, v12, v64
	v_mul_f32_e32 v49, v13, v64
	v_mul_f32_e32 v14, v14, v64
	v_mul_f32_e32 v15, v15, v64
	v_mul_f32_e32 v12, v8, v64
	v_mul_f32_e32 v13, v9, v64
	v_mul_f32_e32 v10, v10, v64
	v_mul_f32_e32 v11, v11, v64
	v_mul_f32_e32 v6, v6, v64
	v_mul_f32_e32 v7, v7, v64
	v_cmp_ne_u64_e32 vcc, 0, v[38:39]
	v_mul_f32_e32 v8, v52, v48
	v_mul_f32_e32 v9, v53, v49
	v_mul_f32_e32 v54, v54, v14
	v_mul_f32_e32 v55, v55, v15
	v_mul_f32_e32 v56, v56, v12
	v_mul_f32_e32 v57, v57, v13
	v_mul_f32_e32 v58, v58, v10
	v_mul_f32_e32 v59, v59, v11
	v_cvt_pk_bf16_f32 v52, v8, v9
	v_cvt_pk_bf16_f32 v53, v54, v55
	v_cvt_pk_bf16_f32 v54, v56, v57
	v_cvt_pk_bf16_f32 v55, v58, v59
	global_store_dwordx4 v[62:63], v[52:55], off
	global_load_dwordx4 v[52:55], v[60:61], off offset:2048
	s_nop 0
	global_load_dwordx4 v[56:59], v[60:61], off offset:2064
	v_mul_f32_e32 v8, v4, v64
	v_mul_f32_e32 v9, v5, v64
	v_mul_f32_e32 v4, v0, v64
	v_mul_f32_e32 v5, v1, v64
	v_mul_f32_e32 v0, v2, v64
	v_mul_f32_e32 v1, v3, v64
	s_waitcnt vmcnt(0)
	v_mul_f32_e32 v2, v52, v8
	v_mul_f32_e32 v3, v53, v9
	v_mul_f32_e32 v54, v54, v6
	v_mul_f32_e32 v55, v55, v7
	v_mul_f32_e32 v56, v56, v4
	v_mul_f32_e32 v57, v57, v5
	v_mul_f32_e32 v58, v58, v0
	v_mul_f32_e32 v59, v59, v1
	v_cvt_pk_bf16_f32 v52, v2, v3
	v_cvt_pk_bf16_f32 v53, v54, v55
	v_cvt_pk_bf16_f32 v54, v56, v57
	v_cvt_pk_bf16_f32 v55, v58, v59
	global_store_dwordx4 v[62:63], v[52:55], off offset:1024
	s_and_saveexec_b64 s[2:3], vcc
	s_cbranch_execz .LBB0_971
	v_lshl_add_u64 v[2:3], v[38:39], 0, v[176:177]
	v_lshl_add_u64 v[54:55], v[36:37], 0, v[50:51]
	global_load_dwordx4 v[36:39], v[2:3], off offset:16
	global_load_dwordx4 v[50:53], v[2:3], off
	s_waitcnt vmcnt(0)
	v_mul_f32_e32 v12, v12, v36
	v_mul_f32_e32 v13, v13, v37
	v_mul_f32_e32 v48, v48, v50
	v_mul_f32_e32 v49, v49, v51
	v_mul_f32_e32 v14, v14, v52
	v_mul_f32_e32 v15, v15, v53
	v_mul_f32_e32 v10, v10, v38
	v_mul_f32_e32 v11, v11, v39
	v_cvt_pk_bf16_f32 v48, v48, v49
	v_cvt_pk_bf16_f32 v49, v14, v15
	v_cvt_pk_bf16_f32 v50, v12, v13
	v_cvt_pk_bf16_f32 v51, v10, v11
	global_store_dwordx4 v[54:55], v[48:51], off
	global_load_dwordx4 v[10:13], v[2:3], off offset:2064
	global_load_dwordx4 v[36:39], v[2:3], off offset:2048
	s_waitcnt vmcnt(0)
	v_mul_f32_e32 v4, v4, v10
	v_mul_f32_e32 v5, v5, v11
	v_mul_f32_e32 v2, v8, v36
	v_mul_f32_e32 v3, v9, v37
	v_mul_f32_e32 v6, v6, v38
	v_mul_f32_e32 v7, v7, v39
	v_mul_f32_e32 v0, v0, v12
	v_mul_f32_e32 v1, v1, v13
	v_cvt_pk_bf16_f32 v2, v2, v3
	v_cvt_pk_bf16_f32 v3, v6, v7
	v_cvt_pk_bf16_f32 v4, v4, v5
	v_cvt_pk_bf16_f32 v5, v0, v1
	global_store_dwordx4 v[54:55], v[2:5], off offset:1024
	s_branch .LBB0_971
